# GEMM K-loops: leading wave group (wr==0) confirms its LDS-DMA pieces (vmcnt) after its MFMA segment instead of before it, one more barrier interval of load-latency slack
# baseline (speedup 1.0000x reference)
; #define PG8_STAGE(bufoff, gbase, voff) do { _Pragma("unroll") for (int _i = 0; _i < 2; ++_i) \
;         __builtin_amdgcn_global_load_lds((const unsigned*)((const char*)(gbase) + (voff)[_i]), (LAS unsigned*)(lds + (bufoff) + ldsw + _i * 8192), 16, 0, 0); } while (0)
; #define PG8_LDA(dst, b, h) do { _Pragma("unroll") for (int m = 0; m < 4; ++m) _Pragma("unroll") for (int k = 0; k < 2; ++k) dst[m][k] = *(const LAS bf16x8*)(lds + PG8_SA(b, h) + aoff + m * 2048 + k * 1024); } while (0)
; #define PG8_LDB(dst, b, h) do { _Pragma("unroll") for (int n = 0; n < 2; ++n) _Pragma("unroll") for (int k = 0; k < 2; ++k) dst[n][k] = *(const LAS bf16x8*)(lds + PG8_SB(b, h) + boff + n * 2048 + k * 1024); } while (0)
; #define PG8_MMA(ai, bj, At, Bt) do { __builtin_amdgcn_s_setprio(1); _Pragma("unroll") for (int m = 0; m < 4; ++m) _Pragma("unroll") for (int n = 0; n < 2; ++n) _Pragma("unroll") for (int k = 0; k < 2; ++k) \
;         acc[ai][bj][m][n] = __builtin_amdgcn_mfma_f32_16x16x32_bf16(Bt[n][k], At[m][k], acc[ai][bj][m][n], 0, 0, 0); __builtin_amdgcn_s_setprio(0); } while (0)
; #define PG8_WAIT_V(n) asm volatile("s_waitcnt vmcnt(" #n ")" ::: "memory")
; #define PG8_WAIT_L(n) asm volatile("s_waitcnt lgkmcnt(" #n ")" ::: "memory")
; #define PG8_BAR __builtin_amdgcn_s_barrier()
; #define PG8_SCHED __builtin_amdgcn_sched_barrier(0)
; template <class Epi, class Sched, bool ALIGN_EPI = true, bool SP2 = true>
; __device__ __forceinline__ void gemm_phase(LAS unsigned char* lds, const Gemm g, const Sched& S, const Epi& E) {
;     ...
;             const char* a1 = cA + (size_t)(t + 1) * kstep;
;             const char* a2 = last ? nA : cA + (size_t)(t + 2) * kstep; const char* b2 = last ? nB : cB + (size_t)(t + 2) * kstep;
;             const char* a3 = a2 + kstep; const char* b3 = b2 + kstep;
;             if (last && has_next) S.a_ready(nxt);
;             if constexpr (SP2) {
;             PG8_LDB(B0, 0, 0); PG8_LDB(B1, 0, 1); PG8_SCHED; PG8_LDA(At, 0, 0); PG8_STAGE(PG8_SA(1, 1), a1 + hstep, voffA);
;             PG8_WAIT_V(8); PG8_WAIT_L(0); PG8_BAR; PG8_MMA(0, 0, At, B0); PG8_MMA(0, 1, At, B1); PG8_BAR; PG8_SCHED;
;             PG8_LDA(At, 0, 1); PG8_STAGE(PG8_SB(0, 0), b2, voffB); PG8_STAGE(PG8_SB(0, 1), b2 + hstep, voffB); PG8_STAGE(PG8_SA(0, 0), a2, voffA);
;             PG8_WAIT_V(8); PG8_WAIT_L(0); PG8_BAR; PG8_MMA(1, 0, At, B0); PG8_MMA(1, 1, At, B1); PG8_BAR; PG8_SCHED;
.LBB0_138:
	ds_read_b128 v[130:133], v170
	ds_read_b128 v[134:137], v170 offset:1024
	ds_read_b128 v[176:179], v170 offset:2048
	ds_read_b128 v[180:183], v170 offset:3072
	ds_read_b128 v[184:187], v171
	ds_read_b128 v[188:191], v171 offset:1024
	ds_read_b128 v[192:195], v171 offset:2048
	ds_read_b128 v[196:199], v171 offset:3072
	s_add_u32 s40, s38, 0xfff00080
	s_addc_u32 s41, s39, -1
	s_cmp_eq_u32 s66, 60
	s_cselect_b32 s43, s5, s41
	s_cselect_b32 s42, s18, s40
	s_cselect_b32 s41, s27, s65
	s_cselect_b32 s40, s29, s64
	s_add_i32 m0, s37, 0xc000
	ds_read_b128 v[200:203], v172
	ds_read_b128 v[204:207], v172 offset:1024
	ds_read_b128 v[208:211], v172 offset:2048
	ds_read_b128 v[212:215], v172 offset:3072
	ds_read_b128 v[220:223], v172 offset:4096
	ds_read_b128 v[224:227], v172 offset:5120
	ds_read_b128 v[228:231], v172 offset:6144
	ds_read_b128 v[232:235], v172 offset:7168
	global_load_lds_dwordx4 v152, s[38:39]
	s_add_i32 m0, s37, 0xe000
	s_nop 0
	global_load_lds_dwordx4 v154, s[38:39]
	s_and_b64 vcc, exec, s[24:25]
	s_cbranch_vccnz .Lkw138_0
	s_waitcnt vmcnt(8)
.Lkw138_0:
	s_waitcnt lgkmcnt(0)
	s_setprio 1
	s_barrier
	v_mfma_f32_16x16x32_bf16 v[126:129], v[130:133], v[200:203], v[126:129]
	v_mfma_f32_16x16x32_bf16 v[122:125], v[176:179], v[200:203], v[122:125]
	v_mfma_f32_16x16x32_bf16 v[106:109], v[176:179], v[208:211], v[106:109]
	v_mfma_f32_16x16x32_bf16 v[110:113], v[130:133], v[208:211], v[110:113]
	v_mfma_f32_16x16x32_bf16 v[94:97], v[130:133], v[220:223], v[94:97]
	v_mfma_f32_16x16x32_bf16 v[90:93], v[176:179], v[220:223], v[90:93]
	v_mfma_f32_16x16x32_bf16 v[74:77], v[176:179], v[228:231], v[74:77]
	v_mfma_f32_16x16x32_bf16 v[78:81], v[130:133], v[228:231], v[78:81]
	v_mfma_f32_16x16x32_bf16 v[126:129], v[134:137], v[204:207], v[126:129]
	v_mfma_f32_16x16x32_bf16 v[122:125], v[180:183], v[204:207], v[122:125]
	v_mfma_f32_16x16x32_bf16 v[106:109], v[180:183], v[212:215], v[106:109]
	v_mfma_f32_16x16x32_bf16 v[110:113], v[134:137], v[212:215], v[110:113]
	v_mfma_f32_16x16x32_bf16 v[94:97], v[134:137], v[224:227], v[94:97]
	v_mfma_f32_16x16x32_bf16 v[90:93], v[180:183], v[224:227], v[90:93]
	v_mfma_f32_16x16x32_bf16 v[74:77], v[180:183], v[232:235], v[74:77]
	v_mfma_f32_16x16x32_bf16 v[78:81], v[134:137], v[232:235], v[78:81]
	v_mfma_f32_16x16x32_bf16 v[118:121], v[184:187], v[200:203], v[118:121]
	v_mfma_f32_16x16x32_bf16 v[114:117], v[192:195], v[200:203], v[114:117]
	v_mfma_f32_16x16x32_bf16 v[98:101], v[192:195], v[208:211], v[98:101]
	v_mfma_f32_16x16x32_bf16 v[102:105], v[184:187], v[208:211], v[102:105]
	v_mfma_f32_16x16x32_bf16 v[86:89], v[184:187], v[220:223], v[86:89]
	v_mfma_f32_16x16x32_bf16 v[82:85], v[192:195], v[220:223], v[82:85]
	v_mfma_f32_16x16x32_bf16 v[66:69], v[192:195], v[228:231], v[66:69]
	v_mfma_f32_16x16x32_bf16 v[70:73], v[184:187], v[228:231], v[70:73]
	v_mfma_f32_16x16x32_bf16 v[118:121], v[188:191], v[204:207], v[118:121]
	v_mfma_f32_16x16x32_bf16 v[114:117], v[196:199], v[204:207], v[114:117]
	v_mfma_f32_16x16x32_bf16 v[98:101], v[196:199], v[212:215], v[98:101]
	v_mfma_f32_16x16x32_bf16 v[102:105], v[188:191], v[212:215], v[102:105]
	v_mfma_f32_16x16x32_bf16 v[86:89], v[188:191], v[224:227], v[86:89]
	v_mfma_f32_16x16x32_bf16 v[82:85], v[196:199], v[224:227], v[82:85]
	v_mfma_f32_16x16x32_bf16 v[66:69], v[196:199], v[232:235], v[66:69]
	v_mfma_f32_16x16x32_bf16 v[70:73], v[188:191], v[232:235], v[70:73]
	s_waitcnt vmcnt(8)
	s_barrier
	s_setprio 0
	s_add_i32 s67, s60, s45
	v_lshl_add_u64 v[216:217], s[40:41], 0, v[140:141]
	s_mov_b32 m0, s67
	ds_read_b128 v[200:203], v172 offset:16384
	ds_read_b128 v[204:207], v172 offset:17408
	ds_read_b128 v[208:211], v172 offset:18432
	ds_read_b128 v[212:215], v172 offset:19456
	ds_read_b128 v[220:223], v172 offset:20480
	ds_read_b128 v[224:227], v172 offset:21504
	ds_read_b128 v[228:231], v172 offset:22528
	ds_read_b128 v[232:235], v172 offset:23552
	global_load_lds_dwordx4 v[216:217], off
	s_add_i32 m0, s67, 0x2000
	s_add_u32 s68, s40, 0x100000
	v_lshl_add_u64 v[218:219], s[40:41], 0, v[144:145]
	s_addc_u32 s69, s41, 0
	s_add_i32 s67, s61, s45
	global_load_lds_dwordx4 v[218:219], off
	s_mov_b32 m0, s67
	v_lshl_add_u64 v[238:239], s[42:43], 0, v[142:143]
	global_load_lds_dwordx4 v140, s[68:69]
	s_add_i32 m0, s67, 0x2000
	s_nop 0
	global_load_lds_dwordx4 v144, s[68:69]
	v_lshl_add_u64 v[236:237], s[42:43], 0, v[138:139]
	s_mov_b32 m0, s37
	s_nop 0
	global_load_lds_dwordx4 v[236:237], off
	s_mov_b32 m0, s47
	s_nop 0
	global_load_lds_dwordx4 v[238:239], off
	s_and_b64 vcc, exec, s[24:25]
	s_cbranch_vccnz .Lkw138_1
	s_waitcnt vmcnt(8)
; #define PG8_STAGE(bufoff, gbase, voff) do { _Pragma("unroll") for (int _i = 0; _i < 2; ++_i) \
;         __builtin_amdgcn_global_load_lds((const unsigned*)((const char*)(gbase) + (voff)[_i]), (LAS unsigned*)(lds + (bufoff) + ldsw + _i * 8192), 16, 0, 0); } while (0)
; #define PG8_LDA(dst, b, h) do { _Pragma("unroll") for (int m = 0; m < 4; ++m) _Pragma("unroll") for (int k = 0; k < 2; ++k) dst[m][k] = *(const LAS bf16x8*)(lds + PG8_SA(b, h) + aoff + m * 2048 + k * 1024); } while (0)
; #define PG8_LDB(dst, b, h) do { _Pragma("unroll") for (int n = 0; n < 2; ++n) _Pragma("unroll") for (int k = 0; k < 2; ++k) dst[n][k] = *(const LAS bf16x8*)(lds + PG8_SB(b, h) + boff + n * 2048 + k * 1024); } while (0)
; #define PG8_MMA(ai, bj, At, Bt) do { __builtin_amdgcn_s_setprio(1); _Pragma("unroll") for (int m = 0; m < 4; ++m) _Pragma("unroll") for (int n = 0; n < 2; ++n) _Pragma("unroll") for (int k = 0; k < 2; ++k) \
;         acc[ai][bj][m][n] = __builtin_amdgcn_mfma_f32_16x16x32_bf16(Bt[n][k], At[m][k], acc[ai][bj][m][n], 0, 0, 0); __builtin_amdgcn_s_setprio(0); } while (0)
; #define PG8_WAIT_V(n) asm volatile("s_waitcnt vmcnt(" #n ")" ::: "memory")
; #define PG8_WAIT_L(n) asm volatile("s_waitcnt lgkmcnt(" #n ")" ::: "memory")
; #define PG8_BAR __builtin_amdgcn_s_barrier()
; #define PG8_SCHED __builtin_amdgcn_sched_barrier(0)
; template <class Epi, class Sched, bool ALIGN_EPI = true, bool SP2 = true>
; __device__ __forceinline__ void gemm_phase(LAS unsigned char* lds, const Gemm g, const Sched& S, const Epi& E) {
;     ...
;             PG8_WAIT_V(8); PG8_WAIT_L(0); PG8_BAR; PG8_MMA(1, 0, At, B0); PG8_MMA(1, 1, At, B1); PG8_BAR; PG8_SCHED;
;             PG8_LDB(B0, 1, 0); PG8_LDB(B1, 1, 1); PG8_SCHED; PG8_LDA(At, 1, 0); PG8_STAGE(PG8_SA(0, 1), a2 + hstep, voffA);
.Lkw138_1:
	s_waitcnt lgkmcnt(0)
	s_setprio 1
	s_barrier
	v_mfma_f32_16x16x32_bf16 v[62:65], v[130:133], v[200:203], v[62:65]
	v_mfma_f32_16x16x32_bf16 v[58:61], v[176:179], v[200:203], v[58:61]
	v_mfma_f32_16x16x32_bf16 v[42:45], v[176:179], v[208:211], v[42:45]
	v_mfma_f32_16x16x32_bf16 v[46:49], v[130:133], v[208:211], v[46:49]
	v_mfma_f32_16x16x32_bf16 v[30:33], v[130:133], v[220:223], v[30:33]
	v_mfma_f32_16x16x32_bf16 v[26:29], v[176:179], v[220:223], v[26:29]
	v_mfma_f32_16x16x32_bf16 v[10:13], v[176:179], v[228:231], v[10:13]
	v_mfma_f32_16x16x32_bf16 v[14:17], v[130:133], v[228:231], v[14:17]
	v_mfma_f32_16x16x32_bf16 v[62:65], v[134:137], v[204:207], v[62:65]
	v_mfma_f32_16x16x32_bf16 v[58:61], v[180:183], v[204:207], v[58:61]
	v_mfma_f32_16x16x32_bf16 v[42:45], v[180:183], v[212:215], v[42:45]
	v_mfma_f32_16x16x32_bf16 v[46:49], v[134:137], v[212:215], v[46:49]
	v_mfma_f32_16x16x32_bf16 v[30:33], v[134:137], v[224:227], v[30:33]
	v_mfma_f32_16x16x32_bf16 v[26:29], v[180:183], v[224:227], v[26:29]
	v_mfma_f32_16x16x32_bf16 v[10:13], v[180:183], v[232:235], v[10:13]
	v_mfma_f32_16x16x32_bf16 v[14:17], v[134:137], v[232:235], v[14:17]
	v_mfma_f32_16x16x32_bf16 v[54:57], v[184:187], v[200:203], v[54:57]
	v_mfma_f32_16x16x32_bf16 v[50:53], v[192:195], v[200:203], v[50:53]
	v_mfma_f32_16x16x32_bf16 v[34:37], v[192:195], v[208:211], v[34:37]
	v_mfma_f32_16x16x32_bf16 v[38:41], v[184:187], v[208:211], v[38:41]
	v_mfma_f32_16x16x32_bf16 v[22:25], v[184:187], v[220:223], v[22:25]
	v_mfma_f32_16x16x32_bf16 v[18:21], v[192:195], v[220:223], v[18:21]
	v_mfma_f32_16x16x32_bf16 v[2:5], v[192:195], v[228:231], v[2:5]
	v_mfma_f32_16x16x32_bf16 v[6:9], v[184:187], v[228:231], v[6:9]
	v_mfma_f32_16x16x32_bf16 v[54:57], v[188:191], v[204:207], v[54:57]
	v_mfma_f32_16x16x32_bf16 v[50:53], v[196:199], v[204:207], v[50:53]
	v_mfma_f32_16x16x32_bf16 v[34:37], v[196:199], v[212:215], v[34:37]
	v_mfma_f32_16x16x32_bf16 v[38:41], v[188:191], v[212:215], v[38:41]
	v_mfma_f32_16x16x32_bf16 v[22:25], v[188:191], v[224:227], v[22:25]
	v_mfma_f32_16x16x32_bf16 v[18:21], v[196:199], v[224:227], v[18:21]
	v_mfma_f32_16x16x32_bf16 v[2:5], v[196:199], v[232:235], v[2:5]
	v_mfma_f32_16x16x32_bf16 v[6:9], v[188:191], v[232:235], v[6:9]
	s_waitcnt vmcnt(8)
	s_barrier
	s_setprio 0
	s_add_i32 s67, 0, 0x18000
	v_add_u32_e32 v146, s67, v160
	s_add_i32 s68, 0, 0x1c000
	ds_read_b128 v[130:133], v146
	ds_read_b128 v[134:137], v146 offset:1024
	ds_read_b128 v[176:179], v146 offset:2048
	ds_read_b128 v[180:183], v146 offset:3072
	v_add_u32_e32 v146, s68, v160
	ds_read_b128 v[184:187], v146
	ds_read_b128 v[188:191], v146 offset:1024
	ds_read_b128 v[192:195], v146 offset:2048
	ds_read_b128 v[196:199], v146 offset:3072
	s_add_u32 s42, s42, 0x100000
	s_addc_u32 s43, s43, 0
	s_mov_b32 m0, s48
	ds_read_b128 v[200:203], v172 offset:32768
	ds_read_b128 v[204:207], v172 offset:33792
	ds_read_b128 v[208:211], v172 offset:34816
	ds_read_b128 v[212:215], v172 offset:35840
	ds_read_b128 v[220:223], v172 offset:36864
	ds_read_b128 v[224:227], v172 offset:37888
	ds_read_b128 v[228:231], v172 offset:38912
	ds_read_b128 v[232:235], v172 offset:39936
	global_load_lds_dwordx4 v138, s[42:43]
	s_mov_b32 m0, s49
	s_nop 0
	global_load_lds_dwordx4 v142, s[42:43]
	s_and_b64 vcc, exec, s[24:25]
	s_cbranch_vccnz .Lkw138_2
	s_waitcnt vmcnt(8)
; #define PG8_STAGE(bufoff, gbase, voff) do { _Pragma("unroll") for (int _i = 0; _i < 2; ++_i) \
;         __builtin_amdgcn_global_load_lds((const unsigned*)((const char*)(gbase) + (voff)[_i]), (LAS unsigned*)(lds + (bufoff) + ldsw + _i * 8192), 16, 0, 0); } while (0)
; #define PG8_LDA(dst, b, h) do { _Pragma("unroll") for (int m = 0; m < 4; ++m) _Pragma("unroll") for (int k = 0; k < 2; ++k) dst[m][k] = *(const LAS bf16x8*)(lds + PG8_SA(b, h) + aoff + m * 2048 + k * 1024); } while (0)
; #define PG8_MMA(ai, bj, At, Bt) do { __builtin_amdgcn_s_setprio(1); _Pragma("unroll") for (int m = 0; m < 4; ++m) _Pragma("unroll") for (int n = 0; n < 2; ++n) _Pragma("unroll") for (int k = 0; k < 2; ++k) \
;         acc[ai][bj][m][n] = __builtin_amdgcn_mfma_f32_16x16x32_bf16(Bt[n][k], At[m][k], acc[ai][bj][m][n], 0, 0, 0); __builtin_amdgcn_s_setprio(0); } while (0)
; #define PG8_WAIT_V(n) asm volatile("s_waitcnt vmcnt(" #n ")" ::: "memory")
; #define PG8_WAIT_L(n) asm volatile("s_waitcnt lgkmcnt(" #n ")" ::: "memory")
; #define PG8_BAR __builtin_amdgcn_s_barrier()
; #define PG8_SCHED __builtin_amdgcn_sched_barrier(0)
; template <class Epi, class Sched, bool ALIGN_EPI = true, bool SP2 = true>
; __device__ __forceinline__ void gemm_phase(LAS unsigned char* lds, const Gemm g, const Sched& S, const Epi& E) {
;     ...
;         for (int t = 0; t < nt; t += 2) {
;     ...
;             PG8_WAIT_V(8); PG8_WAIT_L(0); PG8_BAR; PG8_MMA(0, 0, At, B0); PG8_MMA(0, 1, At, B1); PG8_BAR; PG8_SCHED;
;             PG8_LDA(At, 1, 1); PG8_STAGE(PG8_SB(1, 0), b3, voffB); PG8_STAGE(PG8_SB(1, 1), b3 + hstep, voffB); PG8_STAGE(PG8_SA(1, 0), a3, voffA);
;             PG8_WAIT_V(8); PG8_WAIT_L(0); PG8_BAR; PG8_MMA(1, 0, At, B0); PG8_MMA(1, 1, At, B1); PG8_BAR; PG8_SCHED;
.Lkw138_2:
	s_waitcnt lgkmcnt(0)
	s_setprio 1
	s_barrier
	v_mfma_f32_16x16x32_bf16 v[126:129], v[130:133], v[200:203], v[126:129]
	v_mfma_f32_16x16x32_bf16 v[122:125], v[176:179], v[200:203], v[122:125]
	v_mfma_f32_16x16x32_bf16 v[106:109], v[176:179], v[208:211], v[106:109]
	v_mfma_f32_16x16x32_bf16 v[110:113], v[130:133], v[208:211], v[110:113]
	v_mfma_f32_16x16x32_bf16 v[94:97], v[130:133], v[220:223], v[94:97]
	v_mfma_f32_16x16x32_bf16 v[90:93], v[176:179], v[220:223], v[90:93]
	v_mfma_f32_16x16x32_bf16 v[74:77], v[176:179], v[228:231], v[74:77]
	v_mfma_f32_16x16x32_bf16 v[78:81], v[130:133], v[228:231], v[78:81]
	v_mfma_f32_16x16x32_bf16 v[126:129], v[134:137], v[204:207], v[126:129]
	v_mfma_f32_16x16x32_bf16 v[122:125], v[180:183], v[204:207], v[122:125]
	v_mfma_f32_16x16x32_bf16 v[106:109], v[180:183], v[212:215], v[106:109]
	v_mfma_f32_16x16x32_bf16 v[110:113], v[134:137], v[212:215], v[110:113]
	v_mfma_f32_16x16x32_bf16 v[94:97], v[134:137], v[224:227], v[94:97]
	v_mfma_f32_16x16x32_bf16 v[90:93], v[180:183], v[224:227], v[90:93]
	v_mfma_f32_16x16x32_bf16 v[74:77], v[180:183], v[232:235], v[74:77]
	v_mfma_f32_16x16x32_bf16 v[78:81], v[134:137], v[232:235], v[78:81]
	v_mfma_f32_16x16x32_bf16 v[118:121], v[184:187], v[200:203], v[118:121]
	v_mfma_f32_16x16x32_bf16 v[114:117], v[192:195], v[200:203], v[114:117]
	v_mfma_f32_16x16x32_bf16 v[98:101], v[192:195], v[208:211], v[98:101]
	v_mfma_f32_16x16x32_bf16 v[102:105], v[184:187], v[208:211], v[102:105]
	v_mfma_f32_16x16x32_bf16 v[86:89], v[184:187], v[220:223], v[86:89]
	v_mfma_f32_16x16x32_bf16 v[82:85], v[192:195], v[220:223], v[82:85]
	v_mfma_f32_16x16x32_bf16 v[66:69], v[192:195], v[228:231], v[66:69]
	v_mfma_f32_16x16x32_bf16 v[70:73], v[184:187], v[228:231], v[70:73]
	v_mfma_f32_16x16x32_bf16 v[118:121], v[188:191], v[204:207], v[118:121]
	v_mfma_f32_16x16x32_bf16 v[114:117], v[196:199], v[204:207], v[114:117]
	v_mfma_f32_16x16x32_bf16 v[98:101], v[196:199], v[212:215], v[98:101]
	v_mfma_f32_16x16x32_bf16 v[102:105], v[188:191], v[212:215], v[102:105]
	v_mfma_f32_16x16x32_bf16 v[86:89], v[188:191], v[224:227], v[86:89]
	v_mfma_f32_16x16x32_bf16 v[82:85], v[196:199], v[224:227], v[82:85]
	v_mfma_f32_16x16x32_bf16 v[66:69], v[196:199], v[232:235], v[66:69]
	v_mfma_f32_16x16x32_bf16 v[70:73], v[188:191], v[232:235], v[70:73]
	s_waitcnt vmcnt(8)
	s_barrier
	s_setprio 0
	s_add_i32 s42, s67, s45
	v_lshl_add_u64 v[216:217], v[216:217], 0, s[22:23]
	s_mov_b32 m0, s42
	ds_read_b128 v[200:203], v172 offset:49152
	ds_read_b128 v[204:207], v172 offset:50176
	ds_read_b128 v[208:211], v172 offset:51200
	ds_read_b128 v[212:215], v172 offset:52224
	ds_read_b128 v[220:223], v172 offset:53248
	ds_read_b128 v[224:227], v172 offset:54272
	ds_read_b128 v[228:231], v172 offset:55296
	ds_read_b128 v[232:235], v172 offset:56320
	global_load_lds_dwordx4 v[216:217], off
	s_add_i32 m0, s42, 0x2000
	s_add_u32 s40, s40, 0x100080
	v_lshl_add_u64 v[216:217], v[218:219], 0, s[22:23]
	s_addc_u32 s41, s41, 0
	s_add_i32 s42, s68, s45
	global_load_lds_dwordx4 v[216:217], off
	s_mov_b32 m0, s42
	s_nop 0
	global_load_lds_dwordx4 v140, s[40:41]
	s_add_i32 m0, s42, 0x2000
	s_nop 0
	global_load_lds_dwordx4 v144, s[40:41]
	v_lshl_add_u64 v[216:217], v[236:237], 0, s[22:23]
	s_mov_b32 m0, s54
	s_nop 0
	global_load_lds_dwordx4 v[216:217], off
	v_lshl_add_u64 v[216:217], v[238:239], 0, s[22:23]
	s_mov_b32 m0, s55
	s_nop 0
	global_load_lds_dwordx4 v[216:217], off
	s_and_b64 vcc, exec, s[24:25]
	s_cbranch_vccnz .Lkw138_3
	s_waitcnt vmcnt(8)
.Lkw138_3:
	s_waitcnt lgkmcnt(0)
	s_setprio 1
	s_barrier
	v_mfma_f32_16x16x32_bf16 v[62:65], v[130:133], v[200:203], v[62:65]
	v_mfma_f32_16x16x32_bf16 v[58:61], v[176:179], v[200:203], v[58:61]
	v_mfma_f32_16x16x32_bf16 v[42:45], v[176:179], v[208:211], v[42:45]
	v_mfma_f32_16x16x32_bf16 v[46:49], v[130:133], v[208:211], v[46:49]
	v_mfma_f32_16x16x32_bf16 v[30:33], v[130:133], v[220:223], v[30:33]
	v_mfma_f32_16x16x32_bf16 v[26:29], v[176:179], v[220:223], v[26:29]
	v_mfma_f32_16x16x32_bf16 v[10:13], v[176:179], v[228:231], v[10:13]
	v_mfma_f32_16x16x32_bf16 v[14:17], v[130:133], v[228:231], v[14:17]
	v_mfma_f32_16x16x32_bf16 v[62:65], v[134:137], v[204:207], v[62:65]
	v_mfma_f32_16x16x32_bf16 v[58:61], v[180:183], v[204:207], v[58:61]
	v_mfma_f32_16x16x32_bf16 v[42:45], v[180:183], v[212:215], v[42:45]
	v_mfma_f32_16x16x32_bf16 v[46:49], v[134:137], v[212:215], v[46:49]
	v_mfma_f32_16x16x32_bf16 v[30:33], v[134:137], v[224:227], v[30:33]
	v_mfma_f32_16x16x32_bf16 v[26:29], v[180:183], v[224:227], v[26:29]
	v_mfma_f32_16x16x32_bf16 v[10:13], v[180:183], v[232:235], v[10:13]
	v_mfma_f32_16x16x32_bf16 v[14:17], v[134:137], v[232:235], v[14:17]
	v_mfma_f32_16x16x32_bf16 v[54:57], v[184:187], v[200:203], v[54:57]
	v_mfma_f32_16x16x32_bf16 v[50:53], v[192:195], v[200:203], v[50:53]
	v_mfma_f32_16x16x32_bf16 v[34:37], v[192:195], v[208:211], v[34:37]
	v_mfma_f32_16x16x32_bf16 v[38:41], v[184:187], v[208:211], v[38:41]
	v_mfma_f32_16x16x32_bf16 v[22:25], v[184:187], v[220:223], v[22:25]
	v_mfma_f32_16x16x32_bf16 v[18:21], v[192:195], v[220:223], v[18:21]
	v_mfma_f32_16x16x32_bf16 v[2:5], v[192:195], v[228:231], v[2:5]
	v_mfma_f32_16x16x32_bf16 v[6:9], v[184:187], v[228:231], v[6:9]
	v_mfma_f32_16x16x32_bf16 v[54:57], v[188:191], v[204:207], v[54:57]
	v_mfma_f32_16x16x32_bf16 v[50:53], v[196:199], v[204:207], v[50:53]
	v_mfma_f32_16x16x32_bf16 v[34:37], v[196:199], v[212:215], v[34:37]
	v_mfma_f32_16x16x32_bf16 v[38:41], v[188:191], v[212:215], v[38:41]
	v_mfma_f32_16x16x32_bf16 v[22:25], v[188:191], v[224:227], v[22:25]
	v_mfma_f32_16x16x32_bf16 v[18:21], v[196:199], v[224:227], v[18:21]
	v_mfma_f32_16x16x32_bf16 v[2:5], v[196:199], v[232:235], v[2:5]
	v_mfma_f32_16x16x32_bf16 v[6:9], v[188:191], v[232:235], v[6:9]
	s_waitcnt vmcnt(8)
	s_barrier
	s_setprio 0
	s_add_i32 s66, s66, 2
	s_add_u32 s38, s38, 0x100
	s_addc_u32 s39, s39, 0
	s_add_u32 s64, s64, 0x100
	s_addc_u32 s65, s65, 0
	s_cmp_gt_u32 s66, 61
	s_cbranch_scc0 .LBB0_138
	s_and_b64 vcc, exec, s[24:25]
	s_cbranch_vccz .LBB0_141
	s_barrier

; #define PG8_STAGE(bufoff, gbase, voff) do { _Pragma("unroll") for (int _i = 0; _i < 2; ++_i) \
;         __builtin_amdgcn_global_load_lds((const unsigned*)((const char*)(gbase) + (voff)[_i]), (LAS unsigned*)(lds + (bufoff) + ldsw + _i * 8192), 16, 0, 0); } while (0)
; #define PG8_LDA(dst, b, h) do { _Pragma("unroll") for (int m = 0; m < 4; ++m) _Pragma("unroll") for (int k = 0; k < 2; ++k) dst[m][k] = *(const LAS bf16x8*)(lds + PG8_SA(b, h) + aoff + m * 2048 + k * 1024); } while (0)
; #define PG8_LDB(dst, b, h) do { _Pragma("unroll") for (int n = 0; n < 2; ++n) _Pragma("unroll") for (int k = 0; k < 2; ++k) dst[n][k] = *(const LAS bf16x8*)(lds + PG8_SB(b, h) + boff + n * 2048 + k * 1024); } while (0)
; #define PG8_MMA(ai, bj, At, Bt) do { __builtin_amdgcn_s_setprio(1); _Pragma("unroll") for (int m = 0; m < 4; ++m) _Pragma("unroll") for (int n = 0; n < 2; ++n) _Pragma("unroll") for (int k = 0; k < 2; ++k) \
;         acc[ai][bj][m][n] = __builtin_amdgcn_mfma_f32_16x16x32_bf16(Bt[n][k], At[m][k], acc[ai][bj][m][n], 0, 0, 0); __builtin_amdgcn_s_setprio(0); } while (0)
; #define PG8_WAIT_V(n) asm volatile("s_waitcnt vmcnt(" #n ")" ::: "memory")
; #define PG8_WAIT_L(n) asm volatile("s_waitcnt lgkmcnt(" #n ")" ::: "memory")
; #define PG8_BAR __builtin_amdgcn_s_barrier()
; #define PG8_SCHED __builtin_amdgcn_sched_barrier(0)
; template <class Epi, class Sched, bool ALIGN_EPI = true, bool SP2 = true>
; __device__ __forceinline__ void gemm_phase(LAS unsigned char* lds, const Gemm g, const Sched& S, const Epi& E) {
;     ...
;             const char* a1 = cA + (size_t)(t + 1) * kstep;
;             const char* a2 = last ? nA : cA + (size_t)(t + 2) * kstep; const char* b2 = last ? nB : cB + (size_t)(t + 2) * kstep;
;             const char* a3 = a2 + kstep; const char* b3 = b2 + kstep;
;             if (last && has_next) S.a_ready(nxt);
;             if constexpr (SP2) {
;             PG8_LDB(B0, 0, 0); PG8_LDB(B1, 0, 1); PG8_SCHED; PG8_LDA(At, 0, 0); PG8_STAGE(PG8_SA(1, 1), a1 + hstep, voffA);
;             PG8_WAIT_V(8); PG8_WAIT_L(0); PG8_BAR; PG8_MMA(0, 0, At, B0); PG8_MMA(0, 1, At, B1); PG8_BAR; PG8_SCHED;
;             PG8_LDA(At, 0, 1); PG8_STAGE(PG8_SB(0, 0), b2, voffB); PG8_STAGE(PG8_SB(0, 1), b2 + hstep, voffB); PG8_STAGE(PG8_SA(0, 0), a2, voffA);
;             PG8_WAIT_V(8); PG8_WAIT_L(0); PG8_BAR; PG8_MMA(1, 0, At, B0); PG8_MMA(1, 1, At, B1); PG8_BAR; PG8_SCHED;
.LBB0_451:
	ds_read_b128 v[146:149], v152
	ds_read_b128 v[156:159], v152 offset:1024
	ds_read_b128 v[160:163], v152 offset:2048
	ds_read_b128 v[164:167], v152 offset:3072
	ds_read_b128 v[168:171], v153
	ds_read_b128 v[172:175], v153 offset:1024
	ds_read_b128 v[176:179], v153 offset:2048
	ds_read_b128 v[180:183], v153 offset:3072
	s_add_u32 s22, s20, 0xfffc0080
	s_addc_u32 s23, s21, -1
	s_cmp_eq_u32 s49, 12
	s_cselect_b32 s25, s13, s23
	s_cselect_b32 s24, s45, s22
	s_cselect_b32 s23, s11, s48
	s_cselect_b32 s22, s46, s47
	s_add_i32 m0, s19, 0xc000
	ds_read_b128 v[184:187], v154
	ds_read_b128 v[188:191], v154 offset:1024
	ds_read_b128 v[192:195], v154 offset:2048
	ds_read_b128 v[196:199], v154 offset:3072
	ds_read_b128 v[200:203], v154 offset:4096
	ds_read_b128 v[204:207], v154 offset:5120
	ds_read_b128 v[208:211], v154 offset:6144
	ds_read_b128 v[212:215], v154 offset:7168
	global_load_lds_dwordx4 v138, s[20:21]
	s_add_i32 m0, s19, 0xe000
	s_nop 0
	global_load_lds_dwordx4 v140, s[20:21]
	s_and_b64 vcc, exec, s[8:9]
	s_cbranch_vccnz .Lkw451_0
	s_waitcnt vmcnt(8)
.Lkw451_0:
	s_waitcnt lgkmcnt(0)
	s_setprio 1
	s_barrier
	v_mfma_f32_16x16x32_bf16 v[126:129], v[146:149], v[184:187], v[126:129]
	v_mfma_f32_16x16x32_bf16 v[122:125], v[160:163], v[184:187], v[122:125]
	v_mfma_f32_16x16x32_bf16 v[118:121], v[146:149], v[192:195], v[118:121]
	v_mfma_f32_16x16x32_bf16 v[110:113], v[160:163], v[192:195], v[110:113]
	v_mfma_f32_16x16x32_bf16 v[102:105], v[146:149], v[200:203], v[102:105]
	v_mfma_f32_16x16x32_bf16 v[94:97], v[160:163], v[200:203], v[94:97]
	v_mfma_f32_16x16x32_bf16 v[86:89], v[146:149], v[208:211], v[86:89]
	v_mfma_f32_16x16x32_bf16 v[78:81], v[160:163], v[208:211], v[78:81]
	v_mfma_f32_16x16x32_bf16 v[126:129], v[156:159], v[188:191], v[126:129]
	v_mfma_f32_16x16x32_bf16 v[122:125], v[164:167], v[188:191], v[122:125]
	v_mfma_f32_16x16x32_bf16 v[118:121], v[156:159], v[196:199], v[118:121]
	v_mfma_f32_16x16x32_bf16 v[110:113], v[164:167], v[196:199], v[110:113]
	v_mfma_f32_16x16x32_bf16 v[102:105], v[156:159], v[204:207], v[102:105]
	v_mfma_f32_16x16x32_bf16 v[94:97], v[164:167], v[204:207], v[94:97]
	v_mfma_f32_16x16x32_bf16 v[86:89], v[156:159], v[212:215], v[86:89]
	v_mfma_f32_16x16x32_bf16 v[78:81], v[164:167], v[212:215], v[78:81]
	v_mfma_f32_16x16x32_bf16 v[114:117], v[168:171], v[184:187], v[114:117]
	v_mfma_f32_16x16x32_bf16 v[106:109], v[176:179], v[184:187], v[106:109]
	v_mfma_f32_16x16x32_bf16 v[98:101], v[168:171], v[192:195], v[98:101]
	v_mfma_f32_16x16x32_bf16 v[90:93], v[176:179], v[192:195], v[90:93]
	v_mfma_f32_16x16x32_bf16 v[82:85], v[168:171], v[200:203], v[82:85]
	v_mfma_f32_16x16x32_bf16 v[74:77], v[176:179], v[200:203], v[74:77]
	v_mfma_f32_16x16x32_bf16 v[70:73], v[168:171], v[208:211], v[70:73]
	v_mfma_f32_16x16x32_bf16 v[66:69], v[176:179], v[208:211], v[66:69]
	v_mfma_f32_16x16x32_bf16 v[114:117], v[172:175], v[188:191], v[114:117]
	v_mfma_f32_16x16x32_bf16 v[106:109], v[180:183], v[188:191], v[106:109]
	v_mfma_f32_16x16x32_bf16 v[98:101], v[172:175], v[196:199], v[98:101]
	v_mfma_f32_16x16x32_bf16 v[90:93], v[180:183], v[196:199], v[90:93]
	v_mfma_f32_16x16x32_bf16 v[82:85], v[172:175], v[204:207], v[82:85]
	v_mfma_f32_16x16x32_bf16 v[74:77], v[180:183], v[204:207], v[74:77]
	v_mfma_f32_16x16x32_bf16 v[70:73], v[172:175], v[212:215], v[70:73]
	v_mfma_f32_16x16x32_bf16 v[66:69], v[180:183], v[212:215], v[66:69]
	s_waitcnt vmcnt(8)
	s_barrier
	s_setprio 0
	s_add_i32 s50, s42, s31
	v_lshl_add_u64 v[216:217], s[22:23], 0, v[132:133]
	s_mov_b32 m0, s50
	ds_read_b128 v[184:187], v154 offset:16384
	ds_read_b128 v[188:191], v154 offset:17408
	ds_read_b128 v[192:195], v154 offset:18432
	ds_read_b128 v[196:199], v154 offset:19456
	ds_read_b128 v[200:203], v154 offset:20480
	ds_read_b128 v[204:207], v154 offset:21504
	ds_read_b128 v[208:211], v154 offset:22528
	ds_read_b128 v[212:215], v154 offset:23552
	global_load_lds_dwordx4 v[216:217], off
	s_add_i32 m0, s50, 0x2000
	s_add_u32 s50, s22, 0x40000
	v_lshl_add_u64 v[218:219], s[22:23], 0, v[136:137]
	s_addc_u32 s51, s23, 0
	s_add_i32 s52, s43, s31
	global_load_lds_dwordx4 v[218:219], off
	s_mov_b32 m0, s52
	v_lshl_add_u64 v[222:223], s[24:25], 0, v[134:135]
	global_load_lds_dwordx4 v132, s[50:51]
	s_add_i32 m0, s52, 0x2000
	s_nop 0
	global_load_lds_dwordx4 v136, s[50:51]
	v_lshl_add_u64 v[220:221], s[24:25], 0, v[130:131]
	s_mov_b32 m0, s19
	s_nop 0
	global_load_lds_dwordx4 v[220:221], off
	s_mov_b32 m0, s33
	s_nop 0
	global_load_lds_dwordx4 v[222:223], off
	s_and_b64 vcc, exec, s[8:9]
	s_cbranch_vccnz .Lkw451_1
	s_waitcnt vmcnt(8)
; #define PG8_STAGE(bufoff, gbase, voff) do { _Pragma("unroll") for (int _i = 0; _i < 2; ++_i) \
;         __builtin_amdgcn_global_load_lds((const unsigned*)((const char*)(gbase) + (voff)[_i]), (LAS unsigned*)(lds + (bufoff) + ldsw + _i * 8192), 16, 0, 0); } while (0)
; #define PG8_LDA(dst, b, h) do { _Pragma("unroll") for (int m = 0; m < 4; ++m) _Pragma("unroll") for (int k = 0; k < 2; ++k) dst[m][k] = *(const LAS bf16x8*)(lds + PG8_SA(b, h) + aoff + m * 2048 + k * 1024); } while (0)
; #define PG8_LDB(dst, b, h) do { _Pragma("unroll") for (int n = 0; n < 2; ++n) _Pragma("unroll") for (int k = 0; k < 2; ++k) dst[n][k] = *(const LAS bf16x8*)(lds + PG8_SB(b, h) + boff + n * 2048 + k * 1024); } while (0)
; #define PG8_MMA(ai, bj, At, Bt) do { __builtin_amdgcn_s_setprio(1); _Pragma("unroll") for (int m = 0; m < 4; ++m) _Pragma("unroll") for (int n = 0; n < 2; ++n) _Pragma("unroll") for (int k = 0; k < 2; ++k) \
;         acc[ai][bj][m][n] = __builtin_amdgcn_mfma_f32_16x16x32_bf16(Bt[n][k], At[m][k], acc[ai][bj][m][n], 0, 0, 0); __builtin_amdgcn_s_setprio(0); } while (0)
; #define PG8_WAIT_V(n) asm volatile("s_waitcnt vmcnt(" #n ")" ::: "memory")
; #define PG8_WAIT_L(n) asm volatile("s_waitcnt lgkmcnt(" #n ")" ::: "memory")
; #define PG8_BAR __builtin_amdgcn_s_barrier()
; #define PG8_SCHED __builtin_amdgcn_sched_barrier(0)
; template <class Epi, class Sched, bool ALIGN_EPI = true, bool SP2 = true>
; __device__ __forceinline__ void gemm_phase(LAS unsigned char* lds, const Gemm g, const Sched& S, const Epi& E) {
;     ...
;             PG8_WAIT_V(8); PG8_WAIT_L(0); PG8_BAR; PG8_MMA(1, 0, At, B0); PG8_MMA(1, 1, At, B1); PG8_BAR; PG8_SCHED;
;             PG8_LDB(B0, 1, 0); PG8_LDB(B1, 1, 1); PG8_SCHED; PG8_LDA(At, 1, 0); PG8_STAGE(PG8_SA(0, 1), a2 + hstep, voffA);
.Lkw451_1:
	s_waitcnt lgkmcnt(0)
	s_setprio 1
	s_barrier
	v_mfma_f32_16x16x32_bf16 v[62:65], v[146:149], v[184:187], v[62:65]
	v_mfma_f32_16x16x32_bf16 v[58:61], v[160:163], v[184:187], v[58:61]
	v_mfma_f32_16x16x32_bf16 v[54:57], v[146:149], v[192:195], v[54:57]
	v_mfma_f32_16x16x32_bf16 v[46:49], v[160:163], v[192:195], v[46:49]
	v_mfma_f32_16x16x32_bf16 v[38:41], v[146:149], v[200:203], v[38:41]
	v_mfma_f32_16x16x32_bf16 v[30:33], v[160:163], v[200:203], v[30:33]
	v_mfma_f32_16x16x32_bf16 v[22:25], v[146:149], v[208:211], v[22:25]
	v_mfma_f32_16x16x32_bf16 v[14:17], v[160:163], v[208:211], v[14:17]
	v_mfma_f32_16x16x32_bf16 v[62:65], v[156:159], v[188:191], v[62:65]
	v_mfma_f32_16x16x32_bf16 v[58:61], v[164:167], v[188:191], v[58:61]
	v_mfma_f32_16x16x32_bf16 v[54:57], v[156:159], v[196:199], v[54:57]
	v_mfma_f32_16x16x32_bf16 v[46:49], v[164:167], v[196:199], v[46:49]
	v_mfma_f32_16x16x32_bf16 v[38:41], v[156:159], v[204:207], v[38:41]
	v_mfma_f32_16x16x32_bf16 v[30:33], v[164:167], v[204:207], v[30:33]
	v_mfma_f32_16x16x32_bf16 v[22:25], v[156:159], v[212:215], v[22:25]
	v_mfma_f32_16x16x32_bf16 v[14:17], v[164:167], v[212:215], v[14:17]
	v_mfma_f32_16x16x32_bf16 v[50:53], v[168:171], v[184:187], v[50:53]
	v_mfma_f32_16x16x32_bf16 v[42:45], v[176:179], v[184:187], v[42:45]
	v_mfma_f32_16x16x32_bf16 v[34:37], v[168:171], v[192:195], v[34:37]
	v_mfma_f32_16x16x32_bf16 v[26:29], v[176:179], v[192:195], v[26:29]
	v_mfma_f32_16x16x32_bf16 v[18:21], v[168:171], v[200:203], v[18:21]
	v_mfma_f32_16x16x32_bf16 v[10:13], v[176:179], v[200:203], v[10:13]
	v_mfma_f32_16x16x32_bf16 v[6:9], v[168:171], v[208:211], v[6:9]
	v_mfma_f32_16x16x32_bf16 v[2:5], v[176:179], v[208:211], v[2:5]
	v_mfma_f32_16x16x32_bf16 v[50:53], v[172:175], v[188:191], v[50:53]
	v_mfma_f32_16x16x32_bf16 v[42:45], v[180:183], v[188:191], v[42:45]
	v_mfma_f32_16x16x32_bf16 v[34:37], v[172:175], v[196:199], v[34:37]
	v_mfma_f32_16x16x32_bf16 v[26:29], v[180:183], v[196:199], v[26:29]
	v_mfma_f32_16x16x32_bf16 v[18:21], v[172:175], v[204:207], v[18:21]
	v_mfma_f32_16x16x32_bf16 v[10:13], v[180:183], v[204:207], v[10:13]
	v_mfma_f32_16x16x32_bf16 v[6:9], v[172:175], v[212:215], v[6:9]
	v_mfma_f32_16x16x32_bf16 v[2:5], v[180:183], v[212:215], v[2:5]
	s_waitcnt vmcnt(8)
	s_barrier
	s_setprio 0
	s_add_i32 s50, 0, 0x18000
	v_add_u32_e32 v155, s50, v150
	s_add_i32 s51, 0, 0x1c000
	ds_read_b128 v[146:149], v155
	ds_read_b128 v[156:159], v155 offset:1024
	ds_read_b128 v[160:163], v155 offset:2048
	ds_read_b128 v[164:167], v155 offset:3072
	v_add_u32_e32 v155, s51, v150
	ds_read_b128 v[168:171], v155
	ds_read_b128 v[172:175], v155 offset:1024
	ds_read_b128 v[176:179], v155 offset:2048
	ds_read_b128 v[180:183], v155 offset:3072
	s_add_u32 s24, s24, 0x40000
	s_addc_u32 s25, s25, 0
	s_mov_b32 m0, s34
	ds_read_b128 v[184:187], v154 offset:32768
	ds_read_b128 v[188:191], v154 offset:33792
	ds_read_b128 v[192:195], v154 offset:34816
	ds_read_b128 v[196:199], v154 offset:35840
	ds_read_b128 v[200:203], v154 offset:36864
	ds_read_b128 v[204:207], v154 offset:37888
	ds_read_b128 v[208:211], v154 offset:38912
	ds_read_b128 v[212:215], v154 offset:39936
	global_load_lds_dwordx4 v130, s[24:25]
	s_mov_b32 m0, s35
	s_nop 0
	global_load_lds_dwordx4 v134, s[24:25]
	s_and_b64 vcc, exec, s[8:9]
	s_cbranch_vccnz .Lkw451_2
	s_waitcnt vmcnt(8)
; #define PG8_STAGE(bufoff, gbase, voff) do { _Pragma("unroll") for (int _i = 0; _i < 2; ++_i) \
;         __builtin_amdgcn_global_load_lds((const unsigned*)((const char*)(gbase) + (voff)[_i]), (LAS unsigned*)(lds + (bufoff) + ldsw + _i * 8192), 16, 0, 0); } while (0)
; #define PG8_LDA(dst, b, h) do { _Pragma("unroll") for (int m = 0; m < 4; ++m) _Pragma("unroll") for (int k = 0; k < 2; ++k) dst[m][k] = *(const LAS bf16x8*)(lds + PG8_SA(b, h) + aoff + m * 2048 + k * 1024); } while (0)
; #define PG8_MMA(ai, bj, At, Bt) do { __builtin_amdgcn_s_setprio(1); _Pragma("unroll") for (int m = 0; m < 4; ++m) _Pragma("unroll") for (int n = 0; n < 2; ++n) _Pragma("unroll") for (int k = 0; k < 2; ++k) \
;         acc[ai][bj][m][n] = __builtin_amdgcn_mfma_f32_16x16x32_bf16(Bt[n][k], At[m][k], acc[ai][bj][m][n], 0, 0, 0); __builtin_amdgcn_s_setprio(0); } while (0)
; #define PG8_WAIT_V(n) asm volatile("s_waitcnt vmcnt(" #n ")" ::: "memory")
; #define PG8_WAIT_L(n) asm volatile("s_waitcnt lgkmcnt(" #n ")" ::: "memory")
; #define PG8_BAR __builtin_amdgcn_s_barrier()
; #define PG8_SCHED __builtin_amdgcn_sched_barrier(0)
; template <class Epi, class Sched, bool ALIGN_EPI = true, bool SP2 = true>
; __device__ __forceinline__ void gemm_phase(LAS unsigned char* lds, const Gemm g, const Sched& S, const Epi& E) {
;     ...
;         for (int t = 0; t < nt; t += 2) {
;     ...
;             PG8_WAIT_V(8); PG8_WAIT_L(0); PG8_BAR; PG8_MMA(0, 0, At, B0); PG8_MMA(0, 1, At, B1); PG8_BAR; PG8_SCHED;
;             PG8_LDA(At, 1, 1); PG8_STAGE(PG8_SB(1, 0), b3, voffB); PG8_STAGE(PG8_SB(1, 1), b3 + hstep, voffB); PG8_STAGE(PG8_SA(1, 0), a3, voffA);
;             PG8_WAIT_V(8); PG8_WAIT_L(0); PG8_BAR; PG8_MMA(1, 0, At, B0); PG8_MMA(1, 1, At, B1); PG8_BAR; PG8_SCHED;
.Lkw451_2:
	s_waitcnt lgkmcnt(0)
	s_setprio 1
	s_barrier
	v_mfma_f32_16x16x32_bf16 v[126:129], v[146:149], v[184:187], v[126:129]
	v_mfma_f32_16x16x32_bf16 v[122:125], v[160:163], v[184:187], v[122:125]
	v_mfma_f32_16x16x32_bf16 v[118:121], v[146:149], v[192:195], v[118:121]
	v_mfma_f32_16x16x32_bf16 v[110:113], v[160:163], v[192:195], v[110:113]
	v_mfma_f32_16x16x32_bf16 v[102:105], v[146:149], v[200:203], v[102:105]
	v_mfma_f32_16x16x32_bf16 v[94:97], v[160:163], v[200:203], v[94:97]
	v_mfma_f32_16x16x32_bf16 v[86:89], v[146:149], v[208:211], v[86:89]
	v_mfma_f32_16x16x32_bf16 v[78:81], v[160:163], v[208:211], v[78:81]
	v_mfma_f32_16x16x32_bf16 v[126:129], v[156:159], v[188:191], v[126:129]
	v_mfma_f32_16x16x32_bf16 v[122:125], v[164:167], v[188:191], v[122:125]
	v_mfma_f32_16x16x32_bf16 v[118:121], v[156:159], v[196:199], v[118:121]
	v_mfma_f32_16x16x32_bf16 v[110:113], v[164:167], v[196:199], v[110:113]
	v_mfma_f32_16x16x32_bf16 v[102:105], v[156:159], v[204:207], v[102:105]
	v_mfma_f32_16x16x32_bf16 v[94:97], v[164:167], v[204:207], v[94:97]
	v_mfma_f32_16x16x32_bf16 v[86:89], v[156:159], v[212:215], v[86:89]
	v_mfma_f32_16x16x32_bf16 v[78:81], v[164:167], v[212:215], v[78:81]
	v_mfma_f32_16x16x32_bf16 v[114:117], v[168:171], v[184:187], v[114:117]
	v_mfma_f32_16x16x32_bf16 v[106:109], v[176:179], v[184:187], v[106:109]
	v_mfma_f32_16x16x32_bf16 v[98:101], v[168:171], v[192:195], v[98:101]
	v_mfma_f32_16x16x32_bf16 v[90:93], v[176:179], v[192:195], v[90:93]
	v_mfma_f32_16x16x32_bf16 v[82:85], v[168:171], v[200:203], v[82:85]
	v_mfma_f32_16x16x32_bf16 v[74:77], v[176:179], v[200:203], v[74:77]
	v_mfma_f32_16x16x32_bf16 v[70:73], v[168:171], v[208:211], v[70:73]
	v_mfma_f32_16x16x32_bf16 v[66:69], v[176:179], v[208:211], v[66:69]
	v_mfma_f32_16x16x32_bf16 v[114:117], v[172:175], v[188:191], v[114:117]
	v_mfma_f32_16x16x32_bf16 v[106:109], v[180:183], v[188:191], v[106:109]
	v_mfma_f32_16x16x32_bf16 v[98:101], v[172:175], v[196:199], v[98:101]
	v_mfma_f32_16x16x32_bf16 v[90:93], v[180:183], v[196:199], v[90:93]
	v_mfma_f32_16x16x32_bf16 v[82:85], v[172:175], v[204:207], v[82:85]
	v_mfma_f32_16x16x32_bf16 v[74:77], v[180:183], v[204:207], v[74:77]
	v_mfma_f32_16x16x32_bf16 v[70:73], v[172:175], v[212:215], v[70:73]
	v_mfma_f32_16x16x32_bf16 v[66:69], v[180:183], v[212:215], v[66:69]
	s_waitcnt vmcnt(8)
	s_barrier
	s_setprio 0
	s_add_i32 s24, s50, s31
	v_lshl_add_u64 v[216:217], v[216:217], 0, s[6:7]
	s_mov_b32 m0, s24
	ds_read_b128 v[184:187], v154 offset:49152
	ds_read_b128 v[188:191], v154 offset:50176
	ds_read_b128 v[192:195], v154 offset:51200
	ds_read_b128 v[196:199], v154 offset:52224
	ds_read_b128 v[200:203], v154 offset:53248
	ds_read_b128 v[204:207], v154 offset:54272
	ds_read_b128 v[208:211], v154 offset:55296
	ds_read_b128 v[212:215], v154 offset:56320
	global_load_lds_dwordx4 v[216:217], off
	s_add_i32 m0, s24, 0x2000
	s_add_u32 s22, s22, 0x40080
	v_lshl_add_u64 v[216:217], v[218:219], 0, s[6:7]
	s_addc_u32 s23, s23, 0
	s_add_i32 s24, s51, s31
	global_load_lds_dwordx4 v[216:217], off
	s_mov_b32 m0, s24
	s_nop 0
	global_load_lds_dwordx4 v132, s[22:23]
	s_add_i32 m0, s24, 0x2000
	s_nop 0
	global_load_lds_dwordx4 v136, s[22:23]
	v_lshl_add_u64 v[216:217], v[220:221], 0, s[6:7]
	s_mov_b32 m0, s39
	s_nop 0
	global_load_lds_dwordx4 v[216:217], off
	v_lshl_add_u64 v[216:217], v[222:223], 0, s[6:7]
	s_mov_b32 m0, s40
	s_nop 0
	global_load_lds_dwordx4 v[216:217], off
	s_and_b64 vcc, exec, s[8:9]
	s_cbranch_vccnz .Lkw451_3
	s_waitcnt vmcnt(8)
.Lkw451_3:
	s_waitcnt lgkmcnt(0)
	s_setprio 1
	s_barrier
	v_mfma_f32_16x16x32_bf16 v[62:65], v[146:149], v[184:187], v[62:65]
	v_mfma_f32_16x16x32_bf16 v[58:61], v[160:163], v[184:187], v[58:61]
	v_mfma_f32_16x16x32_bf16 v[54:57], v[146:149], v[192:195], v[54:57]
	v_mfma_f32_16x16x32_bf16 v[46:49], v[160:163], v[192:195], v[46:49]
	v_mfma_f32_16x16x32_bf16 v[38:41], v[146:149], v[200:203], v[38:41]
	v_mfma_f32_16x16x32_bf16 v[30:33], v[160:163], v[200:203], v[30:33]
	v_mfma_f32_16x16x32_bf16 v[22:25], v[146:149], v[208:211], v[22:25]
	v_mfma_f32_16x16x32_bf16 v[14:17], v[160:163], v[208:211], v[14:17]
	v_mfma_f32_16x16x32_bf16 v[62:65], v[156:159], v[188:191], v[62:65]
	v_mfma_f32_16x16x32_bf16 v[58:61], v[164:167], v[188:191], v[58:61]
	v_mfma_f32_16x16x32_bf16 v[54:57], v[156:159], v[196:199], v[54:57]
	v_mfma_f32_16x16x32_bf16 v[46:49], v[164:167], v[196:199], v[46:49]
	v_mfma_f32_16x16x32_bf16 v[38:41], v[156:159], v[204:207], v[38:41]
	v_mfma_f32_16x16x32_bf16 v[30:33], v[164:167], v[204:207], v[30:33]
	v_mfma_f32_16x16x32_bf16 v[22:25], v[156:159], v[212:215], v[22:25]
	v_mfma_f32_16x16x32_bf16 v[14:17], v[164:167], v[212:215], v[14:17]
	v_mfma_f32_16x16x32_bf16 v[50:53], v[168:171], v[184:187], v[50:53]
	v_mfma_f32_16x16x32_bf16 v[42:45], v[176:179], v[184:187], v[42:45]
	v_mfma_f32_16x16x32_bf16 v[34:37], v[168:171], v[192:195], v[34:37]
	v_mfma_f32_16x16x32_bf16 v[26:29], v[176:179], v[192:195], v[26:29]
	v_mfma_f32_16x16x32_bf16 v[18:21], v[168:171], v[200:203], v[18:21]
	v_mfma_f32_16x16x32_bf16 v[10:13], v[176:179], v[200:203], v[10:13]
	v_mfma_f32_16x16x32_bf16 v[6:9], v[168:171], v[208:211], v[6:9]
	v_mfma_f32_16x16x32_bf16 v[2:5], v[176:179], v[208:211], v[2:5]
	v_mfma_f32_16x16x32_bf16 v[50:53], v[172:175], v[188:191], v[50:53]
	v_mfma_f32_16x16x32_bf16 v[42:45], v[180:183], v[188:191], v[42:45]
	v_mfma_f32_16x16x32_bf16 v[34:37], v[172:175], v[196:199], v[34:37]
	v_mfma_f32_16x16x32_bf16 v[26:29], v[180:183], v[196:199], v[26:29]
	v_mfma_f32_16x16x32_bf16 v[18:21], v[172:175], v[204:207], v[18:21]
	v_mfma_f32_16x16x32_bf16 v[10:13], v[180:183], v[204:207], v[10:13]
	v_mfma_f32_16x16x32_bf16 v[6:9], v[172:175], v[212:215], v[6:9]
	v_mfma_f32_16x16x32_bf16 v[2:5], v[180:183], v[212:215], v[2:5]
	s_waitcnt vmcnt(8)
	s_barrier
	s_setprio 0
	s_add_i32 s49, s49, 2
	s_add_u32 s20, s20, 0x100
	s_addc_u32 s21, s21, 0
	s_add_u32 s47, s47, 0x100
	s_addc_u32 s48, s48, 0
	s_cmp_gt_u32 s49, 13
	s_cbranch_scc0 .LBB0_451
	s_and_b64 vcc, exec, s[8:9]
	s_cbranch_vccz .LBB0_454
	s_barrier

; #define PG8_STAGE(bufoff, gbase, voff) do { _Pragma("unroll") for (int _i = 0; _i < 2; ++_i) \
;         __builtin_amdgcn_global_load_lds((const unsigned*)((const char*)(gbase) + (voff)[_i]), (LAS unsigned*)(lds + (bufoff) + ldsw + _i * 8192), 16, 0, 0); } while (0)
; #define PG8_LDA(dst, b, h) do { _Pragma("unroll") for (int m = 0; m < 4; ++m) _Pragma("unroll") for (int k = 0; k < 2; ++k) dst[m][k] = *(const LAS bf16x8*)(lds + PG8_SA(b, h) + aoff + m * 2048 + k * 1024); } while (0)
; #define PG8_LDB(dst, b, h) do { _Pragma("unroll") for (int n = 0; n < 2; ++n) _Pragma("unroll") for (int k = 0; k < 2; ++k) dst[n][k] = *(const LAS bf16x8*)(lds + PG8_SB(b, h) + boff + n * 2048 + k * 1024); } while (0)
; #define PG8_MMA(ai, bj, At, Bt) do { __builtin_amdgcn_s_setprio(1); _Pragma("unroll") for (int m = 0; m < 4; ++m) _Pragma("unroll") for (int n = 0; n < 2; ++n) _Pragma("unroll") for (int k = 0; k < 2; ++k) \
;         acc[ai][bj][m][n] = __builtin_amdgcn_mfma_f32_16x16x32_bf16(Bt[n][k], At[m][k], acc[ai][bj][m][n], 0, 0, 0); __builtin_amdgcn_s_setprio(0); } while (0)
; #define PG8_WAIT_V(n) asm volatile("s_waitcnt vmcnt(" #n ")" ::: "memory")
; #define PG8_WAIT_L(n) asm volatile("s_waitcnt lgkmcnt(" #n ")" ::: "memory")
; #define PG8_BAR __builtin_amdgcn_s_barrier()
; #define PG8_SCHED __builtin_amdgcn_sched_barrier(0)
; template <class Epi, class Sched, bool ALIGN_EPI = true, bool SP2 = true>
; __device__ __forceinline__ void gemm_phase(LAS unsigned char* lds, const Gemm g, const Sched& S, const Epi& E) {
;     ...
;             const char* a1 = cA + (size_t)(t + 1) * kstep;
;             const char* a2 = last ? nA : cA + (size_t)(t + 2) * kstep; const char* b2 = last ? nB : cB + (size_t)(t + 2) * kstep;
;             const char* a3 = a2 + kstep; const char* b3 = b2 + kstep;
;             if (last && has_next) S.a_ready(nxt);
;             if constexpr (SP2) {
;             PG8_LDB(B0, 0, 0); PG8_LDB(B1, 0, 1); PG8_SCHED; PG8_LDA(At, 0, 0); PG8_STAGE(PG8_SA(1, 1), a1 + hstep, voffA);
;             PG8_WAIT_V(8); PG8_WAIT_L(0); PG8_BAR; PG8_MMA(0, 0, At, B0); PG8_MMA(0, 1, At, B1); PG8_BAR; PG8_SCHED;
;             PG8_LDA(At, 0, 1); PG8_STAGE(PG8_SB(0, 0), b2, voffB); PG8_STAGE(PG8_SB(0, 1), b2 + hstep, voffB); PG8_STAGE(PG8_SA(0, 0), a2, voffA);
;             PG8_WAIT_V(8); PG8_WAIT_L(0); PG8_BAR; PG8_MMA(1, 0, At, B0); PG8_MMA(1, 1, At, B1); PG8_BAR; PG8_SCHED;
.LBB0_1460:
	ds_read_b128 v[114:117], v221
	ds_read_b128 v[118:121], v221 offset:1024
	ds_read_b128 v[130:133], v221 offset:2048
	ds_read_b128 v[134:137], v221 offset:3072
	ds_read_b128 v[142:145], v222
	ds_read_b128 v[150:153], v222 offset:1024
	ds_read_b128 v[154:157], v222 offset:2048
	ds_read_b128 v[158:161], v222 offset:3072
	s_add_u32 s36, s34, 0xfff80080
	s_addc_u32 s37, s35, -1
	s_cmp_eq_u32 s64, 28
	s_cselect_b32 s39, s25, s37
	s_cselect_b32 s38, s31, s36
	s_cselect_b32 s37, s23, s63
	s_cselect_b32 s36, s61, s62
	s_add_i32 m0, s44, 0xc000
	ds_read_b128 v[162:165], v223
	ds_read_b128 v[166:169], v223 offset:1024
	ds_read_b128 v[170:173], v223 offset:2048
	ds_read_b128 v[174:177], v223 offset:3072
	ds_read_b128 v[178:181], v223 offset:4096
	ds_read_b128 v[182:185], v223 offset:5120
	ds_read_b128 v[186:189], v223 offset:6144
	ds_read_b128 v[190:193], v223 offset:7168
	global_load_lds_dwordx4 v202, s[34:35]
	s_add_i32 m0, s44, 0xe000
	s_nop 0
	global_load_lds_dwordx4 v204, s[34:35]
	s_and_b64 vcc, exec, s[14:15]
	s_cbranch_vccnz .Lkw1460_0
	s_waitcnt vmcnt(8)
.Lkw1460_0:
	s_waitcnt lgkmcnt(0)
	s_setprio 1
	s_barrier
	v_mfma_f32_16x16x32_bf16 v[146:149], v[114:117], v[162:165], v[146:149]
	v_mfma_f32_16x16x32_bf16 v[138:141], v[130:133], v[162:165], v[138:141]
	v_mfma_f32_16x16x32_bf16 v[110:113], v[114:117], v[170:173], v[110:113]
	v_mfma_f32_16x16x32_bf16 v[106:109], v[130:133], v[170:173], v[106:109]
	v_mfma_f32_16x16x32_bf16 v[94:97], v[114:117], v[178:181], v[94:97]
	v_mfma_f32_16x16x32_bf16 v[90:93], v[130:133], v[178:181], v[90:93]
	v_mfma_f32_16x16x32_bf16 v[78:81], v[114:117], v[186:189], v[78:81]
	v_mfma_f32_16x16x32_bf16 v[74:77], v[130:133], v[186:189], v[74:77]
	v_mfma_f32_16x16x32_bf16 v[146:149], v[118:121], v[166:169], v[146:149]
	v_mfma_f32_16x16x32_bf16 v[138:141], v[134:137], v[166:169], v[138:141]
	v_mfma_f32_16x16x32_bf16 v[110:113], v[118:121], v[174:177], v[110:113]
	v_mfma_f32_16x16x32_bf16 v[106:109], v[134:137], v[174:177], v[106:109]
	v_mfma_f32_16x16x32_bf16 v[94:97], v[118:121], v[182:185], v[94:97]
	v_mfma_f32_16x16x32_bf16 v[90:93], v[134:137], v[182:185], v[90:93]
	v_mfma_f32_16x16x32_bf16 v[78:81], v[118:121], v[190:193], v[78:81]
	v_mfma_f32_16x16x32_bf16 v[74:77], v[134:137], v[190:193], v[74:77]
	v_mfma_f32_16x16x32_bf16 v[126:129], v[142:145], v[162:165], v[126:129]
	v_mfma_f32_16x16x32_bf16 v[122:125], v[154:157], v[162:165], v[122:125]
	v_mfma_f32_16x16x32_bf16 v[102:105], v[142:145], v[170:173], v[102:105]
	v_mfma_f32_16x16x32_bf16 v[98:101], v[154:157], v[170:173], v[98:101]
	v_mfma_f32_16x16x32_bf16 v[86:89], v[142:145], v[178:181], v[86:89]
	v_mfma_f32_16x16x32_bf16 v[82:85], v[154:157], v[178:181], v[82:85]
	v_mfma_f32_16x16x32_bf16 v[70:73], v[142:145], v[186:189], v[70:73]
	v_mfma_f32_16x16x32_bf16 v[66:69], v[154:157], v[186:189], v[66:69]
	v_mfma_f32_16x16x32_bf16 v[126:129], v[150:153], v[166:169], v[126:129]
	v_mfma_f32_16x16x32_bf16 v[122:125], v[158:161], v[166:169], v[122:125]
	v_mfma_f32_16x16x32_bf16 v[102:105], v[150:153], v[174:177], v[102:105]
	v_mfma_f32_16x16x32_bf16 v[98:101], v[158:161], v[174:177], v[98:101]
	v_mfma_f32_16x16x32_bf16 v[86:89], v[150:153], v[182:185], v[86:89]
	v_mfma_f32_16x16x32_bf16 v[82:85], v[158:161], v[182:185], v[82:85]
	v_mfma_f32_16x16x32_bf16 v[70:73], v[150:153], v[190:193], v[70:73]
	v_mfma_f32_16x16x32_bf16 v[66:69], v[158:161], v[190:193], v[66:69]
	s_waitcnt vmcnt(8)
	s_barrier
	s_setprio 0
	s_add_i32 s65, s57, s43
	v_lshl_add_u64 v[210:211], s[36:37], 0, v[196:197]
	s_mov_b32 m0, s65
	ds_read_b128 v[162:165], v223 offset:16384
	ds_read_b128 v[166:169], v223 offset:17408
	ds_read_b128 v[170:173], v223 offset:18432
	ds_read_b128 v[174:177], v223 offset:19456
	ds_read_b128 v[178:181], v223 offset:20480
	ds_read_b128 v[182:185], v223 offset:21504
	ds_read_b128 v[186:189], v223 offset:22528
	ds_read_b128 v[190:193], v223 offset:23552
	global_load_lds_dwordx4 v[210:211], off
	s_add_i32 m0, s65, 0x2000
	s_add_u32 s66, s36, 0x80000
	v_lshl_add_u64 v[212:213], s[36:37], 0, v[200:201]
	s_addc_u32 s67, s37, 0
	s_add_i32 s65, s58, s43
	global_load_lds_dwordx4 v[212:213], off
	s_mov_b32 m0, s65
	v_lshl_add_u64 v[216:217], s[38:39], 0, v[198:199]
	global_load_lds_dwordx4 v196, s[66:67]
	s_add_i32 m0, s65, 0x2000
	s_nop 0
	global_load_lds_dwordx4 v200, s[66:67]
	v_lshl_add_u64 v[214:215], s[38:39], 0, v[194:195]
	s_mov_b32 m0, s44
	s_nop 0
	global_load_lds_dwordx4 v[214:215], off
	s_mov_b32 m0, s45
	s_nop 0
	global_load_lds_dwordx4 v[216:217], off
	s_and_b64 vcc, exec, s[14:15]
	s_cbranch_vccnz .Lkw1460_1
	s_waitcnt vmcnt(8)
; #define PG8_STAGE(bufoff, gbase, voff) do { _Pragma("unroll") for (int _i = 0; _i < 2; ++_i) \
;         __builtin_amdgcn_global_load_lds((const unsigned*)((const char*)(gbase) + (voff)[_i]), (LAS unsigned*)(lds + (bufoff) + ldsw + _i * 8192), 16, 0, 0); } while (0)
; #define PG8_LDA(dst, b, h) do { _Pragma("unroll") for (int m = 0; m < 4; ++m) _Pragma("unroll") for (int k = 0; k < 2; ++k) dst[m][k] = *(const LAS bf16x8*)(lds + PG8_SA(b, h) + aoff + m * 2048 + k * 1024); } while (0)
; #define PG8_LDB(dst, b, h) do { _Pragma("unroll") for (int n = 0; n < 2; ++n) _Pragma("unroll") for (int k = 0; k < 2; ++k) dst[n][k] = *(const LAS bf16x8*)(lds + PG8_SB(b, h) + boff + n * 2048 + k * 1024); } while (0)
; #define PG8_MMA(ai, bj, At, Bt) do { __builtin_amdgcn_s_setprio(1); _Pragma("unroll") for (int m = 0; m < 4; ++m) _Pragma("unroll") for (int n = 0; n < 2; ++n) _Pragma("unroll") for (int k = 0; k < 2; ++k) \
;         acc[ai][bj][m][n] = __builtin_amdgcn_mfma_f32_16x16x32_bf16(Bt[n][k], At[m][k], acc[ai][bj][m][n], 0, 0, 0); __builtin_amdgcn_s_setprio(0); } while (0)
; #define PG8_WAIT_V(n) asm volatile("s_waitcnt vmcnt(" #n ")" ::: "memory")
; #define PG8_WAIT_L(n) asm volatile("s_waitcnt lgkmcnt(" #n ")" ::: "memory")
; #define PG8_BAR __builtin_amdgcn_s_barrier()
; #define PG8_SCHED __builtin_amdgcn_sched_barrier(0)
; template <class Epi, class Sched, bool ALIGN_EPI = true, bool SP2 = true>
; __device__ __forceinline__ void gemm_phase(LAS unsigned char* lds, const Gemm g, const Sched& S, const Epi& E) {
;     ...
;             PG8_WAIT_V(8); PG8_WAIT_L(0); PG8_BAR; PG8_MMA(1, 0, At, B0); PG8_MMA(1, 1, At, B1); PG8_BAR; PG8_SCHED;
;             PG8_LDB(B0, 1, 0); PG8_LDB(B1, 1, 1); PG8_SCHED; PG8_LDA(At, 1, 0); PG8_STAGE(PG8_SA(0, 1), a2 + hstep, voffA);
.Lkw1460_1:
	s_waitcnt lgkmcnt(0)
	s_setprio 1
	s_barrier
	v_mfma_f32_16x16x32_bf16 v[62:65], v[114:117], v[162:165], v[62:65]
	v_mfma_f32_16x16x32_bf16 v[58:61], v[130:133], v[162:165], v[58:61]
	v_mfma_f32_16x16x32_bf16 v[46:49], v[114:117], v[170:173], v[46:49]
	v_mfma_f32_16x16x32_bf16 v[42:45], v[130:133], v[170:173], v[42:45]
	v_mfma_f32_16x16x32_bf16 v[30:33], v[114:117], v[178:181], v[30:33]
	v_mfma_f32_16x16x32_bf16 v[26:29], v[130:133], v[178:181], v[26:29]
	v_mfma_f32_16x16x32_bf16 v[14:17], v[114:117], v[186:189], v[14:17]
	v_mfma_f32_16x16x32_bf16 v[10:13], v[130:133], v[186:189], v[10:13]
	v_mfma_f32_16x16x32_bf16 v[62:65], v[118:121], v[166:169], v[62:65]
	v_mfma_f32_16x16x32_bf16 v[58:61], v[134:137], v[166:169], v[58:61]
	v_mfma_f32_16x16x32_bf16 v[46:49], v[118:121], v[174:177], v[46:49]
	v_mfma_f32_16x16x32_bf16 v[42:45], v[134:137], v[174:177], v[42:45]
	v_mfma_f32_16x16x32_bf16 v[30:33], v[118:121], v[182:185], v[30:33]
	v_mfma_f32_16x16x32_bf16 v[26:29], v[134:137], v[182:185], v[26:29]
	v_mfma_f32_16x16x32_bf16 v[14:17], v[118:121], v[190:193], v[14:17]
	v_mfma_f32_16x16x32_bf16 v[10:13], v[134:137], v[190:193], v[10:13]
	v_mfma_f32_16x16x32_bf16 v[54:57], v[142:145], v[162:165], v[54:57]
	v_mfma_f32_16x16x32_bf16 v[50:53], v[154:157], v[162:165], v[50:53]
	v_mfma_f32_16x16x32_bf16 v[38:41], v[142:145], v[170:173], v[38:41]
	v_mfma_f32_16x16x32_bf16 v[34:37], v[154:157], v[170:173], v[34:37]
	v_mfma_f32_16x16x32_bf16 v[22:25], v[142:145], v[178:181], v[22:25]
	v_mfma_f32_16x16x32_bf16 v[18:21], v[154:157], v[178:181], v[18:21]
	v_mfma_f32_16x16x32_bf16 v[6:9], v[142:145], v[186:189], v[6:9]
	v_mfma_f32_16x16x32_bf16 v[2:5], v[154:157], v[186:189], v[2:5]
	v_mfma_f32_16x16x32_bf16 v[54:57], v[150:153], v[166:169], v[54:57]
	v_mfma_f32_16x16x32_bf16 v[50:53], v[158:161], v[166:169], v[50:53]
	v_mfma_f32_16x16x32_bf16 v[38:41], v[150:153], v[174:177], v[38:41]
	v_mfma_f32_16x16x32_bf16 v[34:37], v[158:161], v[174:177], v[34:37]
	v_mfma_f32_16x16x32_bf16 v[22:25], v[150:153], v[182:185], v[22:25]
	v_mfma_f32_16x16x32_bf16 v[18:21], v[158:161], v[182:185], v[18:21]
	v_mfma_f32_16x16x32_bf16 v[6:9], v[150:153], v[190:193], v[6:9]
	v_mfma_f32_16x16x32_bf16 v[2:5], v[158:161], v[190:193], v[2:5]
	s_waitcnt vmcnt(8)
	s_barrier
	s_setprio 0
	s_add_i32 s65, 0, 0x18000
	s_add_i32 s66, 0, 0x1c000
	v_add_u32_e32 v134, s65, v219
	v_add_u32_e32 v158, s66, v219
	ds_read_b128 v[114:117], v134
	ds_read_b128 v[118:121], v134 offset:1024
	ds_read_b128 v[130:133], v134 offset:2048
	ds_read_b128 v[134:137], v134 offset:3072
	ds_read_b128 v[142:145], v158
	ds_read_b128 v[150:153], v158 offset:1024
	ds_read_b128 v[154:157], v158 offset:2048
	ds_read_b128 v[158:161], v158 offset:3072
	s_add_u32 s38, s38, 0x80000
	s_addc_u32 s39, s39, 0
	s_mov_b32 m0, s46
	ds_read_b128 v[162:165], v223 offset:32768
	ds_read_b128 v[166:169], v223 offset:33792
	ds_read_b128 v[170:173], v223 offset:34816
	ds_read_b128 v[174:177], v223 offset:35840
	ds_read_b128 v[178:181], v223 offset:36864
	ds_read_b128 v[182:185], v223 offset:37888
	ds_read_b128 v[186:189], v223 offset:38912
	ds_read_b128 v[190:193], v223 offset:39936
	global_load_lds_dwordx4 v194, s[38:39]
	s_mov_b32 m0, s47
	s_nop 0
	global_load_lds_dwordx4 v198, s[38:39]
	s_and_b64 vcc, exec, s[14:15]
	s_cbranch_vccnz .Lkw1460_2
	s_waitcnt vmcnt(8)
; #define PG8_STAGE(bufoff, gbase, voff) do { _Pragma("unroll") for (int _i = 0; _i < 2; ++_i) \
;         __builtin_amdgcn_global_load_lds((const unsigned*)((const char*)(gbase) + (voff)[_i]), (LAS unsigned*)(lds + (bufoff) + ldsw + _i * 8192), 16, 0, 0); } while (0)
; #define PG8_LDA(dst, b, h) do { _Pragma("unroll") for (int m = 0; m < 4; ++m) _Pragma("unroll") for (int k = 0; k < 2; ++k) dst[m][k] = *(const LAS bf16x8*)(lds + PG8_SA(b, h) + aoff + m * 2048 + k * 1024); } while (0)
; #define PG8_MMA(ai, bj, At, Bt) do { __builtin_amdgcn_s_setprio(1); _Pragma("unroll") for (int m = 0; m < 4; ++m) _Pragma("unroll") for (int n = 0; n < 2; ++n) _Pragma("unroll") for (int k = 0; k < 2; ++k) \
;         acc[ai][bj][m][n] = __builtin_amdgcn_mfma_f32_16x16x32_bf16(Bt[n][k], At[m][k], acc[ai][bj][m][n], 0, 0, 0); __builtin_amdgcn_s_setprio(0); } while (0)
; #define PG8_WAIT_V(n) asm volatile("s_waitcnt vmcnt(" #n ")" ::: "memory")
; #define PG8_WAIT_L(n) asm volatile("s_waitcnt lgkmcnt(" #n ")" ::: "memory")
; #define PG8_BAR __builtin_amdgcn_s_barrier()
; #define PG8_SCHED __builtin_amdgcn_sched_barrier(0)
; template <class Epi, class Sched, bool ALIGN_EPI = true, bool SP2 = true>
; __device__ __forceinline__ void gemm_phase(LAS unsigned char* lds, const Gemm g, const Sched& S, const Epi& E) {
;     ...
;         for (int t = 0; t < nt; t += 2) {
;     ...
;             PG8_WAIT_V(8); PG8_WAIT_L(0); PG8_BAR; PG8_MMA(0, 0, At, B0); PG8_MMA(0, 1, At, B1); PG8_BAR; PG8_SCHED;
;             PG8_LDA(At, 1, 1); PG8_STAGE(PG8_SB(1, 0), b3, voffB); PG8_STAGE(PG8_SB(1, 1), b3 + hstep, voffB); PG8_STAGE(PG8_SA(1, 0), a3, voffA);
;             PG8_WAIT_V(8); PG8_WAIT_L(0); PG8_BAR; PG8_MMA(1, 0, At, B0); PG8_MMA(1, 1, At, B1); PG8_BAR; PG8_SCHED;
.Lkw1460_2:
	s_waitcnt lgkmcnt(0)
	s_setprio 1
	s_barrier
	v_mfma_f32_16x16x32_bf16 v[146:149], v[114:117], v[162:165], v[146:149]
	v_mfma_f32_16x16x32_bf16 v[138:141], v[130:133], v[162:165], v[138:141]
	v_mfma_f32_16x16x32_bf16 v[110:113], v[114:117], v[170:173], v[110:113]
	v_mfma_f32_16x16x32_bf16 v[106:109], v[130:133], v[170:173], v[106:109]
	v_mfma_f32_16x16x32_bf16 v[94:97], v[114:117], v[178:181], v[94:97]
	v_mfma_f32_16x16x32_bf16 v[90:93], v[130:133], v[178:181], v[90:93]
	v_mfma_f32_16x16x32_bf16 v[78:81], v[114:117], v[186:189], v[78:81]
	v_mfma_f32_16x16x32_bf16 v[74:77], v[130:133], v[186:189], v[74:77]
	v_mfma_f32_16x16x32_bf16 v[146:149], v[118:121], v[166:169], v[146:149]
	v_mfma_f32_16x16x32_bf16 v[138:141], v[134:137], v[166:169], v[138:141]
	v_mfma_f32_16x16x32_bf16 v[110:113], v[118:121], v[174:177], v[110:113]
	v_mfma_f32_16x16x32_bf16 v[106:109], v[134:137], v[174:177], v[106:109]
	v_mfma_f32_16x16x32_bf16 v[94:97], v[118:121], v[182:185], v[94:97]
	v_mfma_f32_16x16x32_bf16 v[90:93], v[134:137], v[182:185], v[90:93]
	v_mfma_f32_16x16x32_bf16 v[78:81], v[118:121], v[190:193], v[78:81]
	v_mfma_f32_16x16x32_bf16 v[74:77], v[134:137], v[190:193], v[74:77]
	v_mfma_f32_16x16x32_bf16 v[126:129], v[142:145], v[162:165], v[126:129]
	v_mfma_f32_16x16x32_bf16 v[122:125], v[154:157], v[162:165], v[122:125]
	v_mfma_f32_16x16x32_bf16 v[102:105], v[142:145], v[170:173], v[102:105]
	v_mfma_f32_16x16x32_bf16 v[98:101], v[154:157], v[170:173], v[98:101]
	v_mfma_f32_16x16x32_bf16 v[86:89], v[142:145], v[178:181], v[86:89]
	v_mfma_f32_16x16x32_bf16 v[82:85], v[154:157], v[178:181], v[82:85]
	v_mfma_f32_16x16x32_bf16 v[70:73], v[142:145], v[186:189], v[70:73]
	v_mfma_f32_16x16x32_bf16 v[66:69], v[154:157], v[186:189], v[66:69]
	v_mfma_f32_16x16x32_bf16 v[126:129], v[150:153], v[166:169], v[126:129]
	v_mfma_f32_16x16x32_bf16 v[122:125], v[158:161], v[166:169], v[122:125]
	v_mfma_f32_16x16x32_bf16 v[102:105], v[150:153], v[174:177], v[102:105]
	v_mfma_f32_16x16x32_bf16 v[98:101], v[158:161], v[174:177], v[98:101]
	v_mfma_f32_16x16x32_bf16 v[86:89], v[150:153], v[182:185], v[86:89]
	v_mfma_f32_16x16x32_bf16 v[82:85], v[158:161], v[182:185], v[82:85]
	v_mfma_f32_16x16x32_bf16 v[70:73], v[150:153], v[190:193], v[70:73]
	v_mfma_f32_16x16x32_bf16 v[66:69], v[158:161], v[190:193], v[66:69]
	s_waitcnt vmcnt(8)
	s_barrier
	s_setprio 0
	s_add_i32 s38, s65, s43
	v_lshl_add_u64 v[210:211], v[210:211], 0, s[12:13]
	s_mov_b32 m0, s38
	ds_read_b128 v[162:165], v223 offset:49152
	ds_read_b128 v[166:169], v223 offset:50176
	ds_read_b128 v[170:173], v223 offset:51200
	ds_read_b128 v[174:177], v223 offset:52224
	ds_read_b128 v[178:181], v223 offset:53248
	ds_read_b128 v[182:185], v223 offset:54272
	ds_read_b128 v[186:189], v223 offset:55296
	ds_read_b128 v[190:193], v223 offset:56320
	global_load_lds_dwordx4 v[210:211], off
	s_add_i32 m0, s38, 0x2000
	s_add_u32 s36, s36, 0x80080
	v_lshl_add_u64 v[210:211], v[212:213], 0, s[12:13]
	s_addc_u32 s37, s37, 0
	s_add_i32 s38, s66, s43
	global_load_lds_dwordx4 v[210:211], off
	s_mov_b32 m0, s38
	s_nop 0
	global_load_lds_dwordx4 v196, s[36:37]
	s_add_i32 m0, s38, 0x2000
	s_nop 0
	global_load_lds_dwordx4 v200, s[36:37]
	v_lshl_add_u64 v[210:211], v[214:215], 0, s[12:13]
	s_mov_b32 m0, s54
	s_nop 0
	global_load_lds_dwordx4 v[210:211], off
	v_lshl_add_u64 v[210:211], v[216:217], 0, s[12:13]
	s_mov_b32 m0, s55
	s_nop 0
	global_load_lds_dwordx4 v[210:211], off
	s_and_b64 vcc, exec, s[14:15]
	s_cbranch_vccnz .Lkw1460_3
	s_waitcnt vmcnt(8)
.Lkw1460_3:
	s_waitcnt lgkmcnt(0)
	s_setprio 1
	s_barrier
	v_mfma_f32_16x16x32_bf16 v[62:65], v[114:117], v[162:165], v[62:65]
	v_mfma_f32_16x16x32_bf16 v[58:61], v[130:133], v[162:165], v[58:61]
	v_mfma_f32_16x16x32_bf16 v[46:49], v[114:117], v[170:173], v[46:49]
	v_mfma_f32_16x16x32_bf16 v[42:45], v[130:133], v[170:173], v[42:45]
	v_mfma_f32_16x16x32_bf16 v[30:33], v[114:117], v[178:181], v[30:33]
	v_mfma_f32_16x16x32_bf16 v[26:29], v[130:133], v[178:181], v[26:29]
	v_mfma_f32_16x16x32_bf16 v[14:17], v[114:117], v[186:189], v[14:17]
	v_mfma_f32_16x16x32_bf16 v[10:13], v[130:133], v[186:189], v[10:13]
	v_mfma_f32_16x16x32_bf16 v[62:65], v[118:121], v[166:169], v[62:65]
	v_mfma_f32_16x16x32_bf16 v[58:61], v[134:137], v[166:169], v[58:61]
	v_mfma_f32_16x16x32_bf16 v[46:49], v[118:121], v[174:177], v[46:49]
	v_mfma_f32_16x16x32_bf16 v[42:45], v[134:137], v[174:177], v[42:45]
	v_mfma_f32_16x16x32_bf16 v[30:33], v[118:121], v[182:185], v[30:33]
	v_mfma_f32_16x16x32_bf16 v[26:29], v[134:137], v[182:185], v[26:29]
	v_mfma_f32_16x16x32_bf16 v[14:17], v[118:121], v[190:193], v[14:17]
	v_mfma_f32_16x16x32_bf16 v[10:13], v[134:137], v[190:193], v[10:13]
	v_mfma_f32_16x16x32_bf16 v[54:57], v[142:145], v[162:165], v[54:57]
	v_mfma_f32_16x16x32_bf16 v[50:53], v[154:157], v[162:165], v[50:53]
	v_mfma_f32_16x16x32_bf16 v[38:41], v[142:145], v[170:173], v[38:41]
	v_mfma_f32_16x16x32_bf16 v[34:37], v[154:157], v[170:173], v[34:37]
	v_mfma_f32_16x16x32_bf16 v[22:25], v[142:145], v[178:181], v[22:25]
	v_mfma_f32_16x16x32_bf16 v[18:21], v[154:157], v[178:181], v[18:21]
	v_mfma_f32_16x16x32_bf16 v[6:9], v[142:145], v[186:189], v[6:9]
	v_mfma_f32_16x16x32_bf16 v[2:5], v[154:157], v[186:189], v[2:5]
	v_mfma_f32_16x16x32_bf16 v[54:57], v[150:153], v[166:169], v[54:57]
	v_mfma_f32_16x16x32_bf16 v[50:53], v[158:161], v[166:169], v[50:53]
	v_mfma_f32_16x16x32_bf16 v[38:41], v[150:153], v[174:177], v[38:41]
	v_mfma_f32_16x16x32_bf16 v[34:37], v[158:161], v[174:177], v[34:37]
	v_mfma_f32_16x16x32_bf16 v[22:25], v[150:153], v[182:185], v[22:25]
	v_mfma_f32_16x16x32_bf16 v[18:21], v[158:161], v[182:185], v[18:21]
	v_mfma_f32_16x16x32_bf16 v[6:9], v[150:153], v[190:193], v[6:9]
	v_mfma_f32_16x16x32_bf16 v[2:5], v[158:161], v[190:193], v[2:5]
	s_waitcnt vmcnt(8)
	s_barrier
	s_setprio 0
	s_add_i32 s64, s64, 2
	s_add_u32 s34, s34, 0x100
	s_addc_u32 s35, s35, 0
	s_add_u32 s62, s62, 0x100
	s_addc_u32 s63, s63, 0
	s_cmp_gt_u32 s64, 29
	s_cbranch_scc0 .LBB0_1460
	s_and_b64 vcc, exec, s[14:15]
	s_cbranch_vccz .LBB0_1463
	s_barrier

; #define PG8_STAGE(bufoff, gbase, voff) do { _Pragma("unroll") for (int _i = 0; _i < 2; ++_i) \
;         __builtin_amdgcn_global_load_lds((const unsigned*)((const char*)(gbase) + (voff)[_i]), (LAS unsigned*)(lds + (bufoff) + ldsw + _i * 8192), 16, 0, 0); } while (0)
; #define PG8_LDA(dst, b, h) do { _Pragma("unroll") for (int m = 0; m < 4; ++m) _Pragma("unroll") for (int k = 0; k < 2; ++k) dst[m][k] = *(const LAS bf16x8*)(lds + PG8_SA(b, h) + aoff + m * 2048 + k * 1024); } while (0)
; #define PG8_LDB(dst, b, h) do { _Pragma("unroll") for (int n = 0; n < 2; ++n) _Pragma("unroll") for (int k = 0; k < 2; ++k) dst[n][k] = *(const LAS bf16x8*)(lds + PG8_SB(b, h) + boff + n * 2048 + k * 1024); } while (0)
; #define PG8_MMA(ai, bj, At, Bt) do { __builtin_amdgcn_s_setprio(1); _Pragma("unroll") for (int m = 0; m < 4; ++m) _Pragma("unroll") for (int n = 0; n < 2; ++n) _Pragma("unroll") for (int k = 0; k < 2; ++k) \
;         acc[ai][bj][m][n] = __builtin_amdgcn_mfma_f32_16x16x32_bf16(Bt[n][k], At[m][k], acc[ai][bj][m][n], 0, 0, 0); __builtin_amdgcn_s_setprio(0); } while (0)
; #define PG8_WAIT_V(n) asm volatile("s_waitcnt vmcnt(" #n ")" ::: "memory")
; #define PG8_WAIT_L(n) asm volatile("s_waitcnt lgkmcnt(" #n ")" ::: "memory")
; #define PG8_BAR __builtin_amdgcn_s_barrier()
; #define PG8_SCHED __builtin_amdgcn_sched_barrier(0)
; template <class Epi, class Sched, bool ALIGN_EPI = true, bool SP2 = true>
; __device__ __forceinline__ void gemm_phase(LAS unsigned char* lds, const Gemm g, const Sched& S, const Epi& E) {
;     ...
;             const char* a1 = cA + (size_t)(t + 1) * kstep;
;             const char* a2 = last ? nA : cA + (size_t)(t + 2) * kstep; const char* b2 = last ? nB : cB + (size_t)(t + 2) * kstep;
;             const char* a3 = a2 + kstep; const char* b3 = b2 + kstep;
;             if (last && has_next) S.a_ready(nxt);
;             if constexpr (SP2) {
;             PG8_LDB(B0, 0, 0); PG8_LDB(B1, 0, 1); PG8_SCHED; PG8_LDA(At, 0, 0); PG8_STAGE(PG8_SA(1, 1), a1 + hstep, voffA);
;             PG8_WAIT_V(8); PG8_WAIT_L(0); PG8_BAR; PG8_MMA(0, 0, At, B0); PG8_MMA(0, 1, At, B1); PG8_BAR; PG8_SCHED;
;             PG8_LDA(At, 0, 1); PG8_STAGE(PG8_SB(0, 0), b2, voffB); PG8_STAGE(PG8_SB(0, 1), b2 + hstep, voffB); PG8_STAGE(PG8_SA(0, 0), a2, voffA);
;             PG8_WAIT_V(8); PG8_WAIT_L(0); PG8_BAR; PG8_MMA(1, 0, At, B0); PG8_MMA(1, 1, At, B1); PG8_BAR; PG8_SCHED;
.LBB0_1639:
	ds_read_b128 v[130:133], v203
	ds_read_b128 v[134:137], v203 offset:1024
	ds_read_b128 v[138:141], v203 offset:2048
	ds_read_b128 v[142:145], v203 offset:3072
	ds_read_b128 v[146:149], v204
	ds_read_b128 v[150:153], v204 offset:1024
	ds_read_b128 v[154:157], v204 offset:2048
	ds_read_b128 v[158:161], v204 offset:3072
	s_add_u32 s54, s52, 0xfff00080
	s_addc_u32 s55, s53, -1
	s_cmp_eq_u32 s74, 60
	s_cselect_b32 s57, s43, s55
	s_cselect_b32 s56, s49, s54
	s_cselect_b32 s55, s41, s73
	s_cselect_b32 s54, s71, s72
	s_add_i32 m0, s51, 0xc000
	ds_read_b128 v[162:165], v205
	ds_read_b128 v[166:169], v205 offset:1024
	ds_read_b128 v[170:173], v205 offset:2048
	ds_read_b128 v[174:177], v205 offset:3072
	ds_read_b128 v[194:197], v205 offset:4096
	ds_read_b128 v[208:211], v205 offset:5120
	ds_read_b128 v[212:215], v205 offset:6144
	ds_read_b128 v[216:219], v205 offset:7168
	global_load_lds_dwordx4 v186, s[52:53]
	s_add_i32 m0, s51, 0xe000
	s_nop 0
	global_load_lds_dwordx4 v188, s[52:53]
	s_and_b64 vcc, exec, s[26:27]
	s_cbranch_vccnz .Lkw1639_0
	s_waitcnt vmcnt(8)
.Lkw1639_0:
	s_waitcnt lgkmcnt(0)
	s_setprio 1
	s_barrier
	v_mfma_f32_16x16x32_bf16 v[126:129], v[130:133], v[162:165], v[126:129]
	v_mfma_f32_16x16x32_bf16 v[122:125], v[138:141], v[162:165], v[122:125]
	v_mfma_f32_16x16x32_bf16 v[110:113], v[130:133], v[170:173], v[110:113]
	v_mfma_f32_16x16x32_bf16 v[106:109], v[138:141], v[170:173], v[106:109]
	v_mfma_f32_16x16x32_bf16 v[94:97], v[130:133], v[194:197], v[94:97]
	v_mfma_f32_16x16x32_bf16 v[90:93], v[138:141], v[194:197], v[90:93]
	v_mfma_f32_16x16x32_bf16 v[78:81], v[130:133], v[212:215], v[78:81]
	v_mfma_f32_16x16x32_bf16 v[74:77], v[138:141], v[212:215], v[74:77]
	v_mfma_f32_16x16x32_bf16 v[126:129], v[134:137], v[166:169], v[126:129]
	v_mfma_f32_16x16x32_bf16 v[122:125], v[142:145], v[166:169], v[122:125]
	v_mfma_f32_16x16x32_bf16 v[110:113], v[134:137], v[174:177], v[110:113]
	v_mfma_f32_16x16x32_bf16 v[106:109], v[142:145], v[174:177], v[106:109]
	v_mfma_f32_16x16x32_bf16 v[94:97], v[134:137], v[208:211], v[94:97]
	v_mfma_f32_16x16x32_bf16 v[90:93], v[142:145], v[208:211], v[90:93]
	v_mfma_f32_16x16x32_bf16 v[78:81], v[134:137], v[216:219], v[78:81]
	v_mfma_f32_16x16x32_bf16 v[74:77], v[142:145], v[216:219], v[74:77]
	v_mfma_f32_16x16x32_bf16 v[118:121], v[146:149], v[162:165], v[118:121]
	v_mfma_f32_16x16x32_bf16 v[114:117], v[154:157], v[162:165], v[114:117]
	v_mfma_f32_16x16x32_bf16 v[102:105], v[146:149], v[170:173], v[102:105]
	v_mfma_f32_16x16x32_bf16 v[98:101], v[154:157], v[170:173], v[98:101]
	v_mfma_f32_16x16x32_bf16 v[86:89], v[146:149], v[194:197], v[86:89]
	v_mfma_f32_16x16x32_bf16 v[82:85], v[154:157], v[194:197], v[82:85]
	v_mfma_f32_16x16x32_bf16 v[70:73], v[146:149], v[212:215], v[70:73]
	v_mfma_f32_16x16x32_bf16 v[66:69], v[154:157], v[212:215], v[66:69]
	v_mfma_f32_16x16x32_bf16 v[118:121], v[150:153], v[166:169], v[118:121]
	v_mfma_f32_16x16x32_bf16 v[114:117], v[158:161], v[166:169], v[114:117]
	v_mfma_f32_16x16x32_bf16 v[102:105], v[150:153], v[174:177], v[102:105]
	v_mfma_f32_16x16x32_bf16 v[98:101], v[158:161], v[174:177], v[98:101]
	v_mfma_f32_16x16x32_bf16 v[86:89], v[150:153], v[208:211], v[86:89]
	v_mfma_f32_16x16x32_bf16 v[82:85], v[158:161], v[208:211], v[82:85]
	v_mfma_f32_16x16x32_bf16 v[70:73], v[150:153], v[216:219], v[70:73]
	v_mfma_f32_16x16x32_bf16 v[66:69], v[158:161], v[216:219], v[66:69]
	s_waitcnt vmcnt(8)
	s_barrier
	s_setprio 0
	s_add_i32 s75, s66, s33
	v_lshl_add_u64 v[198:199], s[54:55], 0, v[180:181]
	s_mov_b32 m0, s75
	ds_read_b128 v[162:165], v205 offset:16384
	ds_read_b128 v[166:169], v205 offset:17408
	ds_read_b128 v[170:173], v205 offset:18432
	ds_read_b128 v[174:177], v205 offset:19456
	ds_read_b128 v[194:197], v205 offset:20480
	ds_read_b128 v[208:211], v205 offset:21504
	ds_read_b128 v[212:215], v205 offset:22528
	ds_read_b128 v[216:219], v205 offset:23552
	global_load_lds_dwordx4 v[198:199], off
	s_add_i32 m0, s75, 0x2000
	s_add_u32 s76, s54, 0x100000
	v_lshl_add_u64 v[220:221], s[54:55], 0, v[184:185]
	s_addc_u32 s77, s55, 0
	s_add_i32 s75, s67, s33
	global_load_lds_dwordx4 v[220:221], off
	s_mov_b32 m0, s75
	v_lshl_add_u64 v[224:225], s[56:57], 0, v[182:183]
	global_load_lds_dwordx4 v180, s[76:77]
	s_add_i32 m0, s75, 0x2000
	s_nop 0
	global_load_lds_dwordx4 v184, s[76:77]
	v_lshl_add_u64 v[222:223], s[56:57], 0, v[178:179]
	s_mov_b32 m0, s51
	s_nop 0
	global_load_lds_dwordx4 v[222:223], off
	s_mov_b32 m0, s58
	s_nop 0
	global_load_lds_dwordx4 v[224:225], off
	s_and_b64 vcc, exec, s[26:27]
	s_cbranch_vccnz .Lkw1639_1
	s_waitcnt vmcnt(8)
; #define PG8_STAGE(bufoff, gbase, voff) do { _Pragma("unroll") for (int _i = 0; _i < 2; ++_i) \
;         __builtin_amdgcn_global_load_lds((const unsigned*)((const char*)(gbase) + (voff)[_i]), (LAS unsigned*)(lds + (bufoff) + ldsw + _i * 8192), 16, 0, 0); } while (0)
; #define PG8_LDA(dst, b, h) do { _Pragma("unroll") for (int m = 0; m < 4; ++m) _Pragma("unroll") for (int k = 0; k < 2; ++k) dst[m][k] = *(const LAS bf16x8*)(lds + PG8_SA(b, h) + aoff + m * 2048 + k * 1024); } while (0)
; #define PG8_LDB(dst, b, h) do { _Pragma("unroll") for (int n = 0; n < 2; ++n) _Pragma("unroll") for (int k = 0; k < 2; ++k) dst[n][k] = *(const LAS bf16x8*)(lds + PG8_SB(b, h) + boff + n * 2048 + k * 1024); } while (0)
; #define PG8_MMA(ai, bj, At, Bt) do { __builtin_amdgcn_s_setprio(1); _Pragma("unroll") for (int m = 0; m < 4; ++m) _Pragma("unroll") for (int n = 0; n < 2; ++n) _Pragma("unroll") for (int k = 0; k < 2; ++k) \
;         acc[ai][bj][m][n] = __builtin_amdgcn_mfma_f32_16x16x32_bf16(Bt[n][k], At[m][k], acc[ai][bj][m][n], 0, 0, 0); __builtin_amdgcn_s_setprio(0); } while (0)
; #define PG8_WAIT_V(n) asm volatile("s_waitcnt vmcnt(" #n ")" ::: "memory")
; #define PG8_WAIT_L(n) asm volatile("s_waitcnt lgkmcnt(" #n ")" ::: "memory")
; #define PG8_BAR __builtin_amdgcn_s_barrier()
; #define PG8_SCHED __builtin_amdgcn_sched_barrier(0)
; template <class Epi, class Sched, bool ALIGN_EPI = true, bool SP2 = true>
; __device__ __forceinline__ void gemm_phase(LAS unsigned char* lds, const Gemm g, const Sched& S, const Epi& E) {
;     ...
;             PG8_WAIT_V(8); PG8_WAIT_L(0); PG8_BAR; PG8_MMA(1, 0, At, B0); PG8_MMA(1, 1, At, B1); PG8_BAR; PG8_SCHED;
;             PG8_LDB(B0, 1, 0); PG8_LDB(B1, 1, 1); PG8_SCHED; PG8_LDA(At, 1, 0); PG8_STAGE(PG8_SA(0, 1), a2 + hstep, voffA);
.Lkw1639_1:
	s_waitcnt lgkmcnt(0)
	s_setprio 1
	s_barrier
	v_mfma_f32_16x16x32_bf16 v[62:65], v[130:133], v[162:165], v[62:65]
	v_mfma_f32_16x16x32_bf16 v[58:61], v[138:141], v[162:165], v[58:61]
	v_mfma_f32_16x16x32_bf16 v[46:49], v[130:133], v[170:173], v[46:49]
	v_mfma_f32_16x16x32_bf16 v[42:45], v[138:141], v[170:173], v[42:45]
	v_mfma_f32_16x16x32_bf16 v[30:33], v[130:133], v[194:197], v[30:33]
	v_mfma_f32_16x16x32_bf16 v[26:29], v[138:141], v[194:197], v[26:29]
	v_mfma_f32_16x16x32_bf16 v[14:17], v[130:133], v[212:215], v[14:17]
	v_mfma_f32_16x16x32_bf16 v[10:13], v[138:141], v[212:215], v[10:13]
	v_mfma_f32_16x16x32_bf16 v[62:65], v[134:137], v[166:169], v[62:65]
	v_mfma_f32_16x16x32_bf16 v[58:61], v[142:145], v[166:169], v[58:61]
	v_mfma_f32_16x16x32_bf16 v[46:49], v[134:137], v[174:177], v[46:49]
	v_mfma_f32_16x16x32_bf16 v[42:45], v[142:145], v[174:177], v[42:45]
	v_mfma_f32_16x16x32_bf16 v[30:33], v[134:137], v[208:211], v[30:33]
	v_mfma_f32_16x16x32_bf16 v[26:29], v[142:145], v[208:211], v[26:29]
	v_mfma_f32_16x16x32_bf16 v[14:17], v[134:137], v[216:219], v[14:17]
	v_mfma_f32_16x16x32_bf16 v[10:13], v[142:145], v[216:219], v[10:13]
	v_mfma_f32_16x16x32_bf16 v[54:57], v[146:149], v[162:165], v[54:57]
	v_mfma_f32_16x16x32_bf16 v[50:53], v[154:157], v[162:165], v[50:53]
	v_mfma_f32_16x16x32_bf16 v[38:41], v[146:149], v[170:173], v[38:41]
	v_mfma_f32_16x16x32_bf16 v[34:37], v[154:157], v[170:173], v[34:37]
	v_mfma_f32_16x16x32_bf16 v[22:25], v[146:149], v[194:197], v[22:25]
	v_mfma_f32_16x16x32_bf16 v[18:21], v[154:157], v[194:197], v[18:21]
	v_mfma_f32_16x16x32_bf16 v[6:9], v[146:149], v[212:215], v[6:9]
	v_mfma_f32_16x16x32_bf16 v[2:5], v[154:157], v[212:215], v[2:5]
	v_mfma_f32_16x16x32_bf16 v[54:57], v[150:153], v[166:169], v[54:57]
	v_mfma_f32_16x16x32_bf16 v[50:53], v[158:161], v[166:169], v[50:53]
	v_mfma_f32_16x16x32_bf16 v[38:41], v[150:153], v[174:177], v[38:41]
	v_mfma_f32_16x16x32_bf16 v[34:37], v[158:161], v[174:177], v[34:37]
	v_mfma_f32_16x16x32_bf16 v[22:25], v[150:153], v[208:211], v[22:25]
	v_mfma_f32_16x16x32_bf16 v[18:21], v[158:161], v[208:211], v[18:21]
	v_mfma_f32_16x16x32_bf16 v[6:9], v[150:153], v[216:219], v[6:9]
	v_mfma_f32_16x16x32_bf16 v[2:5], v[158:161], v[216:219], v[2:5]
	s_waitcnt vmcnt(8)
	s_barrier
	s_setprio 0
	s_add_i32 s75, 0, 0x18000
	s_add_i32 s76, 0, 0x1c000
	v_add_u32_e32 v142, s75, v201
	v_add_u32_e32 v158, s76, v201
	ds_read_b128 v[130:133], v142
	ds_read_b128 v[134:137], v142 offset:1024
	ds_read_b128 v[138:141], v142 offset:2048
	ds_read_b128 v[142:145], v142 offset:3072
	ds_read_b128 v[146:149], v158
	ds_read_b128 v[150:153], v158 offset:1024
	ds_read_b128 v[154:157], v158 offset:2048
	ds_read_b128 v[158:161], v158 offset:3072
	s_add_u32 s56, s56, 0x100000
	s_addc_u32 s57, s57, 0
	s_mov_b32 m0, s59
	ds_read_b128 v[162:165], v205 offset:32768
	ds_read_b128 v[166:169], v205 offset:33792
	ds_read_b128 v[170:173], v205 offset:34816
	ds_read_b128 v[174:177], v205 offset:35840
	ds_read_b128 v[194:197], v205 offset:36864
	ds_read_b128 v[208:211], v205 offset:37888
	ds_read_b128 v[212:215], v205 offset:38912
	ds_read_b128 v[216:219], v205 offset:39936
	global_load_lds_dwordx4 v178, s[56:57]
	s_mov_b32 m0, s60
	s_nop 0
	global_load_lds_dwordx4 v182, s[56:57]
	s_and_b64 vcc, exec, s[26:27]
	s_cbranch_vccnz .Lkw1639_2
	s_waitcnt vmcnt(8)
; #define PG8_STAGE(bufoff, gbase, voff) do { _Pragma("unroll") for (int _i = 0; _i < 2; ++_i) \
;         __builtin_amdgcn_global_load_lds((const unsigned*)((const char*)(gbase) + (voff)[_i]), (LAS unsigned*)(lds + (bufoff) + ldsw + _i * 8192), 16, 0, 0); } while (0)
; #define PG8_LDA(dst, b, h) do { _Pragma("unroll") for (int m = 0; m < 4; ++m) _Pragma("unroll") for (int k = 0; k < 2; ++k) dst[m][k] = *(const LAS bf16x8*)(lds + PG8_SA(b, h) + aoff + m * 2048 + k * 1024); } while (0)
; #define PG8_MMA(ai, bj, At, Bt) do { __builtin_amdgcn_s_setprio(1); _Pragma("unroll") for (int m = 0; m < 4; ++m) _Pragma("unroll") for (int n = 0; n < 2; ++n) _Pragma("unroll") for (int k = 0; k < 2; ++k) \
;         acc[ai][bj][m][n] = __builtin_amdgcn_mfma_f32_16x16x32_bf16(Bt[n][k], At[m][k], acc[ai][bj][m][n], 0, 0, 0); __builtin_amdgcn_s_setprio(0); } while (0)
; #define PG8_WAIT_V(n) asm volatile("s_waitcnt vmcnt(" #n ")" ::: "memory")
; #define PG8_WAIT_L(n) asm volatile("s_waitcnt lgkmcnt(" #n ")" ::: "memory")
; #define PG8_BAR __builtin_amdgcn_s_barrier()
; #define PG8_SCHED __builtin_amdgcn_sched_barrier(0)
; template <class Epi, class Sched, bool ALIGN_EPI = true, bool SP2 = true>
; __device__ __forceinline__ void gemm_phase(LAS unsigned char* lds, const Gemm g, const Sched& S, const Epi& E) {
;     ...
;         for (int t = 0; t < nt; t += 2) {
;     ...
;             PG8_WAIT_V(8); PG8_WAIT_L(0); PG8_BAR; PG8_MMA(0, 0, At, B0); PG8_MMA(0, 1, At, B1); PG8_BAR; PG8_SCHED;
;             PG8_LDA(At, 1, 1); PG8_STAGE(PG8_SB(1, 0), b3, voffB); PG8_STAGE(PG8_SB(1, 1), b3 + hstep, voffB); PG8_STAGE(PG8_SA(1, 0), a3, voffA);
;             PG8_WAIT_V(8); PG8_WAIT_L(0); PG8_BAR; PG8_MMA(1, 0, At, B0); PG8_MMA(1, 1, At, B1); PG8_BAR; PG8_SCHED;
.Lkw1639_2:
	s_waitcnt lgkmcnt(0)
	s_setprio 1
	s_barrier
	v_mfma_f32_16x16x32_bf16 v[126:129], v[130:133], v[162:165], v[126:129]
	v_mfma_f32_16x16x32_bf16 v[122:125], v[138:141], v[162:165], v[122:125]
	v_mfma_f32_16x16x32_bf16 v[110:113], v[130:133], v[170:173], v[110:113]
	v_mfma_f32_16x16x32_bf16 v[106:109], v[138:141], v[170:173], v[106:109]
	v_mfma_f32_16x16x32_bf16 v[94:97], v[130:133], v[194:197], v[94:97]
	v_mfma_f32_16x16x32_bf16 v[90:93], v[138:141], v[194:197], v[90:93]
	v_mfma_f32_16x16x32_bf16 v[78:81], v[130:133], v[212:215], v[78:81]
	v_mfma_f32_16x16x32_bf16 v[74:77], v[138:141], v[212:215], v[74:77]
	v_mfma_f32_16x16x32_bf16 v[126:129], v[134:137], v[166:169], v[126:129]
	v_mfma_f32_16x16x32_bf16 v[122:125], v[142:145], v[166:169], v[122:125]
	v_mfma_f32_16x16x32_bf16 v[110:113], v[134:137], v[174:177], v[110:113]
	v_mfma_f32_16x16x32_bf16 v[106:109], v[142:145], v[174:177], v[106:109]
	v_mfma_f32_16x16x32_bf16 v[94:97], v[134:137], v[208:211], v[94:97]
	v_mfma_f32_16x16x32_bf16 v[90:93], v[142:145], v[208:211], v[90:93]
	v_mfma_f32_16x16x32_bf16 v[78:81], v[134:137], v[216:219], v[78:81]
	v_mfma_f32_16x16x32_bf16 v[74:77], v[142:145], v[216:219], v[74:77]
	v_mfma_f32_16x16x32_bf16 v[118:121], v[146:149], v[162:165], v[118:121]
	v_mfma_f32_16x16x32_bf16 v[114:117], v[154:157], v[162:165], v[114:117]
	v_mfma_f32_16x16x32_bf16 v[102:105], v[146:149], v[170:173], v[102:105]
	v_mfma_f32_16x16x32_bf16 v[98:101], v[154:157], v[170:173], v[98:101]
	v_mfma_f32_16x16x32_bf16 v[86:89], v[146:149], v[194:197], v[86:89]
	v_mfma_f32_16x16x32_bf16 v[82:85], v[154:157], v[194:197], v[82:85]
	v_mfma_f32_16x16x32_bf16 v[70:73], v[146:149], v[212:215], v[70:73]
	v_mfma_f32_16x16x32_bf16 v[66:69], v[154:157], v[212:215], v[66:69]
	v_mfma_f32_16x16x32_bf16 v[118:121], v[150:153], v[166:169], v[118:121]
	v_mfma_f32_16x16x32_bf16 v[114:117], v[158:161], v[166:169], v[114:117]
	v_mfma_f32_16x16x32_bf16 v[102:105], v[150:153], v[174:177], v[102:105]
	v_mfma_f32_16x16x32_bf16 v[98:101], v[158:161], v[174:177], v[98:101]
	v_mfma_f32_16x16x32_bf16 v[86:89], v[150:153], v[208:211], v[86:89]
	v_mfma_f32_16x16x32_bf16 v[82:85], v[158:161], v[208:211], v[82:85]
	v_mfma_f32_16x16x32_bf16 v[70:73], v[150:153], v[216:219], v[70:73]
	v_mfma_f32_16x16x32_bf16 v[66:69], v[158:161], v[216:219], v[66:69]
	s_waitcnt vmcnt(8)
	s_barrier
	s_setprio 0
	s_add_i32 s56, s75, s33
	v_lshl_add_u64 v[198:199], v[198:199], 0, s[22:23]
	s_mov_b32 m0, s56
	ds_read_b128 v[162:165], v205 offset:49152
	ds_read_b128 v[166:169], v205 offset:50176
	ds_read_b128 v[170:173], v205 offset:51200
	ds_read_b128 v[174:177], v205 offset:52224
	ds_read_b128 v[194:197], v205 offset:53248
	ds_read_b128 v[208:211], v205 offset:54272
	ds_read_b128 v[212:215], v205 offset:55296
	ds_read_b128 v[216:219], v205 offset:56320
	global_load_lds_dwordx4 v[198:199], off
	s_add_i32 m0, s56, 0x2000
	s_add_u32 s54, s54, 0x100080
	v_lshl_add_u64 v[198:199], v[220:221], 0, s[22:23]
	s_addc_u32 s55, s55, 0
	s_add_i32 s56, s76, s33
	global_load_lds_dwordx4 v[198:199], off
	s_mov_b32 m0, s56
	s_nop 0
	global_load_lds_dwordx4 v180, s[54:55]
	s_add_i32 m0, s56, 0x2000
	s_nop 0
	global_load_lds_dwordx4 v184, s[54:55]
	v_lshl_add_u64 v[198:199], v[222:223], 0, s[22:23]
	s_mov_b32 m0, s62
	s_nop 0
	global_load_lds_dwordx4 v[198:199], off
	v_lshl_add_u64 v[198:199], v[224:225], 0, s[22:23]
	s_mov_b32 m0, s63
	s_nop 0
	global_load_lds_dwordx4 v[198:199], off
	s_and_b64 vcc, exec, s[26:27]
	s_cbranch_vccnz .Lkw1639_3
	s_waitcnt vmcnt(8)
.Lkw1639_3:
	s_waitcnt lgkmcnt(0)
	s_setprio 1
	s_barrier
	v_mfma_f32_16x16x32_bf16 v[62:65], v[130:133], v[162:165], v[62:65]
	v_mfma_f32_16x16x32_bf16 v[58:61], v[138:141], v[162:165], v[58:61]
	v_mfma_f32_16x16x32_bf16 v[46:49], v[130:133], v[170:173], v[46:49]
	v_mfma_f32_16x16x32_bf16 v[42:45], v[138:141], v[170:173], v[42:45]
	v_mfma_f32_16x16x32_bf16 v[30:33], v[130:133], v[194:197], v[30:33]
	v_mfma_f32_16x16x32_bf16 v[26:29], v[138:141], v[194:197], v[26:29]
	v_mfma_f32_16x16x32_bf16 v[14:17], v[130:133], v[212:215], v[14:17]
	v_mfma_f32_16x16x32_bf16 v[10:13], v[138:141], v[212:215], v[10:13]
	v_mfma_f32_16x16x32_bf16 v[62:65], v[134:137], v[166:169], v[62:65]
	v_mfma_f32_16x16x32_bf16 v[58:61], v[142:145], v[166:169], v[58:61]
	v_mfma_f32_16x16x32_bf16 v[46:49], v[134:137], v[174:177], v[46:49]
	v_mfma_f32_16x16x32_bf16 v[42:45], v[142:145], v[174:177], v[42:45]
	v_mfma_f32_16x16x32_bf16 v[30:33], v[134:137], v[208:211], v[30:33]
	v_mfma_f32_16x16x32_bf16 v[26:29], v[142:145], v[208:211], v[26:29]
	v_mfma_f32_16x16x32_bf16 v[14:17], v[134:137], v[216:219], v[14:17]
	v_mfma_f32_16x16x32_bf16 v[10:13], v[142:145], v[216:219], v[10:13]
	v_mfma_f32_16x16x32_bf16 v[54:57], v[146:149], v[162:165], v[54:57]
	v_mfma_f32_16x16x32_bf16 v[50:53], v[154:157], v[162:165], v[50:53]
	v_mfma_f32_16x16x32_bf16 v[38:41], v[146:149], v[170:173], v[38:41]
	v_mfma_f32_16x16x32_bf16 v[34:37], v[154:157], v[170:173], v[34:37]
	v_mfma_f32_16x16x32_bf16 v[22:25], v[146:149], v[194:197], v[22:25]
	v_mfma_f32_16x16x32_bf16 v[18:21], v[154:157], v[194:197], v[18:21]
	v_mfma_f32_16x16x32_bf16 v[6:9], v[146:149], v[212:215], v[6:9]
	v_mfma_f32_16x16x32_bf16 v[2:5], v[154:157], v[212:215], v[2:5]
	v_mfma_f32_16x16x32_bf16 v[54:57], v[150:153], v[166:169], v[54:57]
	v_mfma_f32_16x16x32_bf16 v[50:53], v[158:161], v[166:169], v[50:53]
	v_mfma_f32_16x16x32_bf16 v[38:41], v[150:153], v[174:177], v[38:41]
	v_mfma_f32_16x16x32_bf16 v[34:37], v[158:161], v[174:177], v[34:37]
	v_mfma_f32_16x16x32_bf16 v[22:25], v[150:153], v[208:211], v[22:25]
	v_mfma_f32_16x16x32_bf16 v[18:21], v[158:161], v[208:211], v[18:21]
	v_mfma_f32_16x16x32_bf16 v[6:9], v[150:153], v[216:219], v[6:9]
	v_mfma_f32_16x16x32_bf16 v[2:5], v[158:161], v[216:219], v[2:5]
	s_waitcnt vmcnt(8)
	s_barrier
	s_setprio 0
	s_add_i32 s74, s74, 2
	s_add_u32 s52, s52, 0x100
	s_addc_u32 s53, s53, 0
	s_add_u32 s72, s72, 0x100
	s_addc_u32 s73, s73, 0
	s_cmp_gt_u32 s74, 61
	s_cbranch_scc0 .LBB0_1639
	s_and_b64 vcc, exec, s[26:27]
	s_cbranch_vccz .LBB0_1642
	s_barrier

; #define PG8_STAGE(bufoff, gbase, voff) do { _Pragma("unroll") for (int _i = 0; _i < 2; ++_i) \
;         __builtin_amdgcn_global_load_lds((const unsigned*)((const char*)(gbase) + (voff)[_i]), (LAS unsigned*)(lds + (bufoff) + ldsw + _i * 8192), 16, 0, 0); } while (0)
; #define PG8_LDA(dst, b, h) do { _Pragma("unroll") for (int m = 0; m < 4; ++m) _Pragma("unroll") for (int k = 0; k < 2; ++k) dst[m][k] = *(const LAS bf16x8*)(lds + PG8_SA(b, h) + aoff + m * 2048 + k * 1024); } while (0)
; #define PG8_LDB(dst, b, h) do { _Pragma("unroll") for (int n = 0; n < 2; ++n) _Pragma("unroll") for (int k = 0; k < 2; ++k) dst[n][k] = *(const LAS bf16x8*)(lds + PG8_SB(b, h) + boff + n * 2048 + k * 1024); } while (0)
; #define PG8_MMA(ai, bj, At, Bt) do { __builtin_amdgcn_s_setprio(1); _Pragma("unroll") for (int m = 0; m < 4; ++m) _Pragma("unroll") for (int n = 0; n < 2; ++n) _Pragma("unroll") for (int k = 0; k < 2; ++k) \
;         acc[ai][bj][m][n] = __builtin_amdgcn_mfma_f32_16x16x32_bf16(Bt[n][k], At[m][k], acc[ai][bj][m][n], 0, 0, 0); __builtin_amdgcn_s_setprio(0); } while (0)
; #define PG8_WAIT_V(n) asm volatile("s_waitcnt vmcnt(" #n ")" ::: "memory")
; #define PG8_WAIT_L(n) asm volatile("s_waitcnt lgkmcnt(" #n ")" ::: "memory")
; #define PG8_BAR __builtin_amdgcn_s_barrier()
; #define PG8_SCHED __builtin_amdgcn_sched_barrier(0)
; template <class Epi, class Sched, bool ALIGN_EPI = true, bool SP2 = true>
; __device__ __forceinline__ void gemm_phase(LAS unsigned char* lds, const Gemm g, const Sched& S, const Epi& E) {
;     ...
;             const char* a1 = cA + (size_t)(t + 1) * kstep;
;             const char* a2 = last ? nA : cA + (size_t)(t + 2) * kstep; const char* b2 = last ? nB : cB + (size_t)(t + 2) * kstep;
;             const char* a3 = a2 + kstep; const char* b3 = b2 + kstep;
;             if (last && has_next) S.a_ready(nxt);
;             if constexpr (SP2) {
;             PG8_LDB(B0, 0, 0); PG8_LDB(B1, 0, 1); PG8_SCHED; PG8_LDA(At, 0, 0); PG8_STAGE(PG8_SA(1, 1), a1 + hstep, voffA);
;             PG8_WAIT_V(8); PG8_WAIT_L(0); PG8_BAR; PG8_MMA(0, 0, At, B0); PG8_MMA(0, 1, At, B1); PG8_BAR; PG8_SCHED;
;             PG8_LDA(At, 0, 1); PG8_STAGE(PG8_SB(0, 0), b2, voffB); PG8_STAGE(PG8_SB(0, 1), b2 + hstep, voffB); PG8_STAGE(PG8_SA(0, 0), a2, voffA);
;             PG8_WAIT_V(8); PG8_WAIT_L(0); PG8_BAR; PG8_MMA(1, 0, At, B0); PG8_MMA(1, 1, At, B1); PG8_BAR; PG8_SCHED;
.LBB0_1810:
	ds_read_b128 v[148:151], v168
	ds_read_b128 v[152:155], v168 offset:1024
	ds_read_b128 v[156:159], v168 offset:2048
	ds_read_b128 v[160:163], v168 offset:3072
	ds_read_b128 v[174:177], v169
	ds_read_b128 v[178:181], v169 offset:1024
	ds_read_b128 v[182:185], v169 offset:2048
	ds_read_b128 v[186:189], v169 offset:3072
	s_add_u32 s30, s4, 0xfff00080
	s_addc_u32 s31, s5, -1
	s_cmp_eq_u32 s56, 60
	s_cselect_b32 s35, s25, s31
	s_cselect_b32 s34, s52, s30
	s_cselect_b32 s31, s23, s55
	s_cselect_b32 s30, s53, s54
	s_add_i32 m0, s40, 0xc000
	ds_read_b128 v[190:193], v170
	ds_read_b128 v[194:197], v170 offset:1024
	ds_read_b128 v[198:201], v170 offset:2048
	ds_read_b128 v[202:205], v170 offset:3072
	ds_read_b128 v[206:209], v170 offset:4096
	ds_read_b128 v[210:213], v170 offset:5120
	ds_read_b128 v[214:217], v170 offset:6144
	ds_read_b128 v[218:221], v170 offset:7168
	global_load_lds_dwordx4 v140, s[4:5]
	s_add_i32 m0, s40, 0xe000
	s_nop 0
	global_load_lds_dwordx4 v142, s[4:5]
	s_and_b64 vcc, exec, s[20:21]
	s_cbranch_vccnz .Lkw1810_0
	s_waitcnt vmcnt(8)
.Lkw1810_0:
	s_waitcnt lgkmcnt(0)
	s_setprio 1
	s_barrier
	v_mfma_f32_16x16x32_bf16 v[126:129], v[148:151], v[190:193], v[126:129]
	v_mfma_f32_16x16x32_bf16 v[122:125], v[156:159], v[190:193], v[122:125]
	v_mfma_f32_16x16x32_bf16 v[106:109], v[156:159], v[198:201], v[106:109]
	v_mfma_f32_16x16x32_bf16 v[110:113], v[148:151], v[198:201], v[110:113]
	v_mfma_f32_16x16x32_bf16 v[94:97], v[148:151], v[206:209], v[94:97]
	v_mfma_f32_16x16x32_bf16 v[90:93], v[156:159], v[206:209], v[90:93]
	v_mfma_f32_16x16x32_bf16 v[74:77], v[156:159], v[214:217], v[74:77]
	v_mfma_f32_16x16x32_bf16 v[78:81], v[148:151], v[214:217], v[78:81]
	v_mfma_f32_16x16x32_bf16 v[126:129], v[152:155], v[194:197], v[126:129]
	v_mfma_f32_16x16x32_bf16 v[122:125], v[160:163], v[194:197], v[122:125]
	v_mfma_f32_16x16x32_bf16 v[106:109], v[160:163], v[202:205], v[106:109]
	v_mfma_f32_16x16x32_bf16 v[110:113], v[152:155], v[202:205], v[110:113]
	v_mfma_f32_16x16x32_bf16 v[94:97], v[152:155], v[210:213], v[94:97]
	v_mfma_f32_16x16x32_bf16 v[90:93], v[160:163], v[210:213], v[90:93]
	v_mfma_f32_16x16x32_bf16 v[74:77], v[160:163], v[218:221], v[74:77]
	v_mfma_f32_16x16x32_bf16 v[78:81], v[152:155], v[218:221], v[78:81]
	v_mfma_f32_16x16x32_bf16 v[118:121], v[174:177], v[190:193], v[118:121]
	v_mfma_f32_16x16x32_bf16 v[114:117], v[182:185], v[190:193], v[114:117]
	v_mfma_f32_16x16x32_bf16 v[98:101], v[182:185], v[198:201], v[98:101]
	v_mfma_f32_16x16x32_bf16 v[102:105], v[174:177], v[198:201], v[102:105]
	v_mfma_f32_16x16x32_bf16 v[86:89], v[174:177], v[206:209], v[86:89]
	v_mfma_f32_16x16x32_bf16 v[82:85], v[182:185], v[206:209], v[82:85]
	v_mfma_f32_16x16x32_bf16 v[66:69], v[182:185], v[214:217], v[66:69]
	v_mfma_f32_16x16x32_bf16 v[70:73], v[174:177], v[214:217], v[70:73]
	v_mfma_f32_16x16x32_bf16 v[118:121], v[178:181], v[194:197], v[118:121]
	v_mfma_f32_16x16x32_bf16 v[114:117], v[186:189], v[194:197], v[114:117]
	v_mfma_f32_16x16x32_bf16 v[98:101], v[186:189], v[202:205], v[98:101]
	v_mfma_f32_16x16x32_bf16 v[102:105], v[178:181], v[202:205], v[102:105]
	v_mfma_f32_16x16x32_bf16 v[86:89], v[178:181], v[210:213], v[86:89]
	v_mfma_f32_16x16x32_bf16 v[82:85], v[186:189], v[210:213], v[82:85]
	v_mfma_f32_16x16x32_bf16 v[66:69], v[186:189], v[218:221], v[66:69]
	v_mfma_f32_16x16x32_bf16 v[70:73], v[178:181], v[218:221], v[70:73]
	s_waitcnt vmcnt(8)
	s_barrier
	s_setprio 0
	s_add_i32 s57, s48, s37
	v_lshl_add_u64 v[164:165], s[30:31], 0, v[134:135]
	s_mov_b32 m0, s57
	ds_read_b128 v[190:193], v170 offset:16384
	ds_read_b128 v[194:197], v170 offset:17408
	ds_read_b128 v[198:201], v170 offset:18432
	ds_read_b128 v[202:205], v170 offset:19456
	ds_read_b128 v[206:209], v170 offset:20480
	ds_read_b128 v[210:213], v170 offset:21504
	ds_read_b128 v[214:217], v170 offset:22528
	ds_read_b128 v[218:221], v170 offset:23552
	global_load_lds_dwordx4 v[164:165], off
	s_add_i32 m0, s57, 0x2000
	s_add_u32 s58, s30, 0x100000
	v_lshl_add_u64 v[222:223], s[30:31], 0, v[130:131]
	s_addc_u32 s59, s31, 0
	s_add_i32 s57, s49, s37
	global_load_lds_dwordx4 v[222:223], off
	s_mov_b32 m0, s57
	v_lshl_add_u64 v[226:227], s[34:35], 0, v[132:133]
	global_load_lds_dwordx4 v134, s[58:59]
	s_add_i32 m0, s57, 0x2000
	s_nop 0
	global_load_lds_dwordx4 v130, s[58:59]
	v_lshl_add_u64 v[224:225], s[34:35], 0, v[136:137]
	s_mov_b32 m0, s40
	s_nop 0
	global_load_lds_dwordx4 v[224:225], off
	s_mov_b32 m0, s41
	s_nop 0
	global_load_lds_dwordx4 v[226:227], off
	s_and_b64 vcc, exec, s[20:21]
	s_cbranch_vccnz .Lkw1810_1
	s_waitcnt vmcnt(8)
; #define PG8_STAGE(bufoff, gbase, voff) do { _Pragma("unroll") for (int _i = 0; _i < 2; ++_i) \
;         __builtin_amdgcn_global_load_lds((const unsigned*)((const char*)(gbase) + (voff)[_i]), (LAS unsigned*)(lds + (bufoff) + ldsw + _i * 8192), 16, 0, 0); } while (0)
; #define PG8_LDA(dst, b, h) do { _Pragma("unroll") for (int m = 0; m < 4; ++m) _Pragma("unroll") for (int k = 0; k < 2; ++k) dst[m][k] = *(const LAS bf16x8*)(lds + PG8_SA(b, h) + aoff + m * 2048 + k * 1024); } while (0)
; #define PG8_LDB(dst, b, h) do { _Pragma("unroll") for (int n = 0; n < 2; ++n) _Pragma("unroll") for (int k = 0; k < 2; ++k) dst[n][k] = *(const LAS bf16x8*)(lds + PG8_SB(b, h) + boff + n * 2048 + k * 1024); } while (0)
; #define PG8_MMA(ai, bj, At, Bt) do { __builtin_amdgcn_s_setprio(1); _Pragma("unroll") for (int m = 0; m < 4; ++m) _Pragma("unroll") for (int n = 0; n < 2; ++n) _Pragma("unroll") for (int k = 0; k < 2; ++k) \
;         acc[ai][bj][m][n] = __builtin_amdgcn_mfma_f32_16x16x32_bf16(Bt[n][k], At[m][k], acc[ai][bj][m][n], 0, 0, 0); __builtin_amdgcn_s_setprio(0); } while (0)
; #define PG8_WAIT_V(n) asm volatile("s_waitcnt vmcnt(" #n ")" ::: "memory")
; #define PG8_WAIT_L(n) asm volatile("s_waitcnt lgkmcnt(" #n ")" ::: "memory")
; #define PG8_BAR __builtin_amdgcn_s_barrier()
; #define PG8_SCHED __builtin_amdgcn_sched_barrier(0)
; template <class Epi, class Sched, bool ALIGN_EPI = true, bool SP2 = true>
; __device__ __forceinline__ void gemm_phase(LAS unsigned char* lds, const Gemm g, const Sched& S, const Epi& E) {
;     ...
;             PG8_WAIT_V(8); PG8_WAIT_L(0); PG8_BAR; PG8_MMA(1, 0, At, B0); PG8_MMA(1, 1, At, B1); PG8_BAR; PG8_SCHED;
;             PG8_LDB(B0, 1, 0); PG8_LDB(B1, 1, 1); PG8_SCHED; PG8_LDA(At, 1, 0); PG8_STAGE(PG8_SA(0, 1), a2 + hstep, voffA);
.Lkw1810_1:
	s_waitcnt lgkmcnt(0)
	s_setprio 1
	s_barrier
	v_mfma_f32_16x16x32_bf16 v[62:65], v[148:151], v[190:193], v[62:65]
	v_mfma_f32_16x16x32_bf16 v[58:61], v[156:159], v[190:193], v[58:61]
	v_mfma_f32_16x16x32_bf16 v[42:45], v[156:159], v[198:201], v[42:45]
	v_mfma_f32_16x16x32_bf16 v[46:49], v[148:151], v[198:201], v[46:49]
	v_mfma_f32_16x16x32_bf16 v[30:33], v[148:151], v[206:209], v[30:33]
	v_mfma_f32_16x16x32_bf16 v[26:29], v[156:159], v[206:209], v[26:29]
	v_mfma_f32_16x16x32_bf16 v[10:13], v[156:159], v[214:217], v[10:13]
	v_mfma_f32_16x16x32_bf16 v[14:17], v[148:151], v[214:217], v[14:17]
	v_mfma_f32_16x16x32_bf16 v[62:65], v[152:155], v[194:197], v[62:65]
	v_mfma_f32_16x16x32_bf16 v[58:61], v[160:163], v[194:197], v[58:61]
	v_mfma_f32_16x16x32_bf16 v[42:45], v[160:163], v[202:205], v[42:45]
	v_mfma_f32_16x16x32_bf16 v[46:49], v[152:155], v[202:205], v[46:49]
	v_mfma_f32_16x16x32_bf16 v[30:33], v[152:155], v[210:213], v[30:33]
	v_mfma_f32_16x16x32_bf16 v[26:29], v[160:163], v[210:213], v[26:29]
	v_mfma_f32_16x16x32_bf16 v[10:13], v[160:163], v[218:221], v[10:13]
	v_mfma_f32_16x16x32_bf16 v[14:17], v[152:155], v[218:221], v[14:17]
	v_mfma_f32_16x16x32_bf16 v[54:57], v[174:177], v[190:193], v[54:57]
	v_mfma_f32_16x16x32_bf16 v[50:53], v[182:185], v[190:193], v[50:53]
	v_mfma_f32_16x16x32_bf16 v[34:37], v[182:185], v[198:201], v[34:37]
	v_mfma_f32_16x16x32_bf16 v[38:41], v[174:177], v[198:201], v[38:41]
	v_mfma_f32_16x16x32_bf16 v[22:25], v[174:177], v[206:209], v[22:25]
	v_mfma_f32_16x16x32_bf16 v[18:21], v[182:185], v[206:209], v[18:21]
	v_mfma_f32_16x16x32_bf16 v[2:5], v[182:185], v[214:217], v[2:5]
	v_mfma_f32_16x16x32_bf16 v[6:9], v[174:177], v[214:217], v[6:9]
	v_mfma_f32_16x16x32_bf16 v[54:57], v[178:181], v[194:197], v[54:57]
	v_mfma_f32_16x16x32_bf16 v[50:53], v[186:189], v[194:197], v[50:53]
	v_mfma_f32_16x16x32_bf16 v[34:37], v[186:189], v[202:205], v[34:37]
	v_mfma_f32_16x16x32_bf16 v[38:41], v[178:181], v[202:205], v[38:41]
	v_mfma_f32_16x16x32_bf16 v[22:25], v[178:181], v[210:213], v[22:25]
	v_mfma_f32_16x16x32_bf16 v[18:21], v[186:189], v[210:213], v[18:21]
	v_mfma_f32_16x16x32_bf16 v[2:5], v[186:189], v[218:221], v[2:5]
	v_mfma_f32_16x16x32_bf16 v[6:9], v[178:181], v[218:221], v[6:9]
	s_waitcnt vmcnt(8)
	s_barrier
	s_setprio 0
	s_add_i32 s57, 0, 0x18000
	s_add_i32 s58, 0, 0x1c000
	v_add_u32_e32 v160, s57, v167
	v_add_u32_e32 v173, s58, v167
	ds_read_b128 v[148:151], v160
	ds_read_b128 v[152:155], v160 offset:1024
	ds_read_b128 v[156:159], v160 offset:2048
	ds_read_b128 v[160:163], v160 offset:3072
	ds_read_b128 v[174:177], v173
	ds_read_b128 v[178:181], v173 offset:1024
	ds_read_b128 v[182:185], v173 offset:2048
	ds_read_b128 v[186:189], v173 offset:3072
	s_add_u32 s34, s34, 0x100000
	s_addc_u32 s35, s35, 0
	s_mov_b32 m0, s42
	ds_read_b128 v[190:193], v170 offset:32768
	ds_read_b128 v[194:197], v170 offset:33792
	ds_read_b128 v[198:201], v170 offset:34816
	ds_read_b128 v[202:205], v170 offset:35840
	ds_read_b128 v[206:209], v170 offset:36864
	ds_read_b128 v[210:213], v170 offset:37888
	ds_read_b128 v[214:217], v170 offset:38912
	ds_read_b128 v[218:221], v170 offset:39936
	global_load_lds_dwordx4 v136, s[34:35]
	s_mov_b32 m0, s43
	s_nop 0
	global_load_lds_dwordx4 v132, s[34:35]
	s_and_b64 vcc, exec, s[20:21]
	s_cbranch_vccnz .Lkw1810_2
	s_waitcnt vmcnt(8)
; #define PG8_STAGE(bufoff, gbase, voff) do { _Pragma("unroll") for (int _i = 0; _i < 2; ++_i) \
;         __builtin_amdgcn_global_load_lds((const unsigned*)((const char*)(gbase) + (voff)[_i]), (LAS unsigned*)(lds + (bufoff) + ldsw + _i * 8192), 16, 0, 0); } while (0)
; #define PG8_LDA(dst, b, h) do { _Pragma("unroll") for (int m = 0; m < 4; ++m) _Pragma("unroll") for (int k = 0; k < 2; ++k) dst[m][k] = *(const LAS bf16x8*)(lds + PG8_SA(b, h) + aoff + m * 2048 + k * 1024); } while (0)
; #define PG8_MMA(ai, bj, At, Bt) do { __builtin_amdgcn_s_setprio(1); _Pragma("unroll") for (int m = 0; m < 4; ++m) _Pragma("unroll") for (int n = 0; n < 2; ++n) _Pragma("unroll") for (int k = 0; k < 2; ++k) \
;         acc[ai][bj][m][n] = __builtin_amdgcn_mfma_f32_16x16x32_bf16(Bt[n][k], At[m][k], acc[ai][bj][m][n], 0, 0, 0); __builtin_amdgcn_s_setprio(0); } while (0)
; #define PG8_WAIT_V(n) asm volatile("s_waitcnt vmcnt(" #n ")" ::: "memory")
; #define PG8_WAIT_L(n) asm volatile("s_waitcnt lgkmcnt(" #n ")" ::: "memory")
; #define PG8_BAR __builtin_amdgcn_s_barrier()
; #define PG8_SCHED __builtin_amdgcn_sched_barrier(0)
; template <class Epi, class Sched, bool ALIGN_EPI = true, bool SP2 = true>
; __device__ __forceinline__ void gemm_phase(LAS unsigned char* lds, const Gemm g, const Sched& S, const Epi& E) {
;     ...
;         for (int t = 0; t < nt; t += 2) {
;     ...
;             PG8_WAIT_V(8); PG8_WAIT_L(0); PG8_BAR; PG8_MMA(0, 0, At, B0); PG8_MMA(0, 1, At, B1); PG8_BAR; PG8_SCHED;
;             PG8_LDA(At, 1, 1); PG8_STAGE(PG8_SB(1, 0), b3, voffB); PG8_STAGE(PG8_SB(1, 1), b3 + hstep, voffB); PG8_STAGE(PG8_SA(1, 0), a3, voffA);
;             PG8_WAIT_V(8); PG8_WAIT_L(0); PG8_BAR; PG8_MMA(1, 0, At, B0); PG8_MMA(1, 1, At, B1); PG8_BAR; PG8_SCHED;
.Lkw1810_2:
	s_waitcnt lgkmcnt(0)
	s_setprio 1
	s_barrier
	v_mfma_f32_16x16x32_bf16 v[126:129], v[148:151], v[190:193], v[126:129]
	v_mfma_f32_16x16x32_bf16 v[122:125], v[156:159], v[190:193], v[122:125]
	v_mfma_f32_16x16x32_bf16 v[106:109], v[156:159], v[198:201], v[106:109]
	v_mfma_f32_16x16x32_bf16 v[110:113], v[148:151], v[198:201], v[110:113]
	v_mfma_f32_16x16x32_bf16 v[94:97], v[148:151], v[206:209], v[94:97]
	v_mfma_f32_16x16x32_bf16 v[90:93], v[156:159], v[206:209], v[90:93]
	v_mfma_f32_16x16x32_bf16 v[74:77], v[156:159], v[214:217], v[74:77]
	v_mfma_f32_16x16x32_bf16 v[78:81], v[148:151], v[214:217], v[78:81]
	v_mfma_f32_16x16x32_bf16 v[126:129], v[152:155], v[194:197], v[126:129]
	v_mfma_f32_16x16x32_bf16 v[122:125], v[160:163], v[194:197], v[122:125]
	v_mfma_f32_16x16x32_bf16 v[106:109], v[160:163], v[202:205], v[106:109]
	v_mfma_f32_16x16x32_bf16 v[110:113], v[152:155], v[202:205], v[110:113]
	v_mfma_f32_16x16x32_bf16 v[94:97], v[152:155], v[210:213], v[94:97]
	v_mfma_f32_16x16x32_bf16 v[90:93], v[160:163], v[210:213], v[90:93]
	v_mfma_f32_16x16x32_bf16 v[74:77], v[160:163], v[218:221], v[74:77]
	v_mfma_f32_16x16x32_bf16 v[78:81], v[152:155], v[218:221], v[78:81]
	v_mfma_f32_16x16x32_bf16 v[118:121], v[174:177], v[190:193], v[118:121]
	v_mfma_f32_16x16x32_bf16 v[114:117], v[182:185], v[190:193], v[114:117]
	v_mfma_f32_16x16x32_bf16 v[98:101], v[182:185], v[198:201], v[98:101]
	v_mfma_f32_16x16x32_bf16 v[102:105], v[174:177], v[198:201], v[102:105]
	v_mfma_f32_16x16x32_bf16 v[86:89], v[174:177], v[206:209], v[86:89]
	v_mfma_f32_16x16x32_bf16 v[82:85], v[182:185], v[206:209], v[82:85]
	v_mfma_f32_16x16x32_bf16 v[66:69], v[182:185], v[214:217], v[66:69]
	v_mfma_f32_16x16x32_bf16 v[70:73], v[174:177], v[214:217], v[70:73]
	v_mfma_f32_16x16x32_bf16 v[118:121], v[178:181], v[194:197], v[118:121]
	v_mfma_f32_16x16x32_bf16 v[114:117], v[186:189], v[194:197], v[114:117]
	v_mfma_f32_16x16x32_bf16 v[98:101], v[186:189], v[202:205], v[98:101]
	v_mfma_f32_16x16x32_bf16 v[102:105], v[178:181], v[202:205], v[102:105]
	v_mfma_f32_16x16x32_bf16 v[86:89], v[178:181], v[210:213], v[86:89]
	v_mfma_f32_16x16x32_bf16 v[82:85], v[186:189], v[210:213], v[82:85]
	v_mfma_f32_16x16x32_bf16 v[66:69], v[186:189], v[218:221], v[66:69]
	v_mfma_f32_16x16x32_bf16 v[70:73], v[178:181], v[218:221], v[70:73]
	s_waitcnt vmcnt(8)
	s_barrier
	s_setprio 0
	s_add_i32 s34, s57, s37
	v_lshl_add_u64 v[164:165], v[164:165], 0, s[18:19]
	s_mov_b32 m0, s34
	ds_read_b128 v[190:193], v170 offset:49152
	ds_read_b128 v[194:197], v170 offset:50176
	ds_read_b128 v[198:201], v170 offset:51200
	ds_read_b128 v[202:205], v170 offset:52224
	ds_read_b128 v[206:209], v170 offset:53248
	ds_read_b128 v[210:213], v170 offset:54272
	ds_read_b128 v[214:217], v170 offset:55296
	ds_read_b128 v[218:221], v170 offset:56320
	global_load_lds_dwordx4 v[164:165], off
	s_add_i32 m0, s34, 0x2000
	s_add_u32 s30, s30, 0x100080
	v_lshl_add_u64 v[164:165], v[222:223], 0, s[18:19]
	s_addc_u32 s31, s31, 0
	s_add_i32 s34, s58, s37
	global_load_lds_dwordx4 v[164:165], off
	s_mov_b32 m0, s34
	s_nop 0
	global_load_lds_dwordx4 v134, s[30:31]
	s_add_i32 m0, s34, 0x2000
	s_nop 0
	global_load_lds_dwordx4 v130, s[30:31]
	v_lshl_add_u64 v[164:165], v[224:225], 0, s[18:19]
	s_mov_b32 m0, s45
	s_nop 0
	global_load_lds_dwordx4 v[164:165], off
	v_lshl_add_u64 v[164:165], v[226:227], 0, s[18:19]
	s_mov_b32 m0, s46
	s_nop 0
	global_load_lds_dwordx4 v[164:165], off
	s_and_b64 vcc, exec, s[20:21]
	s_cbranch_vccnz .Lkw1810_3
	s_waitcnt vmcnt(8)
.Lkw1810_3:
	s_waitcnt lgkmcnt(0)
	s_setprio 1
	s_barrier
	v_mfma_f32_16x16x32_bf16 v[62:65], v[148:151], v[190:193], v[62:65]
	v_mfma_f32_16x16x32_bf16 v[58:61], v[156:159], v[190:193], v[58:61]
	v_mfma_f32_16x16x32_bf16 v[42:45], v[156:159], v[198:201], v[42:45]
	v_mfma_f32_16x16x32_bf16 v[46:49], v[148:151], v[198:201], v[46:49]
	v_mfma_f32_16x16x32_bf16 v[30:33], v[148:151], v[206:209], v[30:33]
	v_mfma_f32_16x16x32_bf16 v[26:29], v[156:159], v[206:209], v[26:29]
	v_mfma_f32_16x16x32_bf16 v[10:13], v[156:159], v[214:217], v[10:13]
	v_mfma_f32_16x16x32_bf16 v[14:17], v[148:151], v[214:217], v[14:17]
	v_mfma_f32_16x16x32_bf16 v[62:65], v[152:155], v[194:197], v[62:65]
	v_mfma_f32_16x16x32_bf16 v[58:61], v[160:163], v[194:197], v[58:61]
	v_mfma_f32_16x16x32_bf16 v[42:45], v[160:163], v[202:205], v[42:45]
	v_mfma_f32_16x16x32_bf16 v[46:49], v[152:155], v[202:205], v[46:49]
	v_mfma_f32_16x16x32_bf16 v[30:33], v[152:155], v[210:213], v[30:33]
	v_mfma_f32_16x16x32_bf16 v[26:29], v[160:163], v[210:213], v[26:29]
	v_mfma_f32_16x16x32_bf16 v[10:13], v[160:163], v[218:221], v[10:13]
	v_mfma_f32_16x16x32_bf16 v[14:17], v[152:155], v[218:221], v[14:17]
	v_mfma_f32_16x16x32_bf16 v[54:57], v[174:177], v[190:193], v[54:57]
	v_mfma_f32_16x16x32_bf16 v[50:53], v[182:185], v[190:193], v[50:53]
	v_mfma_f32_16x16x32_bf16 v[34:37], v[182:185], v[198:201], v[34:37]
	v_mfma_f32_16x16x32_bf16 v[38:41], v[174:177], v[198:201], v[38:41]
	v_mfma_f32_16x16x32_bf16 v[22:25], v[174:177], v[206:209], v[22:25]
	v_mfma_f32_16x16x32_bf16 v[18:21], v[182:185], v[206:209], v[18:21]
	v_mfma_f32_16x16x32_bf16 v[2:5], v[182:185], v[214:217], v[2:5]
	v_mfma_f32_16x16x32_bf16 v[6:9], v[174:177], v[214:217], v[6:9]
	v_mfma_f32_16x16x32_bf16 v[54:57], v[178:181], v[194:197], v[54:57]
	v_mfma_f32_16x16x32_bf16 v[50:53], v[186:189], v[194:197], v[50:53]
	v_mfma_f32_16x16x32_bf16 v[34:37], v[186:189], v[202:205], v[34:37]
	v_mfma_f32_16x16x32_bf16 v[38:41], v[178:181], v[202:205], v[38:41]
	v_mfma_f32_16x16x32_bf16 v[22:25], v[178:181], v[210:213], v[22:25]
	v_mfma_f32_16x16x32_bf16 v[18:21], v[186:189], v[210:213], v[18:21]
	v_mfma_f32_16x16x32_bf16 v[2:5], v[186:189], v[218:221], v[2:5]
	v_mfma_f32_16x16x32_bf16 v[6:9], v[178:181], v[218:221], v[6:9]
	s_waitcnt vmcnt(8)
	s_barrier
	s_setprio 0
	s_add_i32 s56, s56, 2
	s_add_u32 s4, s4, 0x100
	s_addc_u32 s5, s5, 0
	s_add_u32 s54, s54, 0x100
	s_addc_u32 s55, s55, 0
	s_cmp_gt_u32 s56, 61
	s_cbranch_scc0 .LBB0_1810
	s_and_b64 vcc, exec, s[20:21]
	s_cbranch_vccz .LBB0_1813
	s_barrier

; #define PG8_STAGE(bufoff, gbase, voff) do { _Pragma("unroll") for (int _i = 0; _i < 2; ++_i) \
;         __builtin_amdgcn_global_load_lds((const unsigned*)((const char*)(gbase) + (voff)[_i]), (LAS unsigned*)(lds + (bufoff) + ldsw + _i * 8192), 16, 0, 0); } while (0)
; #define PG8_LDA(dst, b, h) do { _Pragma("unroll") for (int m = 0; m < 4; ++m) _Pragma("unroll") for (int k = 0; k < 2; ++k) dst[m][k] = *(const LAS bf16x8*)(lds + PG8_SA(b, h) + aoff + m * 2048 + k * 1024); } while (0)
; #define PG8_LDB(dst, b, h) do { _Pragma("unroll") for (int n = 0; n < 2; ++n) _Pragma("unroll") for (int k = 0; k < 2; ++k) dst[n][k] = *(const LAS bf16x8*)(lds + PG8_SB(b, h) + boff + n * 2048 + k * 1024); } while (0)
; #define PG8_MMA(ai, bj, At, Bt) do { __builtin_amdgcn_s_setprio(1); _Pragma("unroll") for (int m = 0; m < 4; ++m) _Pragma("unroll") for (int n = 0; n < 2; ++n) _Pragma("unroll") for (int k = 0; k < 2; ++k) \
;         acc[ai][bj][m][n] = __builtin_amdgcn_mfma_f32_16x16x32_bf16(Bt[n][k], At[m][k], acc[ai][bj][m][n], 0, 0, 0); __builtin_amdgcn_s_setprio(0); } while (0)
; template <class Epi, class Sched, bool ALIGN_EPI = true, bool SP2 = true>
; __device__ __forceinline__ void gemm_phase(LAS unsigned char* lds, const Gemm g, const Sched& S, const Epi& E) {
;     ...
;             PG8_LDB(B0, 0, 0); PG8_LDB(B1, 0, 1); PG8_SCHED; PG8_LDA(At, 0, 0); PG8_STAGE(PG8_SA(1, 1), a1 + hstep, voffA);
;             PG8_WAIT_V(8); PG8_WAIT_L(0); PG8_BAR; PG8_MMA(0, 0, At, B0); PG8_MMA(0, 1, At, B1); PG8_BAR; PG8_SCHED;
;             PG8_LDA(At, 0, 1); PG8_STAGE(PG8_SB(0, 0), b2, voffB); PG8_STAGE(PG8_SB(0, 1), b2 + hstep, voffB); PG8_STAGE(PG8_SA(0, 0), a2, voffA);
;             PG8_WAIT_V(8); PG8_WAIT_L(0); PG8_BAR; PG8_MMA(1, 0, At, B0); PG8_MMA(1, 1, At, B1); PG8_BAR; PG8_SCHED;
;             PG8_LDB(B0, 1, 0); PG8_LDB(B1, 1, 1); PG8_SCHED; PG8_LDA(At, 1, 0); PG8_STAGE(PG8_SA(0, 1), a2 + hstep, voffA);
;             PG8_WAIT_V(8); PG8_WAIT_L(0); PG8_BAR; PG8_MMA(0, 0, At, B0); PG8_MMA(0, 1, At, B1); PG8_BAR; PG8_SCHED;
;             PG8_LDA(At, 1, 1); PG8_STAGE(PG8_SB(1, 0), b3, voffB); PG8_STAGE(PG8_SB(1, 1), b3 + hstep, voffB); PG8_STAGE(PG8_SA(1, 0), a3, voffA);
;             PG8_WAIT_V(8); PG8_WAIT_L(0); PG8_BAR; PG8_MMA(1, 0, At, B0); PG8_MMA(1, 1, At, B1); PG8_BAR; PG8_SCHED;
;     ...
;         if constexpr (ALIGN_EPI) { if (wr == 0) PG8_BAR; }
.LBB0_2060:
	ds_read_b128 v[130:133], v187
	ds_read_b128 v[134:137], v187 offset:1024
	ds_read_b128 v[138:141], v187 offset:2048
	ds_read_b128 v[142:145], v187 offset:3072
	ds_read_b128 v[146:149], v188
	ds_read_b128 v[150:153], v188 offset:1024
	ds_read_b128 v[170:173], v188 offset:2048
	ds_read_b128 v[192:195], v188 offset:3072
	s_add_u32 s26, s24, 0xffd50080
	s_addc_u32 s27, s25, -1
	s_cmpk_eq_i32 s53, 0xa8
	s_cselect_b32 s29, s7, s27
	s_cselect_b32 s28, s6, s26
	s_cselect_b32 s27, s23, s52
	s_cselect_b32 s26, s22, s51
	s_add_i32 m0, s36, 0xc000
	ds_read_b128 v[196:199], v189
	ds_read_b128 v[200:203], v189 offset:1024
	ds_read_b128 v[204:207], v189 offset:2048
	ds_read_b128 v[208:211], v189 offset:3072
	ds_read_b128 v[212:215], v189 offset:4096
	ds_read_b128 v[216:219], v189 offset:5120
	ds_read_b128 v[220:223], v189 offset:6144
	ds_read_b128 v[224:227], v189 offset:7168
	global_load_lds_dwordx4 v162, s[24:25]
	s_add_i32 m0, s36, 0xe000
	s_nop 0
	global_load_lds_dwordx4 v164, s[24:25]
	s_and_b64 vcc, exec, s[20:21]
	s_cbranch_vccnz .Lkw2060_0
	s_waitcnt vmcnt(8)
.Lkw2060_0:
	s_waitcnt lgkmcnt(0)
	s_setprio 1
	s_barrier
	v_mfma_f32_16x16x32_bf16 v[126:129], v[130:133], v[196:199], v[126:129]
	v_mfma_f32_16x16x32_bf16 v[122:125], v[138:141], v[196:199], v[122:125]
	v_mfma_f32_16x16x32_bf16 v[110:113], v[130:133], v[204:207], v[110:113]
	v_mfma_f32_16x16x32_bf16 v[106:109], v[138:141], v[204:207], v[106:109]
	v_mfma_f32_16x16x32_bf16 v[94:97], v[130:133], v[212:215], v[94:97]
	v_mfma_f32_16x16x32_bf16 v[90:93], v[138:141], v[212:215], v[90:93]
	v_mfma_f32_16x16x32_bf16 v[78:81], v[130:133], v[220:223], v[78:81]
	v_mfma_f32_16x16x32_bf16 v[74:77], v[138:141], v[220:223], v[74:77]
	v_mfma_f32_16x16x32_bf16 v[126:129], v[134:137], v[200:203], v[126:129]
	v_mfma_f32_16x16x32_bf16 v[122:125], v[142:145], v[200:203], v[122:125]
	v_mfma_f32_16x16x32_bf16 v[110:113], v[134:137], v[208:211], v[110:113]
	v_mfma_f32_16x16x32_bf16 v[106:109], v[142:145], v[208:211], v[106:109]
	v_mfma_f32_16x16x32_bf16 v[94:97], v[134:137], v[216:219], v[94:97]
	v_mfma_f32_16x16x32_bf16 v[90:93], v[142:145], v[216:219], v[90:93]
	v_mfma_f32_16x16x32_bf16 v[78:81], v[134:137], v[224:227], v[78:81]
	v_mfma_f32_16x16x32_bf16 v[74:77], v[142:145], v[224:227], v[74:77]
	v_mfma_f32_16x16x32_bf16 v[118:121], v[146:149], v[196:199], v[118:121]
	v_mfma_f32_16x16x32_bf16 v[114:117], v[170:173], v[196:199], v[114:117]
	v_mfma_f32_16x16x32_bf16 v[102:105], v[146:149], v[204:207], v[102:105]
	v_mfma_f32_16x16x32_bf16 v[98:101], v[170:173], v[204:207], v[98:101]
	v_mfma_f32_16x16x32_bf16 v[86:89], v[146:149], v[212:215], v[86:89]
	v_mfma_f32_16x16x32_bf16 v[82:85], v[170:173], v[212:215], v[82:85]
	v_mfma_f32_16x16x32_bf16 v[70:73], v[146:149], v[220:223], v[70:73]
	v_mfma_f32_16x16x32_bf16 v[66:69], v[170:173], v[220:223], v[66:69]
	v_mfma_f32_16x16x32_bf16 v[118:121], v[150:153], v[200:203], v[118:121]
	v_mfma_f32_16x16x32_bf16 v[114:117], v[192:195], v[200:203], v[114:117]
	v_mfma_f32_16x16x32_bf16 v[102:105], v[150:153], v[208:211], v[102:105]
	v_mfma_f32_16x16x32_bf16 v[98:101], v[192:195], v[208:211], v[98:101]
	v_mfma_f32_16x16x32_bf16 v[86:89], v[150:153], v[216:219], v[86:89]
	v_mfma_f32_16x16x32_bf16 v[82:85], v[192:195], v[216:219], v[82:85]
	v_mfma_f32_16x16x32_bf16 v[70:73], v[150:153], v[224:227], v[70:73]
	v_mfma_f32_16x16x32_bf16 v[66:69], v[192:195], v[224:227], v[66:69]
	s_waitcnt vmcnt(8)
	s_barrier
	s_setprio 0
	s_add_i32 s54, s45, s35
	v_lshl_add_u64 v[174:175], s[26:27], 0, v[156:157]
	s_mov_b32 m0, s54
	ds_read_b128 v[196:199], v189 offset:16384
	ds_read_b128 v[200:203], v189 offset:17408
	ds_read_b128 v[204:207], v189 offset:18432
	ds_read_b128 v[208:211], v189 offset:19456
	ds_read_b128 v[212:215], v189 offset:20480
	ds_read_b128 v[216:219], v189 offset:21504
	ds_read_b128 v[220:223], v189 offset:22528
	ds_read_b128 v[224:227], v189 offset:23552
	global_load_lds_dwordx4 v[174:175], off
	s_add_i32 m0, s54, 0x2000
	s_add_u32 s54, s26, 0x2b0000
	v_lshl_add_u64 v[228:229], s[26:27], 0, v[160:161]
	s_addc_u32 s55, s27, 0
	s_add_i32 s56, s46, s35
	global_load_lds_dwordx4 v[228:229], off
	s_mov_b32 m0, s56
	v_lshl_add_u64 v[232:233], s[28:29], 0, v[158:159]
	global_load_lds_dwordx4 v156, s[54:55]
	s_add_i32 m0, s56, 0x2000
	s_nop 0
	global_load_lds_dwordx4 v160, s[54:55]
	v_lshl_add_u64 v[230:231], s[28:29], 0, v[154:155]
	s_mov_b32 m0, s36
	s_nop 0
	global_load_lds_dwordx4 v[230:231], off
	s_mov_b32 m0, s37
	s_nop 0
	global_load_lds_dwordx4 v[232:233], off
	s_and_b64 vcc, exec, s[20:21]
	s_cbranch_vccnz .Lkw2060_1
	s_waitcnt vmcnt(8)
; #define PG8_STAGE(bufoff, gbase, voff) do { _Pragma("unroll") for (int _i = 0; _i < 2; ++_i) \
;         __builtin_amdgcn_global_load_lds((const unsigned*)((const char*)(gbase) + (voff)[_i]), (LAS unsigned*)(lds + (bufoff) + ldsw + _i * 8192), 16, 0, 0); } while (0)
; #define PG8_LDA(dst, b, h) do { _Pragma("unroll") for (int m = 0; m < 4; ++m) _Pragma("unroll") for (int k = 0; k < 2; ++k) dst[m][k] = *(const LAS bf16x8*)(lds + PG8_SA(b, h) + aoff + m * 2048 + k * 1024); } while (0)
; #define PG8_LDB(dst, b, h) do { _Pragma("unroll") for (int n = 0; n < 2; ++n) _Pragma("unroll") for (int k = 0; k < 2; ++k) dst[n][k] = *(const LAS bf16x8*)(lds + PG8_SB(b, h) + boff + n * 2048 + k * 1024); } while (0)
; #define PG8_MMA(ai, bj, At, Bt) do { __builtin_amdgcn_s_setprio(1); _Pragma("unroll") for (int m = 0; m < 4; ++m) _Pragma("unroll") for (int n = 0; n < 2; ++n) _Pragma("unroll") for (int k = 0; k < 2; ++k) \
;         acc[ai][bj][m][n] = __builtin_amdgcn_mfma_f32_16x16x32_bf16(Bt[n][k], At[m][k], acc[ai][bj][m][n], 0, 0, 0); __builtin_amdgcn_s_setprio(0); } while (0)
; #define PG8_WAIT_V(n) asm volatile("s_waitcnt vmcnt(" #n ")" ::: "memory")
; #define PG8_WAIT_L(n) asm volatile("s_waitcnt lgkmcnt(" #n ")" ::: "memory")
; #define PG8_BAR __builtin_amdgcn_s_barrier()
; #define PG8_SCHED __builtin_amdgcn_sched_barrier(0)
; template <class Epi, class Sched, bool ALIGN_EPI = true, bool SP2 = true>
; __device__ __forceinline__ void gemm_phase(LAS unsigned char* lds, const Gemm g, const Sched& S, const Epi& E) {
;     ...
;             PG8_WAIT_V(8); PG8_WAIT_L(0); PG8_BAR; PG8_MMA(1, 0, At, B0); PG8_MMA(1, 1, At, B1); PG8_BAR; PG8_SCHED;
;             PG8_LDB(B0, 1, 0); PG8_LDB(B1, 1, 1); PG8_SCHED; PG8_LDA(At, 1, 0); PG8_STAGE(PG8_SA(0, 1), a2 + hstep, voffA);
;             PG8_WAIT_V(8); PG8_WAIT_L(0); PG8_BAR; PG8_MMA(0, 0, At, B0); PG8_MMA(0, 1, At, B1); PG8_BAR; PG8_SCHED;
.Lkw2060_1:
	s_waitcnt lgkmcnt(0)
	s_setprio 1
	s_barrier
	v_mfma_f32_16x16x32_bf16 v[62:65], v[130:133], v[196:199], v[62:65]
	v_mfma_f32_16x16x32_bf16 v[58:61], v[138:141], v[196:199], v[58:61]
	v_mfma_f32_16x16x32_bf16 v[46:49], v[130:133], v[204:207], v[46:49]
	v_mfma_f32_16x16x32_bf16 v[42:45], v[138:141], v[204:207], v[42:45]
	v_mfma_f32_16x16x32_bf16 v[30:33], v[130:133], v[212:215], v[30:33]
	v_mfma_f32_16x16x32_bf16 v[26:29], v[138:141], v[212:215], v[26:29]
	v_mfma_f32_16x16x32_bf16 v[14:17], v[130:133], v[220:223], v[14:17]
	v_mfma_f32_16x16x32_bf16 v[10:13], v[138:141], v[220:223], v[10:13]
	v_mfma_f32_16x16x32_bf16 v[62:65], v[134:137], v[200:203], v[62:65]
	v_mfma_f32_16x16x32_bf16 v[58:61], v[142:145], v[200:203], v[58:61]
	v_mfma_f32_16x16x32_bf16 v[46:49], v[134:137], v[208:211], v[46:49]
	v_mfma_f32_16x16x32_bf16 v[42:45], v[142:145], v[208:211], v[42:45]
	v_mfma_f32_16x16x32_bf16 v[30:33], v[134:137], v[216:219], v[30:33]
	v_mfma_f32_16x16x32_bf16 v[26:29], v[142:145], v[216:219], v[26:29]
	v_mfma_f32_16x16x32_bf16 v[14:17], v[134:137], v[224:227], v[14:17]
	v_mfma_f32_16x16x32_bf16 v[10:13], v[142:145], v[224:227], v[10:13]
	v_mfma_f32_16x16x32_bf16 v[54:57], v[146:149], v[196:199], v[54:57]
	v_mfma_f32_16x16x32_bf16 v[50:53], v[170:173], v[196:199], v[50:53]
	v_mfma_f32_16x16x32_bf16 v[38:41], v[146:149], v[204:207], v[38:41]
	v_mfma_f32_16x16x32_bf16 v[34:37], v[170:173], v[204:207], v[34:37]
	v_mfma_f32_16x16x32_bf16 v[22:25], v[146:149], v[212:215], v[22:25]
	v_mfma_f32_16x16x32_bf16 v[18:21], v[170:173], v[212:215], v[18:21]
	v_mfma_f32_16x16x32_bf16 v[6:9], v[146:149], v[220:223], v[6:9]
	v_mfma_f32_16x16x32_bf16 v[2:5], v[170:173], v[220:223], v[2:5]
	v_mfma_f32_16x16x32_bf16 v[54:57], v[150:153], v[200:203], v[54:57]
	v_mfma_f32_16x16x32_bf16 v[50:53], v[192:195], v[200:203], v[50:53]
	v_mfma_f32_16x16x32_bf16 v[38:41], v[150:153], v[208:211], v[38:41]
	v_mfma_f32_16x16x32_bf16 v[34:37], v[192:195], v[208:211], v[34:37]
	v_mfma_f32_16x16x32_bf16 v[22:25], v[150:153], v[216:219], v[22:25]
	v_mfma_f32_16x16x32_bf16 v[18:21], v[192:195], v[216:219], v[18:21]
	v_mfma_f32_16x16x32_bf16 v[6:9], v[150:153], v[224:227], v[6:9]
	v_mfma_f32_16x16x32_bf16 v[2:5], v[192:195], v[224:227], v[2:5]
	s_waitcnt vmcnt(8)
	s_barrier
	s_setprio 0
	s_add_i32 s54, 0, 0x18000
	s_add_i32 s55, 0, 0x1c000
	v_add_u32_e32 v142, s54, v185
	v_add_u32_e32 v191, s55, v185
	ds_read_b128 v[130:133], v142
	ds_read_b128 v[134:137], v142 offset:1024
	ds_read_b128 v[138:141], v142 offset:2048
	ds_read_b128 v[142:145], v142 offset:3072
	ds_read_b128 v[146:149], v191
	ds_read_b128 v[150:153], v191 offset:1024
	ds_read_b128 v[170:173], v191 offset:2048
	ds_read_b128 v[192:195], v191 offset:3072
	s_add_u32 s28, s28, 0x2b0000
	s_addc_u32 s29, s29, 0
	s_mov_b32 m0, s38
	ds_read_b128 v[196:199], v189 offset:32768
	ds_read_b128 v[200:203], v189 offset:33792
	ds_read_b128 v[204:207], v189 offset:34816
	ds_read_b128 v[208:211], v189 offset:35840
	ds_read_b128 v[212:215], v189 offset:36864
	ds_read_b128 v[216:219], v189 offset:37888
	ds_read_b128 v[220:223], v189 offset:38912
	ds_read_b128 v[224:227], v189 offset:39936
	global_load_lds_dwordx4 v154, s[28:29]
	s_mov_b32 m0, s39
	s_nop 0
	global_load_lds_dwordx4 v158, s[28:29]
	s_and_b64 vcc, exec, s[20:21]
	s_cbranch_vccnz .Lkw2060_2
	s_waitcnt vmcnt(8)
; #define PG8_STAGE(bufoff, gbase, voff) do { _Pragma("unroll") for (int _i = 0; _i < 2; ++_i) \
;         __builtin_amdgcn_global_load_lds((const unsigned*)((const char*)(gbase) + (voff)[_i]), (LAS unsigned*)(lds + (bufoff) + ldsw + _i * 8192), 16, 0, 0); } while (0)
; #define PG8_LDA(dst, b, h) do { _Pragma("unroll") for (int m = 0; m < 4; ++m) _Pragma("unroll") for (int k = 0; k < 2; ++k) dst[m][k] = *(const LAS bf16x8*)(lds + PG8_SA(b, h) + aoff + m * 2048 + k * 1024); } while (0)
; #define PG8_MMA(ai, bj, At, Bt) do { __builtin_amdgcn_s_setprio(1); _Pragma("unroll") for (int m = 0; m < 4; ++m) _Pragma("unroll") for (int n = 0; n < 2; ++n) _Pragma("unroll") for (int k = 0; k < 2; ++k) \
;         acc[ai][bj][m][n] = __builtin_amdgcn_mfma_f32_16x16x32_bf16(Bt[n][k], At[m][k], acc[ai][bj][m][n], 0, 0, 0); __builtin_amdgcn_s_setprio(0); } while (0)
; #define PG8_WAIT_V(n) asm volatile("s_waitcnt vmcnt(" #n ")" ::: "memory")
; #define PG8_WAIT_L(n) asm volatile("s_waitcnt lgkmcnt(" #n ")" ::: "memory")
; #define PG8_BAR __builtin_amdgcn_s_barrier()
; #define PG8_SCHED __builtin_amdgcn_sched_barrier(0)
; template <class Epi, class Sched, bool ALIGN_EPI = true, bool SP2 = true>
; __device__ __forceinline__ void gemm_phase(LAS unsigned char* lds, const Gemm g, const Sched& S, const Epi& E) {
;     ...
;         for (int t = 0; t < nt; t += 2) {
;     ...
;             PG8_WAIT_V(8); PG8_WAIT_L(0); PG8_BAR; PG8_MMA(0, 0, At, B0); PG8_MMA(0, 1, At, B1); PG8_BAR; PG8_SCHED;
;             PG8_LDA(At, 1, 1); PG8_STAGE(PG8_SB(1, 0), b3, voffB); PG8_STAGE(PG8_SB(1, 1), b3 + hstep, voffB); PG8_STAGE(PG8_SA(1, 0), a3, voffA);
;             PG8_WAIT_V(8); PG8_WAIT_L(0); PG8_BAR; PG8_MMA(1, 0, At, B0); PG8_MMA(1, 1, At, B1); PG8_BAR; PG8_SCHED;
;     ...
;         if constexpr (ALIGN_EPI) { if (wr == 0) PG8_BAR; }
.Lkw2060_2:
	s_waitcnt lgkmcnt(0)
	s_setprio 1
	s_barrier
	v_mfma_f32_16x16x32_bf16 v[126:129], v[130:133], v[196:199], v[126:129]
	v_mfma_f32_16x16x32_bf16 v[122:125], v[138:141], v[196:199], v[122:125]
	v_mfma_f32_16x16x32_bf16 v[110:113], v[130:133], v[204:207], v[110:113]
	v_mfma_f32_16x16x32_bf16 v[106:109], v[138:141], v[204:207], v[106:109]
	v_mfma_f32_16x16x32_bf16 v[94:97], v[130:133], v[212:215], v[94:97]
	v_mfma_f32_16x16x32_bf16 v[90:93], v[138:141], v[212:215], v[90:93]
	v_mfma_f32_16x16x32_bf16 v[78:81], v[130:133], v[220:223], v[78:81]
	v_mfma_f32_16x16x32_bf16 v[74:77], v[138:141], v[220:223], v[74:77]
	v_mfma_f32_16x16x32_bf16 v[126:129], v[134:137], v[200:203], v[126:129]
	v_mfma_f32_16x16x32_bf16 v[122:125], v[142:145], v[200:203], v[122:125]
	v_mfma_f32_16x16x32_bf16 v[110:113], v[134:137], v[208:211], v[110:113]
	v_mfma_f32_16x16x32_bf16 v[106:109], v[142:145], v[208:211], v[106:109]
	v_mfma_f32_16x16x32_bf16 v[94:97], v[134:137], v[216:219], v[94:97]
	v_mfma_f32_16x16x32_bf16 v[90:93], v[142:145], v[216:219], v[90:93]
	v_mfma_f32_16x16x32_bf16 v[78:81], v[134:137], v[224:227], v[78:81]
	v_mfma_f32_16x16x32_bf16 v[74:77], v[142:145], v[224:227], v[74:77]
	v_mfma_f32_16x16x32_bf16 v[118:121], v[146:149], v[196:199], v[118:121]
	v_mfma_f32_16x16x32_bf16 v[114:117], v[170:173], v[196:199], v[114:117]
	v_mfma_f32_16x16x32_bf16 v[102:105], v[146:149], v[204:207], v[102:105]
	v_mfma_f32_16x16x32_bf16 v[98:101], v[170:173], v[204:207], v[98:101]
	v_mfma_f32_16x16x32_bf16 v[86:89], v[146:149], v[212:215], v[86:89]
	v_mfma_f32_16x16x32_bf16 v[82:85], v[170:173], v[212:215], v[82:85]
	v_mfma_f32_16x16x32_bf16 v[70:73], v[146:149], v[220:223], v[70:73]
	v_mfma_f32_16x16x32_bf16 v[66:69], v[170:173], v[220:223], v[66:69]
	v_mfma_f32_16x16x32_bf16 v[118:121], v[150:153], v[200:203], v[118:121]
	v_mfma_f32_16x16x32_bf16 v[114:117], v[192:195], v[200:203], v[114:117]
	v_mfma_f32_16x16x32_bf16 v[102:105], v[150:153], v[208:211], v[102:105]
	v_mfma_f32_16x16x32_bf16 v[98:101], v[192:195], v[208:211], v[98:101]
	v_mfma_f32_16x16x32_bf16 v[86:89], v[150:153], v[216:219], v[86:89]
	v_mfma_f32_16x16x32_bf16 v[82:85], v[192:195], v[216:219], v[82:85]
	v_mfma_f32_16x16x32_bf16 v[70:73], v[150:153], v[224:227], v[70:73]
	v_mfma_f32_16x16x32_bf16 v[66:69], v[192:195], v[224:227], v[66:69]
	s_waitcnt vmcnt(8)
	s_barrier
	s_setprio 0
	s_add_i32 s28, s54, s35
	v_lshl_add_u64 v[174:175], v[174:175], 0, s[18:19]
	s_mov_b32 m0, s28
	ds_read_b128 v[196:199], v189 offset:49152
	ds_read_b128 v[200:203], v189 offset:50176
	ds_read_b128 v[204:207], v189 offset:51200
	ds_read_b128 v[208:211], v189 offset:52224
	ds_read_b128 v[212:215], v189 offset:53248
	ds_read_b128 v[216:219], v189 offset:54272
	ds_read_b128 v[220:223], v189 offset:55296
	ds_read_b128 v[224:227], v189 offset:56320
	global_load_lds_dwordx4 v[174:175], off
	s_add_i32 m0, s28, 0x2000
	s_add_u32 s26, s26, 0x2b0080
	v_lshl_add_u64 v[174:175], v[228:229], 0, s[18:19]
	s_addc_u32 s27, s27, 0
	s_add_i32 s28, s55, s35
	global_load_lds_dwordx4 v[174:175], off
	s_mov_b32 m0, s28
	s_nop 0
	global_load_lds_dwordx4 v156, s[26:27]
	s_add_i32 m0, s28, 0x2000
	s_nop 0
	global_load_lds_dwordx4 v160, s[26:27]
	v_lshl_add_u64 v[174:175], v[230:231], 0, s[18:19]
	s_mov_b32 m0, s41
	s_nop 0
	global_load_lds_dwordx4 v[174:175], off
	v_lshl_add_u64 v[174:175], v[232:233], 0, s[18:19]
	s_mov_b32 m0, s42
	s_nop 0
	global_load_lds_dwordx4 v[174:175], off
	s_and_b64 vcc, exec, s[20:21]
	s_cbranch_vccnz .Lkw2060_3
	s_waitcnt vmcnt(8)
.Lkw2060_3:
	s_waitcnt lgkmcnt(0)
	s_setprio 1
	s_barrier
	v_mfma_f32_16x16x32_bf16 v[62:65], v[130:133], v[196:199], v[62:65]
	v_mfma_f32_16x16x32_bf16 v[58:61], v[138:141], v[196:199], v[58:61]
	v_mfma_f32_16x16x32_bf16 v[46:49], v[130:133], v[204:207], v[46:49]
	v_mfma_f32_16x16x32_bf16 v[42:45], v[138:141], v[204:207], v[42:45]
	v_mfma_f32_16x16x32_bf16 v[30:33], v[130:133], v[212:215], v[30:33]
	v_mfma_f32_16x16x32_bf16 v[26:29], v[138:141], v[212:215], v[26:29]
	v_mfma_f32_16x16x32_bf16 v[14:17], v[130:133], v[220:223], v[14:17]
	v_mfma_f32_16x16x32_bf16 v[10:13], v[138:141], v[220:223], v[10:13]
	v_mfma_f32_16x16x32_bf16 v[62:65], v[134:137], v[200:203], v[62:65]
	v_mfma_f32_16x16x32_bf16 v[58:61], v[142:145], v[200:203], v[58:61]
	v_mfma_f32_16x16x32_bf16 v[46:49], v[134:137], v[208:211], v[46:49]
	v_mfma_f32_16x16x32_bf16 v[42:45], v[142:145], v[208:211], v[42:45]
	v_mfma_f32_16x16x32_bf16 v[30:33], v[134:137], v[216:219], v[30:33]
	v_mfma_f32_16x16x32_bf16 v[26:29], v[142:145], v[216:219], v[26:29]
	v_mfma_f32_16x16x32_bf16 v[14:17], v[134:137], v[224:227], v[14:17]
	v_mfma_f32_16x16x32_bf16 v[10:13], v[142:145], v[224:227], v[10:13]
	v_mfma_f32_16x16x32_bf16 v[54:57], v[146:149], v[196:199], v[54:57]
	v_mfma_f32_16x16x32_bf16 v[50:53], v[170:173], v[196:199], v[50:53]
	v_mfma_f32_16x16x32_bf16 v[38:41], v[146:149], v[204:207], v[38:41]
	v_mfma_f32_16x16x32_bf16 v[34:37], v[170:173], v[204:207], v[34:37]
	v_mfma_f32_16x16x32_bf16 v[22:25], v[146:149], v[212:215], v[22:25]
	v_mfma_f32_16x16x32_bf16 v[18:21], v[170:173], v[212:215], v[18:21]
	v_mfma_f32_16x16x32_bf16 v[6:9], v[146:149], v[220:223], v[6:9]
	v_mfma_f32_16x16x32_bf16 v[2:5], v[170:173], v[220:223], v[2:5]
	v_mfma_f32_16x16x32_bf16 v[54:57], v[150:153], v[200:203], v[54:57]
	v_mfma_f32_16x16x32_bf16 v[50:53], v[192:195], v[200:203], v[50:53]
	v_mfma_f32_16x16x32_bf16 v[38:41], v[150:153], v[208:211], v[38:41]
	v_mfma_f32_16x16x32_bf16 v[34:37], v[192:195], v[208:211], v[34:37]
	v_mfma_f32_16x16x32_bf16 v[22:25], v[150:153], v[216:219], v[22:25]
	v_mfma_f32_16x16x32_bf16 v[18:21], v[192:195], v[216:219], v[18:21]
	v_mfma_f32_16x16x32_bf16 v[6:9], v[150:153], v[224:227], v[6:9]
	v_mfma_f32_16x16x32_bf16 v[2:5], v[192:195], v[224:227], v[2:5]
	s_waitcnt vmcnt(8)
	s_barrier
	s_setprio 0
	s_add_i32 s53, s53, 2
	s_add_u32 s24, s24, 0x100
	s_addc_u32 s25, s25, 0
	s_add_u32 s51, s51, 0x100
	s_addc_u32 s52, s52, 0
	s_cmpk_gt_u32 s53, 0xa9
	s_cbranch_scc0 .LBB0_2060
	s_and_b64 vcc, exec, s[20:21]
	s_cbranch_vccz .LBB0_2063
	s_barrier

; #define PG8_STAGE(bufoff, gbase, voff) do { _Pragma("unroll") for (int _i = 0; _i < 2; ++_i) \
;         __builtin_amdgcn_global_load_lds((const unsigned*)((const char*)(gbase) + (voff)[_i]), (LAS unsigned*)(lds + (bufoff) + ldsw + _i * 8192), 16, 0, 0); } while (0)
; #define PG8_LDA(dst, b, h) do { _Pragma("unroll") for (int m = 0; m < 4; ++m) _Pragma("unroll") for (int k = 0; k < 2; ++k) dst[m][k] = *(const LAS bf16x8*)(lds + PG8_SA(b, h) + aoff + m * 2048 + k * 1024); } while (0)
; #define PG8_WAIT_V(n) asm volatile("s_waitcnt vmcnt(" #n ")" ::: "memory")
; #define PG8_BAR __builtin_amdgcn_s_barrier()
; template <class Epi, class Sched, bool ALIGN_EPI = true, bool SP2 = true>
; __device__ __forceinline__ void gemm_phase(LAS unsigned char* lds, const Gemm g, const Sched& S, const Epi& E) {
;     ...
;         const char* nA = has_next ? PG8_ABASE(nxt) : cA; const char* nB = has_next ? PG8_BBASE(nxt) : cB;
;         for (int t = 0; t < nt; t += 2) {
;             const bool last = (t == nt - 2);
;             const char* a1 = cA + (size_t)(t + 1) * kstep;
;             const char* a2 = last ? nA : cA + (size_t)(t + 2) * kstep; const char* b2 = last ? nB : cB + (size_t)(t + 2) * kstep;
;             const char* a3 = a2 + kstep; const char* b3 = b2 + kstep;
;             if (last && has_next) S.a_ready(nxt);
;             if constexpr (SP2) {
;             PG8_LDB(B0, 0, 0); PG8_LDB(B1, 0, 1); PG8_SCHED; PG8_LDA(At, 0, 0); PG8_STAGE(PG8_SA(1, 1), a1 + hstep, voffA);
;             PG8_WAIT_V(8); PG8_WAIT_L(0); PG8_BAR; PG8_MMA(0, 0, At, B0); PG8_MMA(0, 1, At, B1); PG8_BAR; PG8_SCHED;
;             PG8_LDA(At, 0, 1); PG8_STAGE(PG8_SB(0, 0), b2, voffB); PG8_STAGE(PG8_SB(0, 1), b2 + hstep, voffB); PG8_STAGE(PG8_SA(0, 0), a2, voffA);
;             PG8_WAIT_V(8); PG8_WAIT_L(0); PG8_BAR; PG8_MMA(1, 0, At, B0); PG8_MMA(1, 1, At, B1); PG8_BAR; PG8_SCHED;
;             PG8_LDB(B0, 1, 0); PG8_LDB(B1, 1, 1); PG8_SCHED; PG8_LDA(At, 1, 0); PG8_STAGE(PG8_SA(0, 1), a2 + hstep, voffA);
;             PG8_WAIT_V(8); PG8_WAIT_L(0); PG8_BAR; PG8_MMA(0, 0, At, B0); PG8_MMA(0, 1, At, B1); PG8_BAR; PG8_SCHED;
;             PG8_LDA(At, 1, 1); PG8_STAGE(PG8_SB(1, 0), b3, voffB); PG8_STAGE(PG8_SB(1, 1), b3 + hstep, voffB); PG8_STAGE(PG8_SA(1, 0), a3, voffA);
;             PG8_WAIT_V(8); PG8_WAIT_L(0); PG8_BAR; PG8_MMA(1, 0, At, B0); PG8_MMA(1, 1, At, B1); PG8_BAR; PG8_SCHED;
.LBB0_2100:
	s_add_u32 s31, s24, s30
	s_addc_u32 s38, s25, 0
	s_add_u32 s36, s31, 0x100
	s_addc_u32 s37, s38, 0
	s_and_b64 s[34:35], s[28:29], exec
	s_cselect_b32 s35, s15, s37
	s_cselect_b32 s34, s57, s36
	s_add_u32 s30, s22, s30
	s_addc_u32 s36, s23, 0
	s_add_u32 s30, s30, 0x100
	s_addc_u32 s36, s36, 0
	s_and_b64 s[28:29], s[28:29], exec
	s_cselect_b32 s37, s13, s36
	s_cselect_b32 s36, s58, s30
	s_add_u32 s40, s31, 0x10080
	ds_read_b128 v[142:145], v148
	ds_read_b128 v[152:155], v148 offset:1024
	ds_read_b128 v[156:159], v148 offset:2048
	ds_read_b128 v[160:163], v148 offset:3072
	ds_read_b128 v[164:167], v149
	ds_read_b128 v[168:171], v149 offset:1024
	ds_read_b128 v[172:175], v149 offset:2048
	ds_read_b128 v[176:179], v149 offset:3072
	s_addc_u32 s41, s38, 0
	s_add_i32 s66, s54, s46
	s_add_i32 m0, s21, 0xc000
	s_add_i32 s69, s21, 0xe000
	s_add_i32 s63, s66, 0x2000
	s_add_u32 s38, s36, 0x10000
	s_addc_u32 s39, s37, 0
	s_add_i32 s65, s55, s46
	s_add_i32 s64, s65, 0x2000
	s_add_i32 s62, 0, 0x18000
	s_add_i32 s61, 0, 0x1c000
	s_add_u32 s30, s34, 0x10000
	s_addc_u32 s31, s35, 0
	s_add_i32 s60, s62, s46
	s_add_i32 s59, s60, 0x2000
	s_add_u32 s28, s36, 0x10080
	s_addc_u32 s29, s37, 0
	s_add_i32 s68, s61, s46
	s_add_i32 s67, s68, 0x2000
	ds_read_b128 v[180:183], v150
	ds_read_b128 v[184:187], v150 offset:1024
	ds_read_b128 v[188:191], v150 offset:2048
	ds_read_b128 v[192:195], v150 offset:3072
	ds_read_b128 v[196:199], v150 offset:4096
	ds_read_b128 v[200:203], v150 offset:5120
	ds_read_b128 v[204:207], v150 offset:6144
	ds_read_b128 v[208:211], v150 offset:7168
	global_load_lds_dwordx4 v130, s[40:41]
	s_mov_b32 m0, s69
	s_nop 0
	global_load_lds_dwordx4 v134, s[40:41]
	s_and_b64 vcc, exec, s[10:11]
	s_cbranch_vccnz .Lkw2100_0
	s_waitcnt vmcnt(8)
.Lkw2100_0:
	s_waitcnt lgkmcnt(0)
	s_setprio 1
	s_barrier
	v_mfma_f32_16x16x32_bf16 v[126:129], v[142:145], v[180:183], v[126:129]
	v_mfma_f32_16x16x32_bf16 v[122:125], v[156:159], v[180:183], v[122:125]
	v_mfma_f32_16x16x32_bf16 v[118:121], v[142:145], v[188:191], v[118:121]
	v_mfma_f32_16x16x32_bf16 v[110:113], v[156:159], v[188:191], v[110:113]
	v_mfma_f32_16x16x32_bf16 v[102:105], v[142:145], v[196:199], v[102:105]
	v_mfma_f32_16x16x32_bf16 v[94:97], v[156:159], v[196:199], v[94:97]
	v_mfma_f32_16x16x32_bf16 v[86:89], v[142:145], v[204:207], v[86:89]
	v_mfma_f32_16x16x32_bf16 v[78:81], v[156:159], v[204:207], v[78:81]
	v_mfma_f32_16x16x32_bf16 v[126:129], v[152:155], v[184:187], v[126:129]
	v_mfma_f32_16x16x32_bf16 v[122:125], v[160:163], v[184:187], v[122:125]
	v_mfma_f32_16x16x32_bf16 v[118:121], v[152:155], v[192:195], v[118:121]
	v_mfma_f32_16x16x32_bf16 v[110:113], v[160:163], v[192:195], v[110:113]
	v_mfma_f32_16x16x32_bf16 v[102:105], v[152:155], v[200:203], v[102:105]
	v_mfma_f32_16x16x32_bf16 v[94:97], v[160:163], v[200:203], v[94:97]
	v_mfma_f32_16x16x32_bf16 v[86:89], v[152:155], v[208:211], v[86:89]
	v_mfma_f32_16x16x32_bf16 v[78:81], v[160:163], v[208:211], v[78:81]
	v_mfma_f32_16x16x32_bf16 v[114:117], v[164:167], v[180:183], v[114:117]
	v_mfma_f32_16x16x32_bf16 v[106:109], v[172:175], v[180:183], v[106:109]
	v_mfma_f32_16x16x32_bf16 v[98:101], v[164:167], v[188:191], v[98:101]
	v_mfma_f32_16x16x32_bf16 v[90:93], v[172:175], v[188:191], v[90:93]
	v_mfma_f32_16x16x32_bf16 v[82:85], v[164:167], v[196:199], v[82:85]
	v_mfma_f32_16x16x32_bf16 v[74:77], v[172:175], v[196:199], v[74:77]
	v_mfma_f32_16x16x32_bf16 v[70:73], v[164:167], v[204:207], v[70:73]
	v_mfma_f32_16x16x32_bf16 v[66:69], v[172:175], v[204:207], v[66:69]
	v_mfma_f32_16x16x32_bf16 v[114:117], v[168:171], v[184:187], v[114:117]
	v_mfma_f32_16x16x32_bf16 v[106:109], v[176:179], v[184:187], v[106:109]
	v_mfma_f32_16x16x32_bf16 v[98:101], v[168:171], v[192:195], v[98:101]
	v_mfma_f32_16x16x32_bf16 v[90:93], v[176:179], v[192:195], v[90:93]
	v_mfma_f32_16x16x32_bf16 v[82:85], v[168:171], v[200:203], v[82:85]
	v_mfma_f32_16x16x32_bf16 v[74:77], v[176:179], v[200:203], v[74:77]
	v_mfma_f32_16x16x32_bf16 v[70:73], v[168:171], v[208:211], v[70:73]
	v_mfma_f32_16x16x32_bf16 v[66:69], v[176:179], v[208:211], v[66:69]
	s_waitcnt vmcnt(8)
	s_barrier
	s_setprio 0
	s_mov_b32 m0, s66
	v_lshl_add_u64 v[212:213], s[36:37], 0, v[132:133]
	ds_read_b128 v[180:183], v150 offset:16384
	ds_read_b128 v[184:187], v150 offset:17408
	ds_read_b128 v[188:191], v150 offset:18432
	ds_read_b128 v[192:195], v150 offset:19456
	ds_read_b128 v[196:199], v150 offset:20480
	ds_read_b128 v[200:203], v150 offset:21504
	ds_read_b128 v[204:207], v150 offset:22528
	ds_read_b128 v[208:211], v150 offset:23552
	global_load_lds_dwordx4 v[212:213], off
	v_lshl_add_u64 v[214:215], s[36:37], 0, v[136:137]
	s_mov_b32 m0, s63
	s_nop 0
	global_load_lds_dwordx4 v[214:215], off
	s_mov_b32 m0, s65
	v_lshl_add_u64 v[218:219], s[34:35], 0, v[134:135]
	global_load_lds_dwordx4 v132, s[38:39]
	s_mov_b32 m0, s64
	s_nop 0
	global_load_lds_dwordx4 v136, s[38:39]
	v_lshl_add_u64 v[216:217], s[34:35], 0, v[130:131]
	s_mov_b32 m0, s21
	s_nop 0
	global_load_lds_dwordx4 v[216:217], off
	s_mov_b32 m0, s47
	s_nop 0
	global_load_lds_dwordx4 v[218:219], off
	s_and_b64 vcc, exec, s[10:11]
	s_cbranch_vccnz .Lkw2100_1
	s_waitcnt vmcnt(8)
; #define PG8_STAGE(bufoff, gbase, voff) do { _Pragma("unroll") for (int _i = 0; _i < 2; ++_i) \
;         __builtin_amdgcn_global_load_lds((const unsigned*)((const char*)(gbase) + (voff)[_i]), (LAS unsigned*)(lds + (bufoff) + ldsw + _i * 8192), 16, 0, 0); } while (0)
; #define PG8_LDA(dst, b, h) do { _Pragma("unroll") for (int m = 0; m < 4; ++m) _Pragma("unroll") for (int k = 0; k < 2; ++k) dst[m][k] = *(const LAS bf16x8*)(lds + PG8_SA(b, h) + aoff + m * 2048 + k * 1024); } while (0)
; #define PG8_LDB(dst, b, h) do { _Pragma("unroll") for (int n = 0; n < 2; ++n) _Pragma("unroll") for (int k = 0; k < 2; ++k) dst[n][k] = *(const LAS bf16x8*)(lds + PG8_SB(b, h) + boff + n * 2048 + k * 1024); } while (0)
; #define PG8_MMA(ai, bj, At, Bt) do { __builtin_amdgcn_s_setprio(1); _Pragma("unroll") for (int m = 0; m < 4; ++m) _Pragma("unroll") for (int n = 0; n < 2; ++n) _Pragma("unroll") for (int k = 0; k < 2; ++k) \
;         acc[ai][bj][m][n] = __builtin_amdgcn_mfma_f32_16x16x32_bf16(Bt[n][k], At[m][k], acc[ai][bj][m][n], 0, 0, 0); __builtin_amdgcn_s_setprio(0); } while (0)
; #define PG8_WAIT_V(n) asm volatile("s_waitcnt vmcnt(" #n ")" ::: "memory")
; #define PG8_WAIT_L(n) asm volatile("s_waitcnt lgkmcnt(" #n ")" ::: "memory")
; #define PG8_BAR __builtin_amdgcn_s_barrier()
; #define PG8_SCHED __builtin_amdgcn_sched_barrier(0)
; template <class Epi, class Sched, bool ALIGN_EPI = true, bool SP2 = true>
; __device__ __forceinline__ void gemm_phase(LAS unsigned char* lds, const Gemm g, const Sched& S, const Epi& E) {
;     ...
;             PG8_WAIT_V(8); PG8_WAIT_L(0); PG8_BAR; PG8_MMA(1, 0, At, B0); PG8_MMA(1, 1, At, B1); PG8_BAR; PG8_SCHED;
;             PG8_LDB(B0, 1, 0); PG8_LDB(B1, 1, 1); PG8_SCHED; PG8_LDA(At, 1, 0); PG8_STAGE(PG8_SA(0, 1), a2 + hstep, voffA);
;             PG8_WAIT_V(8); PG8_WAIT_L(0); PG8_BAR; PG8_MMA(0, 0, At, B0); PG8_MMA(0, 1, At, B1); PG8_BAR; PG8_SCHED;
.Lkw2100_1:
	s_waitcnt lgkmcnt(0)
	s_setprio 1
	s_barrier
	v_mfma_f32_16x16x32_bf16 v[62:65], v[142:145], v[180:183], v[62:65]
	v_mfma_f32_16x16x32_bf16 v[58:61], v[156:159], v[180:183], v[58:61]
	v_mfma_f32_16x16x32_bf16 v[54:57], v[142:145], v[188:191], v[54:57]
	v_mfma_f32_16x16x32_bf16 v[46:49], v[156:159], v[188:191], v[46:49]
	v_mfma_f32_16x16x32_bf16 v[38:41], v[142:145], v[196:199], v[38:41]
	v_mfma_f32_16x16x32_bf16 v[30:33], v[156:159], v[196:199], v[30:33]
	v_mfma_f32_16x16x32_bf16 v[22:25], v[142:145], v[204:207], v[22:25]
	v_mfma_f32_16x16x32_bf16 v[14:17], v[156:159], v[204:207], v[14:17]
	v_mfma_f32_16x16x32_bf16 v[62:65], v[152:155], v[184:187], v[62:65]
	v_mfma_f32_16x16x32_bf16 v[58:61], v[160:163], v[184:187], v[58:61]
	v_mfma_f32_16x16x32_bf16 v[54:57], v[152:155], v[192:195], v[54:57]
	v_mfma_f32_16x16x32_bf16 v[46:49], v[160:163], v[192:195], v[46:49]
	v_mfma_f32_16x16x32_bf16 v[38:41], v[152:155], v[200:203], v[38:41]
	v_mfma_f32_16x16x32_bf16 v[30:33], v[160:163], v[200:203], v[30:33]
	v_mfma_f32_16x16x32_bf16 v[22:25], v[152:155], v[208:211], v[22:25]
	v_mfma_f32_16x16x32_bf16 v[14:17], v[160:163], v[208:211], v[14:17]
	v_mfma_f32_16x16x32_bf16 v[50:53], v[164:167], v[180:183], v[50:53]
	v_mfma_f32_16x16x32_bf16 v[42:45], v[172:175], v[180:183], v[42:45]
	v_mfma_f32_16x16x32_bf16 v[34:37], v[164:167], v[188:191], v[34:37]
	v_mfma_f32_16x16x32_bf16 v[26:29], v[172:175], v[188:191], v[26:29]
	v_mfma_f32_16x16x32_bf16 v[18:21], v[164:167], v[196:199], v[18:21]
	v_mfma_f32_16x16x32_bf16 v[10:13], v[172:175], v[196:199], v[10:13]
	v_mfma_f32_16x16x32_bf16 v[6:9], v[164:167], v[204:207], v[6:9]
	v_mfma_f32_16x16x32_bf16 v[2:5], v[172:175], v[204:207], v[2:5]
	v_mfma_f32_16x16x32_bf16 v[50:53], v[168:171], v[184:187], v[50:53]
	v_mfma_f32_16x16x32_bf16 v[42:45], v[176:179], v[184:187], v[42:45]
	v_mfma_f32_16x16x32_bf16 v[34:37], v[168:171], v[192:195], v[34:37]
	v_mfma_f32_16x16x32_bf16 v[26:29], v[176:179], v[192:195], v[26:29]
	v_mfma_f32_16x16x32_bf16 v[18:21], v[168:171], v[200:203], v[18:21]
	v_mfma_f32_16x16x32_bf16 v[10:13], v[176:179], v[200:203], v[10:13]
	v_mfma_f32_16x16x32_bf16 v[6:9], v[168:171], v[208:211], v[6:9]
	v_mfma_f32_16x16x32_bf16 v[2:5], v[176:179], v[208:211], v[2:5]
	s_waitcnt vmcnt(8)
	s_barrier
	s_setprio 0
	v_add_u32_e32 v151, s62, v147
	ds_read_b128 v[142:145], v151
	ds_read_b128 v[152:155], v151 offset:1024
	ds_read_b128 v[156:159], v151 offset:2048
	ds_read_b128 v[160:163], v151 offset:3072
	v_add_u32_e32 v151, s61, v147
	ds_read_b128 v[164:167], v151
	ds_read_b128 v[168:171], v151 offset:1024
	ds_read_b128 v[172:175], v151 offset:2048
	ds_read_b128 v[176:179], v151 offset:3072
	s_mov_b32 m0, s48
	ds_read_b128 v[180:183], v150 offset:32768
	ds_read_b128 v[184:187], v150 offset:33792
	ds_read_b128 v[188:191], v150 offset:34816
	ds_read_b128 v[192:195], v150 offset:35840
	ds_read_b128 v[196:199], v150 offset:36864
	ds_read_b128 v[200:203], v150 offset:37888
	ds_read_b128 v[204:207], v150 offset:38912
	ds_read_b128 v[208:211], v150 offset:39936
	global_load_lds_dwordx4 v130, s[30:31]
	s_mov_b32 m0, s49
	s_nop 0
	global_load_lds_dwordx4 v134, s[30:31]
	s_and_b64 vcc, exec, s[10:11]
	s_cbranch_vccnz .Lkw2100_2
	s_waitcnt vmcnt(8)
;     __host__ __device__ bool next(int i, Unit& u) const { const bool ok = StaticOrder::next(i >> 1, u); u.z = i & 1; return ok; }
; #define PG8_STAGE(bufoff, gbase, voff) do { _Pragma("unroll") for (int _i = 0; _i < 2; ++_i) \
;         __builtin_amdgcn_global_load_lds((const unsigned*)((const char*)(gbase) + (voff)[_i]), (LAS unsigned*)(lds + (bufoff) + ldsw + _i * 8192), 16, 0, 0); } while (0)
; #define PG8_LDA(dst, b, h) do { _Pragma("unroll") for (int m = 0; m < 4; ++m) _Pragma("unroll") for (int k = 0; k < 2; ++k) dst[m][k] = *(const LAS bf16x8*)(lds + PG8_SA(b, h) + aoff + m * 2048 + k * 1024); } while (0)
; #define PG8_MMA(ai, bj, At, Bt) do { __builtin_amdgcn_s_setprio(1); _Pragma("unroll") for (int m = 0; m < 4; ++m) _Pragma("unroll") for (int n = 0; n < 2; ++n) _Pragma("unroll") for (int k = 0; k < 2; ++k) \
;         acc[ai][bj][m][n] = __builtin_amdgcn_mfma_f32_16x16x32_bf16(Bt[n][k], At[m][k], acc[ai][bj][m][n], 0, 0, 0); __builtin_amdgcn_s_setprio(0); } while (0)
; #define PG8_WAIT_V(n) asm volatile("s_waitcnt vmcnt(" #n ")" ::: "memory")
; #define PG8_WAIT_L(n) asm volatile("s_waitcnt lgkmcnt(" #n ")" ::: "memory")
; #define PG8_BAR __builtin_amdgcn_s_barrier()
; #define PG8_SCHED __builtin_amdgcn_sched_barrier(0)
; template <class Epi, class Sched, bool ALIGN_EPI = true, bool SP2 = true>
; __device__ __forceinline__ void gemm_phase(LAS unsigned char* lds, const Gemm g, const Sched& S, const Epi& E) {
;     ...
;     for (;;) {
;         const bool has_next = S.next(ui + 1, nxt);
;         const char* nA = has_next ? PG8_ABASE(nxt) : cA; const char* nB = has_next ? PG8_BBASE(nxt) : cB;
;     ...
;             PG8_WAIT_V(8); PG8_WAIT_L(0); PG8_BAR; PG8_MMA(0, 0, At, B0); PG8_MMA(0, 1, At, B1); PG8_BAR; PG8_SCHED;
;             PG8_LDA(At, 1, 1); PG8_STAGE(PG8_SB(1, 0), b3, voffB); PG8_STAGE(PG8_SB(1, 1), b3 + hstep, voffB); PG8_STAGE(PG8_SA(1, 0), a3, voffA);
;             PG8_WAIT_V(8); PG8_WAIT_L(0); PG8_BAR; PG8_MMA(1, 0, At, B0); PG8_MMA(1, 1, At, B1); PG8_BAR; PG8_SCHED;
;     ...
;         if constexpr (ALIGN_EPI) { if (wr == 0) PG8_BAR; }
.Lkw2100_2:
	s_waitcnt lgkmcnt(0)
	s_setprio 1
	s_barrier
	v_mfma_f32_16x16x32_bf16 v[126:129], v[142:145], v[180:183], v[126:129]
	v_mfma_f32_16x16x32_bf16 v[122:125], v[156:159], v[180:183], v[122:125]
	v_mfma_f32_16x16x32_bf16 v[118:121], v[142:145], v[188:191], v[118:121]
	v_mfma_f32_16x16x32_bf16 v[110:113], v[156:159], v[188:191], v[110:113]
	v_mfma_f32_16x16x32_bf16 v[102:105], v[142:145], v[196:199], v[102:105]
	v_mfma_f32_16x16x32_bf16 v[94:97], v[156:159], v[196:199], v[94:97]
	v_mfma_f32_16x16x32_bf16 v[86:89], v[142:145], v[204:207], v[86:89]
	v_mfma_f32_16x16x32_bf16 v[78:81], v[156:159], v[204:207], v[78:81]
	v_mfma_f32_16x16x32_bf16 v[126:129], v[152:155], v[184:187], v[126:129]
	v_mfma_f32_16x16x32_bf16 v[122:125], v[160:163], v[184:187], v[122:125]
	v_mfma_f32_16x16x32_bf16 v[118:121], v[152:155], v[192:195], v[118:121]
	v_mfma_f32_16x16x32_bf16 v[110:113], v[160:163], v[192:195], v[110:113]
	v_mfma_f32_16x16x32_bf16 v[102:105], v[152:155], v[200:203], v[102:105]
	v_mfma_f32_16x16x32_bf16 v[94:97], v[160:163], v[200:203], v[94:97]
	v_mfma_f32_16x16x32_bf16 v[86:89], v[152:155], v[208:211], v[86:89]
	v_mfma_f32_16x16x32_bf16 v[78:81], v[160:163], v[208:211], v[78:81]
	v_mfma_f32_16x16x32_bf16 v[114:117], v[164:167], v[180:183], v[114:117]
	v_mfma_f32_16x16x32_bf16 v[106:109], v[172:175], v[180:183], v[106:109]
	v_mfma_f32_16x16x32_bf16 v[98:101], v[164:167], v[188:191], v[98:101]
	v_mfma_f32_16x16x32_bf16 v[90:93], v[172:175], v[188:191], v[90:93]
	v_mfma_f32_16x16x32_bf16 v[82:85], v[164:167], v[196:199], v[82:85]
	v_mfma_f32_16x16x32_bf16 v[74:77], v[172:175], v[196:199], v[74:77]
	v_mfma_f32_16x16x32_bf16 v[70:73], v[164:167], v[204:207], v[70:73]
	v_mfma_f32_16x16x32_bf16 v[66:69], v[172:175], v[204:207], v[66:69]
	v_mfma_f32_16x16x32_bf16 v[114:117], v[168:171], v[184:187], v[114:117]
	v_mfma_f32_16x16x32_bf16 v[106:109], v[176:179], v[184:187], v[106:109]
	v_mfma_f32_16x16x32_bf16 v[98:101], v[168:171], v[192:195], v[98:101]
	v_mfma_f32_16x16x32_bf16 v[90:93], v[176:179], v[192:195], v[90:93]
	v_mfma_f32_16x16x32_bf16 v[82:85], v[168:171], v[200:203], v[82:85]
	v_mfma_f32_16x16x32_bf16 v[74:77], v[176:179], v[200:203], v[74:77]
	v_mfma_f32_16x16x32_bf16 v[70:73], v[168:171], v[208:211], v[70:73]
	v_mfma_f32_16x16x32_bf16 v[66:69], v[176:179], v[208:211], v[66:69]
	s_waitcnt vmcnt(8)
	s_barrier
	s_setprio 0
	s_mov_b32 m0, s60
	v_lshl_add_u64 v[212:213], v[212:213], 0, s[6:7]
	ds_read_b128 v[180:183], v150 offset:49152
	ds_read_b128 v[184:187], v150 offset:50176
	ds_read_b128 v[188:191], v150 offset:51200
	ds_read_b128 v[192:195], v150 offset:52224
	ds_read_b128 v[196:199], v150 offset:53248
	ds_read_b128 v[200:203], v150 offset:54272
	ds_read_b128 v[204:207], v150 offset:55296
	ds_read_b128 v[208:211], v150 offset:56320
	global_load_lds_dwordx4 v[212:213], off
	v_lshl_add_u64 v[212:213], v[214:215], 0, s[6:7]
	s_mov_b32 m0, s59
	s_nop 0
	global_load_lds_dwordx4 v[212:213], off
	s_mov_b32 m0, s68
	s_nop 0
	global_load_lds_dwordx4 v132, s[28:29]
	s_mov_b32 m0, s67
	s_nop 0
	global_load_lds_dwordx4 v136, s[28:29]
	v_lshl_add_u64 v[212:213], v[216:217], 0, s[6:7]
	s_mov_b32 m0, s51
	s_nop 0
	global_load_lds_dwordx4 v[212:213], off
	v_lshl_add_u64 v[212:213], v[218:219], 0, s[6:7]
	s_mov_b32 m0, s52
	s_nop 0
	global_load_lds_dwordx4 v[212:213], off
	s_and_b64 vcc, exec, s[10:11]
	s_cbranch_vccnz .Lkw2100_3
	s_waitcnt vmcnt(8)
.Lkw2100_3:
	s_waitcnt lgkmcnt(0)
	s_setprio 1
	s_barrier
	v_mfma_f32_16x16x32_bf16 v[62:65], v[142:145], v[180:183], v[62:65]
	v_mfma_f32_16x16x32_bf16 v[58:61], v[156:159], v[180:183], v[58:61]
	v_mfma_f32_16x16x32_bf16 v[54:57], v[142:145], v[188:191], v[54:57]
	v_mfma_f32_16x16x32_bf16 v[46:49], v[156:159], v[188:191], v[46:49]
	v_mfma_f32_16x16x32_bf16 v[38:41], v[142:145], v[196:199], v[38:41]
	v_mfma_f32_16x16x32_bf16 v[30:33], v[156:159], v[196:199], v[30:33]
	v_mfma_f32_16x16x32_bf16 v[22:25], v[142:145], v[204:207], v[22:25]
	v_mfma_f32_16x16x32_bf16 v[14:17], v[156:159], v[204:207], v[14:17]
	v_mfma_f32_16x16x32_bf16 v[62:65], v[152:155], v[184:187], v[62:65]
	v_mfma_f32_16x16x32_bf16 v[58:61], v[160:163], v[184:187], v[58:61]
	v_mfma_f32_16x16x32_bf16 v[54:57], v[152:155], v[192:195], v[54:57]
	v_mfma_f32_16x16x32_bf16 v[46:49], v[160:163], v[192:195], v[46:49]
	v_mfma_f32_16x16x32_bf16 v[38:41], v[152:155], v[200:203], v[38:41]
	v_mfma_f32_16x16x32_bf16 v[30:33], v[160:163], v[200:203], v[30:33]
	v_mfma_f32_16x16x32_bf16 v[22:25], v[152:155], v[208:211], v[22:25]
	v_mfma_f32_16x16x32_bf16 v[14:17], v[160:163], v[208:211], v[14:17]
	v_mfma_f32_16x16x32_bf16 v[50:53], v[164:167], v[180:183], v[50:53]
	v_mfma_f32_16x16x32_bf16 v[42:45], v[172:175], v[180:183], v[42:45]
	v_mfma_f32_16x16x32_bf16 v[34:37], v[164:167], v[188:191], v[34:37]
	v_mfma_f32_16x16x32_bf16 v[26:29], v[172:175], v[188:191], v[26:29]
	v_mfma_f32_16x16x32_bf16 v[18:21], v[164:167], v[196:199], v[18:21]
	v_mfma_f32_16x16x32_bf16 v[10:13], v[172:175], v[196:199], v[10:13]
	v_mfma_f32_16x16x32_bf16 v[6:9], v[164:167], v[204:207], v[6:9]
	v_mfma_f32_16x16x32_bf16 v[2:5], v[172:175], v[204:207], v[2:5]
	v_mfma_f32_16x16x32_bf16 v[50:53], v[168:171], v[184:187], v[50:53]
	v_mfma_f32_16x16x32_bf16 v[42:45], v[176:179], v[184:187], v[42:45]
	v_mfma_f32_16x16x32_bf16 v[34:37], v[168:171], v[192:195], v[34:37]
	v_mfma_f32_16x16x32_bf16 v[26:29], v[176:179], v[192:195], v[26:29]
	v_mfma_f32_16x16x32_bf16 v[18:21], v[168:171], v[200:203], v[18:21]
	v_mfma_f32_16x16x32_bf16 v[10:13], v[176:179], v[200:203], v[10:13]
	v_mfma_f32_16x16x32_bf16 v[6:9], v[168:171], v[208:211], v[6:9]
	v_mfma_f32_16x16x32_bf16 v[2:5], v[176:179], v[208:211], v[2:5]
	s_waitcnt vmcnt(8)
	s_barrier
	s_setprio 0
	s_movk_i32 s30, 0x100
	s_andn2_b64 vcc, exec, s[26:27]
	s_mov_b64 s[28:29], -1
	s_mov_b64 s[26:27], 0
	s_cbranch_vccz .LBB0_2100
	s_and_b64 vcc, exec, s[10:11]
	s_cbranch_vccz .LBB0_2103
	s_barrier

; #define PG8_STAGE(bufoff, gbase, voff) do { _Pragma("unroll") for (int _i = 0; _i < 2; ++_i) \
;         __builtin_amdgcn_global_load_lds((const unsigned*)((const char*)(gbase) + (voff)[_i]), (LAS unsigned*)(lds + (bufoff) + ldsw + _i * 8192), 16, 0, 0); } while (0)
; #define PG8_LDA(dst, b, h) do { _Pragma("unroll") for (int m = 0; m < 4; ++m) _Pragma("unroll") for (int k = 0; k < 2; ++k) dst[m][k] = *(const LAS bf16x8*)(lds + PG8_SA(b, h) + aoff + m * 2048 + k * 1024); } while (0)
; #define PG8_LDB(dst, b, h) do { _Pragma("unroll") for (int n = 0; n < 2; ++n) _Pragma("unroll") for (int k = 0; k < 2; ++k) dst[n][k] = *(const LAS bf16x8*)(lds + PG8_SB(b, h) + boff + n * 2048 + k * 1024); } while (0)
; #define PG8_MMA(ai, bj, At, Bt) do { __builtin_amdgcn_s_setprio(1); _Pragma("unroll") for (int m = 0; m < 4; ++m) _Pragma("unroll") for (int n = 0; n < 2; ++n) _Pragma("unroll") for (int k = 0; k < 2; ++k) \
;         acc[ai][bj][m][n] = __builtin_amdgcn_mfma_f32_16x16x32_bf16(Bt[n][k], At[m][k], acc[ai][bj][m][n], 0, 0, 0); __builtin_amdgcn_s_setprio(0); } while (0)
; #define PG8_WAIT_V(n) asm volatile("s_waitcnt vmcnt(" #n ")" ::: "memory")
; #define PG8_WAIT_L(n) asm volatile("s_waitcnt lgkmcnt(" #n ")" ::: "memory")
; #define PG8_BAR __builtin_amdgcn_s_barrier()
; #define PG8_SCHED __builtin_amdgcn_sched_barrier(0)
; template <class Epi, class Sched, bool ALIGN_EPI = true, bool SP2 = true>
; __device__ __forceinline__ void gemm_phase(LAS unsigned char* lds, const Gemm g, const Sched& S, const Epi& E) {
;     ...
;             const char* a2 = last ? nA : cA + (size_t)(t + 2) * kstep; const char* b2 = last ? nB : cB + (size_t)(t + 2) * kstep;
;     ...
;             PG8_LDB(B0, 0, 0); PG8_LDB(B1, 0, 1); PG8_SCHED; PG8_LDA(At, 0, 0); PG8_STAGE(PG8_SA(1, 1), a1 + hstep, voffA);
;             PG8_WAIT_V(8); PG8_WAIT_L(0); PG8_BAR; PG8_MMA(0, 0, At, B0); PG8_MMA(0, 1, At, B1); PG8_BAR; PG8_SCHED;
.LBB0_2179:
	ds_read_b128 v[120:123], v201
	ds_read_b128 v[124:127], v201 offset:1024
	ds_read_b128 v[132:135], v201 offset:2048
	ds_read_b128 v[140:143], v201 offset:3072
	ds_read_b128 v[144:147], v202
	ds_read_b128 v[148:151], v202 offset:1024
	ds_read_b128 v[152:155], v202 offset:2048
	ds_read_b128 v[156:159], v202 offset:3072
	s_add_u32 s36, s34, 0xfff00080
	s_addc_u32 s37, s35, -1
	s_cmp_eq_u32 s61, 60
	s_cselect_b32 s39, s27, s37
	s_cselect_b32 s38, s57, s36
	s_cselect_b32 s37, s25, s60
	s_cselect_b32 s36, s58, s59
	s_add_i32 m0, s43, 0xc000
	ds_read_b128 v[160:163], v203
	ds_read_b128 v[164:167], v203 offset:1024
	ds_read_b128 v[168:171], v203 offset:2048
	ds_read_b128 v[172:175], v203 offset:3072
	ds_read_b128 v[192:195], v203 offset:4096
	ds_read_b128 v[206:209], v203 offset:5120
	ds_read_b128 v[210:213], v203 offset:6144
	ds_read_b128 v[214:217], v203 offset:7168
	global_load_lds_dwordx4 v184, s[34:35]
	s_add_i32 m0, s43, 0xe000
	s_nop 0
	global_load_lds_dwordx4 v186, s[34:35]
	s_and_b64 vcc, exec, s[16:17]
	s_cbranch_vccnz .Lkw2179_0
	s_waitcnt vmcnt(8)
.Lkw2179_0:
	s_waitcnt lgkmcnt(0)
	s_setprio 1
	s_barrier
	v_mfma_f32_16x16x32_bf16 v[136:139], v[120:123], v[160:163], v[136:139]
	v_mfma_f32_16x16x32_bf16 v[128:131], v[132:135], v[160:163], v[128:131]
	v_mfma_f32_16x16x32_bf16 v[108:111], v[120:123], v[168:171], v[108:111]
	v_mfma_f32_16x16x32_bf16 v[104:107], v[132:135], v[168:171], v[104:107]
	v_mfma_f32_16x16x32_bf16 v[92:95], v[120:123], v[192:195], v[92:95]
	v_mfma_f32_16x16x32_bf16 v[88:91], v[132:135], v[192:195], v[88:91]
	v_mfma_f32_16x16x32_bf16 v[76:79], v[120:123], v[210:213], v[76:79]
	v_mfma_f32_16x16x32_bf16 v[72:75], v[132:135], v[210:213], v[72:75]
	v_mfma_f32_16x16x32_bf16 v[136:139], v[124:127], v[164:167], v[136:139]
	v_mfma_f32_16x16x32_bf16 v[128:131], v[140:143], v[164:167], v[128:131]
	v_mfma_f32_16x16x32_bf16 v[108:111], v[124:127], v[172:175], v[108:111]
	v_mfma_f32_16x16x32_bf16 v[104:107], v[140:143], v[172:175], v[104:107]
	v_mfma_f32_16x16x32_bf16 v[92:95], v[124:127], v[206:209], v[92:95]
	v_mfma_f32_16x16x32_bf16 v[88:91], v[140:143], v[206:209], v[88:91]
	v_mfma_f32_16x16x32_bf16 v[76:79], v[124:127], v[214:217], v[76:79]
	v_mfma_f32_16x16x32_bf16 v[72:75], v[140:143], v[214:217], v[72:75]
	v_mfma_f32_16x16x32_bf16 v[116:119], v[144:147], v[160:163], v[116:119]
	v_mfma_f32_16x16x32_bf16 v[112:115], v[152:155], v[160:163], v[112:115]
	v_mfma_f32_16x16x32_bf16 v[100:103], v[144:147], v[168:171], v[100:103]
	v_mfma_f32_16x16x32_bf16 v[96:99], v[152:155], v[168:171], v[96:99]
	v_mfma_f32_16x16x32_bf16 v[84:87], v[144:147], v[192:195], v[84:87]
	v_mfma_f32_16x16x32_bf16 v[80:83], v[152:155], v[192:195], v[80:83]
	v_mfma_f32_16x16x32_bf16 v[68:71], v[144:147], v[210:213], v[68:71]
	v_mfma_f32_16x16x32_bf16 v[64:67], v[152:155], v[210:213], v[64:67]
	v_mfma_f32_16x16x32_bf16 v[116:119], v[148:151], v[164:167], v[116:119]
	v_mfma_f32_16x16x32_bf16 v[112:115], v[156:159], v[164:167], v[112:115]
	v_mfma_f32_16x16x32_bf16 v[100:103], v[148:151], v[172:175], v[100:103]
	v_mfma_f32_16x16x32_bf16 v[96:99], v[156:159], v[172:175], v[96:99]
	v_mfma_f32_16x16x32_bf16 v[84:87], v[148:151], v[206:209], v[84:87]
	v_mfma_f32_16x16x32_bf16 v[80:83], v[156:159], v[206:209], v[80:83]
	v_mfma_f32_16x16x32_bf16 v[68:71], v[148:151], v[214:217], v[68:71]
	v_mfma_f32_16x16x32_bf16 v[64:67], v[156:159], v[214:217], v[64:67]
	s_waitcnt vmcnt(8)
	s_barrier
	s_setprio 0
	s_add_i32 s62, s51, s42
	v_lshl_add_u64 v[196:197], s[36:37], 0, v[178:179]
	s_mov_b32 m0, s62
	ds_read_b128 v[160:163], v203 offset:16384
	ds_read_b128 v[164:167], v203 offset:17408
	ds_read_b128 v[168:171], v203 offset:18432
	ds_read_b128 v[172:175], v203 offset:19456
	ds_read_b128 v[192:195], v203 offset:20480
	ds_read_b128 v[206:209], v203 offset:21504
	ds_read_b128 v[210:213], v203 offset:22528
	ds_read_b128 v[214:217], v203 offset:23552
	global_load_lds_dwordx4 v[196:197], off
	s_add_i32 m0, s62, 0x2000
	s_add_u32 s62, s36, 0x100000
	v_lshl_add_u64 v[218:219], s[36:37], 0, v[182:183]
	s_addc_u32 s63, s37, 0
	s_add_i32 s64, s52, s42
	global_load_lds_dwordx4 v[218:219], off
	s_mov_b32 m0, s64
	v_lshl_add_u64 v[222:223], s[38:39], 0, v[180:181]
	global_load_lds_dwordx4 v178, s[62:63]
	s_add_i32 m0, s64, 0x2000
	s_nop 0
	global_load_lds_dwordx4 v182, s[62:63]
	v_lshl_add_u64 v[220:221], s[38:39], 0, v[176:177]
	s_mov_b32 m0, s43
	s_nop 0
	global_load_lds_dwordx4 v[220:221], off
	s_mov_b32 m0, s44
	s_nop 0
	global_load_lds_dwordx4 v[222:223], off
	s_and_b64 vcc, exec, s[16:17]
	s_cbranch_vccnz .Lkw2179_1
	s_waitcnt vmcnt(8)
; #define PG8_STAGE(bufoff, gbase, voff) do { _Pragma("unroll") for (int _i = 0; _i < 2; ++_i) \
;         __builtin_amdgcn_global_load_lds((const unsigned*)((const char*)(gbase) + (voff)[_i]), (LAS unsigned*)(lds + (bufoff) + ldsw + _i * 8192), 16, 0, 0); } while (0)
; #define PG8_LDA(dst, b, h) do { _Pragma("unroll") for (int m = 0; m < 4; ++m) _Pragma("unroll") for (int k = 0; k < 2; ++k) dst[m][k] = *(const LAS bf16x8*)(lds + PG8_SA(b, h) + aoff + m * 2048 + k * 1024); } while (0)
; #define PG8_LDB(dst, b, h) do { _Pragma("unroll") for (int n = 0; n < 2; ++n) _Pragma("unroll") for (int k = 0; k < 2; ++k) dst[n][k] = *(const LAS bf16x8*)(lds + PG8_SB(b, h) + boff + n * 2048 + k * 1024); } while (0)
; #define PG8_MMA(ai, bj, At, Bt) do { __builtin_amdgcn_s_setprio(1); _Pragma("unroll") for (int m = 0; m < 4; ++m) _Pragma("unroll") for (int n = 0; n < 2; ++n) _Pragma("unroll") for (int k = 0; k < 2; ++k) \
;         acc[ai][bj][m][n] = __builtin_amdgcn_mfma_f32_16x16x32_bf16(Bt[n][k], At[m][k], acc[ai][bj][m][n], 0, 0, 0); __builtin_amdgcn_s_setprio(0); } while (0)
; #define PG8_WAIT_V(n) asm volatile("s_waitcnt vmcnt(" #n ")" ::: "memory")
; #define PG8_WAIT_L(n) asm volatile("s_waitcnt lgkmcnt(" #n ")" ::: "memory")
; #define PG8_BAR __builtin_amdgcn_s_barrier()
; #define PG8_SCHED __builtin_amdgcn_sched_barrier(0)
; template <class Epi, class Sched, bool ALIGN_EPI = true, bool SP2 = true>
; __device__ __forceinline__ void gemm_phase(LAS unsigned char* lds, const Gemm g, const Sched& S, const Epi& E) {
;     ...
;             PG8_WAIT_V(8); PG8_WAIT_L(0); PG8_BAR; PG8_MMA(1, 0, At, B0); PG8_MMA(1, 1, At, B1); PG8_BAR; PG8_SCHED;
;             PG8_LDB(B0, 1, 0); PG8_LDB(B1, 1, 1); PG8_SCHED; PG8_LDA(At, 1, 0); PG8_STAGE(PG8_SA(0, 1), a2 + hstep, voffA);
;             PG8_WAIT_V(8); PG8_WAIT_L(0); PG8_BAR; PG8_MMA(0, 0, At, B0); PG8_MMA(0, 1, At, B1); PG8_BAR; PG8_SCHED;
.Lkw2179_1:
	s_waitcnt lgkmcnt(0)
	s_setprio 1
	s_barrier
	v_mfma_f32_16x16x32_bf16 v[60:63], v[120:123], v[160:163], v[60:63]
	v_mfma_f32_16x16x32_bf16 v[56:59], v[132:135], v[160:163], v[56:59]
	v_mfma_f32_16x16x32_bf16 v[44:47], v[120:123], v[168:171], v[44:47]
	v_mfma_f32_16x16x32_bf16 v[40:43], v[132:135], v[168:171], v[40:43]
	v_mfma_f32_16x16x32_bf16 v[28:31], v[120:123], v[192:195], v[28:31]
	v_mfma_f32_16x16x32_bf16 v[24:27], v[132:135], v[192:195], v[24:27]
	v_mfma_f32_16x16x32_bf16 v[12:15], v[120:123], v[210:213], v[12:15]
	v_mfma_f32_16x16x32_bf16 v[8:11], v[132:135], v[210:213], v[8:11]
	v_mfma_f32_16x16x32_bf16 v[60:63], v[124:127], v[164:167], v[60:63]
	v_mfma_f32_16x16x32_bf16 v[56:59], v[140:143], v[164:167], v[56:59]
	v_mfma_f32_16x16x32_bf16 v[44:47], v[124:127], v[172:175], v[44:47]
	v_mfma_f32_16x16x32_bf16 v[40:43], v[140:143], v[172:175], v[40:43]
	v_mfma_f32_16x16x32_bf16 v[28:31], v[124:127], v[206:209], v[28:31]
	v_mfma_f32_16x16x32_bf16 v[24:27], v[140:143], v[206:209], v[24:27]
	v_mfma_f32_16x16x32_bf16 v[12:15], v[124:127], v[214:217], v[12:15]
	v_mfma_f32_16x16x32_bf16 v[8:11], v[140:143], v[214:217], v[8:11]
	v_mfma_f32_16x16x32_bf16 v[52:55], v[144:147], v[160:163], v[52:55]
	v_mfma_f32_16x16x32_bf16 v[48:51], v[152:155], v[160:163], v[48:51]
	v_mfma_f32_16x16x32_bf16 v[36:39], v[144:147], v[168:171], v[36:39]
	v_mfma_f32_16x16x32_bf16 v[32:35], v[152:155], v[168:171], v[32:35]
	v_mfma_f32_16x16x32_bf16 v[20:23], v[144:147], v[192:195], v[20:23]
	v_mfma_f32_16x16x32_bf16 v[16:19], v[152:155], v[192:195], v[16:19]
	v_mfma_f32_16x16x32_bf16 v[4:7], v[144:147], v[210:213], v[4:7]
	v_mfma_f32_16x16x32_bf16 v[0:3], v[152:155], v[210:213], v[0:3]
	v_mfma_f32_16x16x32_bf16 v[52:55], v[148:151], v[164:167], v[52:55]
	v_mfma_f32_16x16x32_bf16 v[48:51], v[156:159], v[164:167], v[48:51]
	v_mfma_f32_16x16x32_bf16 v[36:39], v[148:151], v[172:175], v[36:39]
	v_mfma_f32_16x16x32_bf16 v[32:35], v[156:159], v[172:175], v[32:35]
	v_mfma_f32_16x16x32_bf16 v[20:23], v[148:151], v[206:209], v[20:23]
	v_mfma_f32_16x16x32_bf16 v[16:19], v[156:159], v[206:209], v[16:19]
	v_mfma_f32_16x16x32_bf16 v[4:7], v[148:151], v[214:217], v[4:7]
	v_mfma_f32_16x16x32_bf16 v[0:3], v[156:159], v[214:217], v[0:3]
	s_waitcnt vmcnt(8)
	s_barrier
	s_setprio 0
	s_add_i32 s62, 0, 0x18000
	s_add_i32 s63, 0, 0x1c000
	v_add_u32_e32 v140, s62, v199
	v_add_u32_e32 v156, s63, v199
	ds_read_b128 v[120:123], v140
	ds_read_b128 v[124:127], v140 offset:1024
	ds_read_b128 v[132:135], v140 offset:2048
	ds_read_b128 v[140:143], v140 offset:3072
	ds_read_b128 v[144:147], v156
	ds_read_b128 v[148:151], v156 offset:1024
	ds_read_b128 v[152:155], v156 offset:2048
	ds_read_b128 v[156:159], v156 offset:3072
	s_add_u32 s38, s38, 0x100000
	s_addc_u32 s39, s39, 0
	s_mov_b32 m0, s45
	ds_read_b128 v[160:163], v203 offset:32768
	ds_read_b128 v[164:167], v203 offset:33792
	ds_read_b128 v[168:171], v203 offset:34816
	ds_read_b128 v[172:175], v203 offset:35840
	ds_read_b128 v[192:195], v203 offset:36864
	ds_read_b128 v[206:209], v203 offset:37888
	ds_read_b128 v[210:213], v203 offset:38912
	ds_read_b128 v[214:217], v203 offset:39936
	global_load_lds_dwordx4 v176, s[38:39]
	s_mov_b32 m0, s46
	s_nop 0
	global_load_lds_dwordx4 v180, s[38:39]
	s_and_b64 vcc, exec, s[16:17]
	s_cbranch_vccnz .Lkw2179_2
	s_waitcnt vmcnt(8)
; #define PG8_STAGE(bufoff, gbase, voff) do { _Pragma("unroll") for (int _i = 0; _i < 2; ++_i) \
;         __builtin_amdgcn_global_load_lds((const unsigned*)((const char*)(gbase) + (voff)[_i]), (LAS unsigned*)(lds + (bufoff) + ldsw + _i * 8192), 16, 0, 0); } while (0)
; #define PG8_LDA(dst, b, h) do { _Pragma("unroll") for (int m = 0; m < 4; ++m) _Pragma("unroll") for (int k = 0; k < 2; ++k) dst[m][k] = *(const LAS bf16x8*)(lds + PG8_SA(b, h) + aoff + m * 2048 + k * 1024); } while (0)
; #define PG8_MMA(ai, bj, At, Bt) do { __builtin_amdgcn_s_setprio(1); _Pragma("unroll") for (int m = 0; m < 4; ++m) _Pragma("unroll") for (int n = 0; n < 2; ++n) _Pragma("unroll") for (int k = 0; k < 2; ++k) \
;         acc[ai][bj][m][n] = __builtin_amdgcn_mfma_f32_16x16x32_bf16(Bt[n][k], At[m][k], acc[ai][bj][m][n], 0, 0, 0); __builtin_amdgcn_s_setprio(0); } while (0)
; #define PG8_WAIT_V(n) asm volatile("s_waitcnt vmcnt(" #n ")" ::: "memory")
; #define PG8_WAIT_L(n) asm volatile("s_waitcnt lgkmcnt(" #n ")" ::: "memory")
; #define PG8_BAR __builtin_amdgcn_s_barrier()
; #define PG8_SCHED __builtin_amdgcn_sched_barrier(0)
; template <class Epi, class Sched, bool ALIGN_EPI = true, bool SP2 = true>
; __device__ __forceinline__ void gemm_phase(LAS unsigned char* lds, const Gemm g, const Sched& S, const Epi& E) {
;     ...
;         for (int t = 0; t < nt; t += 2) {
;     ...
;             PG8_WAIT_V(8); PG8_WAIT_L(0); PG8_BAR; PG8_MMA(0, 0, At, B0); PG8_MMA(0, 1, At, B1); PG8_BAR; PG8_SCHED;
;             PG8_LDA(At, 1, 1); PG8_STAGE(PG8_SB(1, 0), b3, voffB); PG8_STAGE(PG8_SB(1, 1), b3 + hstep, voffB); PG8_STAGE(PG8_SA(1, 0), a3, voffA);
;             PG8_WAIT_V(8); PG8_WAIT_L(0); PG8_BAR; PG8_MMA(1, 0, At, B0); PG8_MMA(1, 1, At, B1); PG8_BAR; PG8_SCHED;
;     ...
;         if constexpr (ALIGN_EPI) { if (wr == 0) PG8_BAR; }
.Lkw2179_2:
	s_waitcnt lgkmcnt(0)
	s_setprio 1
	s_barrier
	v_mfma_f32_16x16x32_bf16 v[136:139], v[120:123], v[160:163], v[136:139]
	v_mfma_f32_16x16x32_bf16 v[128:131], v[132:135], v[160:163], v[128:131]
	v_mfma_f32_16x16x32_bf16 v[108:111], v[120:123], v[168:171], v[108:111]
	v_mfma_f32_16x16x32_bf16 v[104:107], v[132:135], v[168:171], v[104:107]
	v_mfma_f32_16x16x32_bf16 v[92:95], v[120:123], v[192:195], v[92:95]
	v_mfma_f32_16x16x32_bf16 v[88:91], v[132:135], v[192:195], v[88:91]
	v_mfma_f32_16x16x32_bf16 v[76:79], v[120:123], v[210:213], v[76:79]
	v_mfma_f32_16x16x32_bf16 v[72:75], v[132:135], v[210:213], v[72:75]
	v_mfma_f32_16x16x32_bf16 v[136:139], v[124:127], v[164:167], v[136:139]
	v_mfma_f32_16x16x32_bf16 v[128:131], v[140:143], v[164:167], v[128:131]
	v_mfma_f32_16x16x32_bf16 v[108:111], v[124:127], v[172:175], v[108:111]
	v_mfma_f32_16x16x32_bf16 v[104:107], v[140:143], v[172:175], v[104:107]
	v_mfma_f32_16x16x32_bf16 v[92:95], v[124:127], v[206:209], v[92:95]
	v_mfma_f32_16x16x32_bf16 v[88:91], v[140:143], v[206:209], v[88:91]
	v_mfma_f32_16x16x32_bf16 v[76:79], v[124:127], v[214:217], v[76:79]
	v_mfma_f32_16x16x32_bf16 v[72:75], v[140:143], v[214:217], v[72:75]
	v_mfma_f32_16x16x32_bf16 v[116:119], v[144:147], v[160:163], v[116:119]
	v_mfma_f32_16x16x32_bf16 v[112:115], v[152:155], v[160:163], v[112:115]
	v_mfma_f32_16x16x32_bf16 v[100:103], v[144:147], v[168:171], v[100:103]
	v_mfma_f32_16x16x32_bf16 v[96:99], v[152:155], v[168:171], v[96:99]
	v_mfma_f32_16x16x32_bf16 v[84:87], v[144:147], v[192:195], v[84:87]
	v_mfma_f32_16x16x32_bf16 v[80:83], v[152:155], v[192:195], v[80:83]
	v_mfma_f32_16x16x32_bf16 v[68:71], v[144:147], v[210:213], v[68:71]
	v_mfma_f32_16x16x32_bf16 v[64:67], v[152:155], v[210:213], v[64:67]
	v_mfma_f32_16x16x32_bf16 v[116:119], v[148:151], v[164:167], v[116:119]
	v_mfma_f32_16x16x32_bf16 v[112:115], v[156:159], v[164:167], v[112:115]
	v_mfma_f32_16x16x32_bf16 v[100:103], v[148:151], v[172:175], v[100:103]
	v_mfma_f32_16x16x32_bf16 v[96:99], v[156:159], v[172:175], v[96:99]
	v_mfma_f32_16x16x32_bf16 v[84:87], v[148:151], v[206:209], v[84:87]
	v_mfma_f32_16x16x32_bf16 v[80:83], v[156:159], v[206:209], v[80:83]
	v_mfma_f32_16x16x32_bf16 v[68:71], v[148:151], v[214:217], v[68:71]
	v_mfma_f32_16x16x32_bf16 v[64:67], v[156:159], v[214:217], v[64:67]
	s_waitcnt vmcnt(8)
	s_barrier
	s_setprio 0
	s_add_i32 s38, s62, s42
	v_lshl_add_u64 v[196:197], v[196:197], 0, s[14:15]
	s_mov_b32 m0, s38
	ds_read_b128 v[160:163], v203 offset:49152
	ds_read_b128 v[164:167], v203 offset:50176
	ds_read_b128 v[168:171], v203 offset:51200
	ds_read_b128 v[172:175], v203 offset:52224
	ds_read_b128 v[192:195], v203 offset:53248
	ds_read_b128 v[206:209], v203 offset:54272
	ds_read_b128 v[210:213], v203 offset:55296
	ds_read_b128 v[214:217], v203 offset:56320
	global_load_lds_dwordx4 v[196:197], off
	s_add_i32 m0, s38, 0x2000
	s_add_u32 s36, s36, 0x100080
	v_lshl_add_u64 v[196:197], v[218:219], 0, s[14:15]
	s_addc_u32 s37, s37, 0
	s_add_i32 s38, s63, s42
	global_load_lds_dwordx4 v[196:197], off
	s_mov_b32 m0, s38
	s_nop 0
	global_load_lds_dwordx4 v178, s[36:37]
	s_add_i32 m0, s38, 0x2000
	s_nop 0
	global_load_lds_dwordx4 v182, s[36:37]
	v_lshl_add_u64 v[196:197], v[220:221], 0, s[14:15]
	s_mov_b32 m0, s48
	s_nop 0
	global_load_lds_dwordx4 v[196:197], off
	v_lshl_add_u64 v[196:197], v[222:223], 0, s[14:15]
	s_mov_b32 m0, s49
	s_nop 0
	global_load_lds_dwordx4 v[196:197], off
	s_and_b64 vcc, exec, s[16:17]
	s_cbranch_vccnz .Lkw2179_3
	s_waitcnt vmcnt(8)
.Lkw2179_3:
	s_waitcnt lgkmcnt(0)
	s_setprio 1
	s_barrier
	v_mfma_f32_16x16x32_bf16 v[60:63], v[120:123], v[160:163], v[60:63]
	v_mfma_f32_16x16x32_bf16 v[56:59], v[132:135], v[160:163], v[56:59]
	v_mfma_f32_16x16x32_bf16 v[44:47], v[120:123], v[168:171], v[44:47]
	v_mfma_f32_16x16x32_bf16 v[40:43], v[132:135], v[168:171], v[40:43]
	v_mfma_f32_16x16x32_bf16 v[28:31], v[120:123], v[192:195], v[28:31]
	v_mfma_f32_16x16x32_bf16 v[24:27], v[132:135], v[192:195], v[24:27]
	v_mfma_f32_16x16x32_bf16 v[12:15], v[120:123], v[210:213], v[12:15]
	v_mfma_f32_16x16x32_bf16 v[8:11], v[132:135], v[210:213], v[8:11]
	v_mfma_f32_16x16x32_bf16 v[60:63], v[124:127], v[164:167], v[60:63]
	v_mfma_f32_16x16x32_bf16 v[56:59], v[140:143], v[164:167], v[56:59]
	v_mfma_f32_16x16x32_bf16 v[44:47], v[124:127], v[172:175], v[44:47]
	v_mfma_f32_16x16x32_bf16 v[40:43], v[140:143], v[172:175], v[40:43]
	v_mfma_f32_16x16x32_bf16 v[28:31], v[124:127], v[206:209], v[28:31]
	v_mfma_f32_16x16x32_bf16 v[24:27], v[140:143], v[206:209], v[24:27]
	v_mfma_f32_16x16x32_bf16 v[12:15], v[124:127], v[214:217], v[12:15]
	v_mfma_f32_16x16x32_bf16 v[8:11], v[140:143], v[214:217], v[8:11]
	v_mfma_f32_16x16x32_bf16 v[52:55], v[144:147], v[160:163], v[52:55]
	v_mfma_f32_16x16x32_bf16 v[48:51], v[152:155], v[160:163], v[48:51]
	v_mfma_f32_16x16x32_bf16 v[36:39], v[144:147], v[168:171], v[36:39]
	v_mfma_f32_16x16x32_bf16 v[32:35], v[152:155], v[168:171], v[32:35]
	v_mfma_f32_16x16x32_bf16 v[20:23], v[144:147], v[192:195], v[20:23]
	v_mfma_f32_16x16x32_bf16 v[16:19], v[152:155], v[192:195], v[16:19]
	v_mfma_f32_16x16x32_bf16 v[4:7], v[144:147], v[210:213], v[4:7]
	v_mfma_f32_16x16x32_bf16 v[0:3], v[152:155], v[210:213], v[0:3]
	v_mfma_f32_16x16x32_bf16 v[52:55], v[148:151], v[164:167], v[52:55]
	v_mfma_f32_16x16x32_bf16 v[48:51], v[156:159], v[164:167], v[48:51]
	v_mfma_f32_16x16x32_bf16 v[36:39], v[148:151], v[172:175], v[36:39]
	v_mfma_f32_16x16x32_bf16 v[32:35], v[156:159], v[172:175], v[32:35]
	v_mfma_f32_16x16x32_bf16 v[20:23], v[148:151], v[206:209], v[20:23]
	v_mfma_f32_16x16x32_bf16 v[16:19], v[156:159], v[206:209], v[16:19]
	v_mfma_f32_16x16x32_bf16 v[4:7], v[148:151], v[214:217], v[4:7]
	v_mfma_f32_16x16x32_bf16 v[0:3], v[156:159], v[214:217], v[0:3]
	s_waitcnt vmcnt(8)
	s_barrier
	s_setprio 0
	s_add_i32 s61, s61, 2
	s_add_u32 s34, s34, 0x100
	s_addc_u32 s35, s35, 0
	s_add_u32 s59, s59, 0x100
	s_addc_u32 s60, s60, 0
	s_cmp_gt_u32 s61, 61
	s_cbranch_scc0 .LBB0_2179
	s_and_b64 vcc, exec, s[16:17]
	s_cbranch_vccz .LBB0_2182
	s_barrier
